# v82 + K-loop wait cleanup: vmcnt(8) and lgkmcnt(0) merged into one s_waitcnt before each pre-MFMA barrier, redundant post-barrier lgkmcnt(0) removed (80 fewer issue slots per loop pair)
# baseline (speedup 1.0000x reference)
; #define PG8_STAGE(bufoff, gbase, voff) do { _Pragma("unroll") for (int _i = 0; _i < 2; ++_i) \
;         __builtin_amdgcn_global_load_lds((const unsigned*)((const char*)(gbase) + (voff)[_i]), (PG8_LAS unsigned*)(lds + (bufoff) + ldsw + _i * 8192), 16, 0, 0); } while (0)
; #define PG8_LDA(dst, b, h) do { _Pragma("unroll") for (int m = 0; m < 4; ++m) _Pragma("unroll") for (int k = 0; k < 2; ++k) dst[m][k] = *(const PG8_LAS bf16x8*)(lds + PG8_SA(b, h) + aoff + m * 2048 + k * 1024); } while (0)
; #define PG8_LDB(dst, b, h) do { _Pragma("unroll") for (int n = 0; n < 2; ++n) _Pragma("unroll") for (int k = 0; k < 2; ++k) dst[n][k] = *(const PG8_LAS bf16x8*)(lds + PG8_SB(b, h) + boff + n * 2048 + k * 1024); } while (0)
; #define PG8_MMA(ai, bj, At, Bt) do { __builtin_amdgcn_s_setprio(1); _Pragma("unroll") for (int m = 0; m < 4; ++m) _Pragma("unroll") for (int n = 0; n < 2; ++n) _Pragma("unroll") for (int k = 0; k < 2; ++k) \
;         acc[ai][bj][m][n] = mma16<Epi::I8>(Bt[n][k], At[m][k], acc[ai][bj][m][n]); __builtin_amdgcn_s_setprio(0); } while (0)
; #define PG8_WAIT_V(n) asm volatile("s_waitcnt vmcnt(" #n ")" ::: "memory")
; #define PG8_WAIT_L(n) asm volatile("s_waitcnt lgkmcnt(" #n ")" ::: "memory")
; #define PG8_BAR __builtin_amdgcn_s_barrier()
; template <class Epi, class Sched, bool ALIGN_EPI = false, bool SP2 = false>
; __device__ __forceinline__ void gemm_phase(PG8_LAS unsigned char* lds, const Gemm g, const Sched& S, const Epi& E) {
;     ...
;             const bool last = (t == nt - 2);
;             const char* a1 = cA + (size_t)(t + 1) * kstep;
;             const char* a2 = last ? nA : cA + (size_t)(t + 2) * kstep; const char* b2 = last ? nB : cB + (size_t)(t + 2) * kstep;
;             const char* a3 = a2 + kstep; const char* b3 = b2 + kstep;
;             if (last && has_next) S.a_ready(nxt);
;             if constexpr (SP2) {
;             PG8_LDB(B0, 0, 0); PG8_LDB(B1, 0, 1); PG8_SCHED; PG8_LDA(At, 0, 0); PG8_STAGE(PG8_SA(1, 1), a1 + hstep, voffA);
;             PG8_WAIT_V(8); PG8_WAIT_L(0); PG8_BAR; PG8_MMA(0, 0, At, B0); PG8_MMA(0, 1, At, B1); PG8_BAR; PG8_SCHED;
;             PG8_LDA(At, 0, 1); PG8_STAGE(PG8_SB(0, 0), b2, voffB); PG8_STAGE(PG8_SB(0, 1), b2 + hstep, voffB); PG8_STAGE(PG8_SA(0, 0), a2, voffA);
;             PG8_WAIT_V(8); PG8_WAIT_L(0); PG8_BAR; PG8_MMA(1, 0, At, B0); PG8_MMA(1, 1, At, B1); PG8_BAR; PG8_SCHED;
.Lpeel80:
	s_add_u32 s8, s0, 0x100
	s_addc_u32 s9, s1, 0
	s_add_i32 vcc_hi, 0, 0x10000
	s_cmp_eq_u32 vcc_lo, 12
	s_cselect_b32 s13, s66, s9
	s_cselect_b32 s12, s67, s8
	s_cselect_b32 s7, s82, s97
	s_cselect_b32 s6, s83, s96
	s_add_i32 s4, 0, 0x14000
	v_add_u32_e32 v38, vcc_hi, v242
	v_add_u32_e32 v158, s4, v242
	ds_read_b128 v[18:21], v38
	ds_read_b128 v[22:25], v38 offset:1024
	ds_read_b128 v[34:37], v38 offset:2048
	ds_read_b128 v[38:41], v38 offset:3072
	ds_read_b128 v[130:133], v158
	ds_read_b128 v[134:137], v158 offset:1024
	ds_read_b128 v[154:157], v158 offset:2048
	ds_read_b128 v[158:161], v158 offset:3072
	s_add_i32 m0, s11, 0xc000
	ds_read_b128 v[162:165], v243
	ds_read_b128 v[166:169], v243 offset:1024
	ds_read_b128 v[170:173], v243 offset:2048
	ds_read_b128 v[174:177], v243 offset:3072
	ds_read_b128 v[178:181], v243 offset:4096
	ds_read_b128 v[182:185], v243 offset:5120
	ds_read_b128 v[186:189], v243 offset:6144
	ds_read_b128 v[190:193], v243 offset:7168
	global_load_lds_dwordx4 v216, s[0:1]
	s_add_i32 m0, s11, 0xe000
	s_nop 0
	global_load_lds_dwordx4 v218, s[0:1]
	s_waitcnt vmcnt(8) lgkmcnt(0)
	s_barrier
	v_mfma_i32_16x16x64_i8 v[150:153], v[18:21], v[162:165], 0
	v_mfma_i32_16x16x64_i8 v[146:149], v[34:37], v[162:165], 0
	v_mfma_i32_16x16x64_i8 v[110:113], v[34:37], v[170:173], 0
	v_mfma_i32_16x16x64_i8 v[118:121], v[18:21], v[170:173], 0
	v_mfma_i32_16x16x64_i8 v[54:57], v[18:21], v[178:181], 0
	v_mfma_i32_16x16x64_i8 v[30:33], v[34:37], v[178:181], 0
	v_mfma_i32_16x16x64_i8 v[58:61], v[34:37], v[186:189], 0
	v_mfma_i32_16x16x64_i8 v[94:97], v[18:21], v[186:189], 0
	v_mfma_i32_16x16x64_i8 v[150:153], v[22:25], v[166:169], v[150:153]
	v_mfma_i32_16x16x64_i8 v[146:149], v[38:41], v[166:169], v[146:149]
	v_mfma_i32_16x16x64_i8 v[110:113], v[38:41], v[174:177], v[110:113]
	v_mfma_i32_16x16x64_i8 v[118:121], v[22:25], v[174:177], v[118:121]
	v_mfma_i32_16x16x64_i8 v[54:57], v[22:25], v[182:185], v[54:57]
	v_mfma_i32_16x16x64_i8 v[30:33], v[38:41], v[182:185], v[30:33]
	v_mfma_i32_16x16x64_i8 v[58:61], v[38:41], v[190:193], v[58:61]
	v_mfma_i32_16x16x64_i8 v[94:97], v[22:25], v[190:193], v[94:97]
	v_mfma_i32_16x16x64_i8 v[142:145], v[130:133], v[162:165], 0
	v_mfma_i32_16x16x64_i8 v[138:141], v[154:157], v[162:165], 0
	v_mfma_i32_16x16x64_i8 v[98:101], v[154:157], v[170:173], 0
	v_mfma_i32_16x16x64_i8 v[102:105], v[130:133], v[170:173], 0
	v_mfma_i32_16x16x64_i8 v[42:45], v[130:133], v[178:181], 0
	v_mfma_i32_16x16x64_i8 v[26:29], v[154:157], v[178:181], 0
	v_mfma_i32_16x16x64_i8 v[62:65], v[154:157], v[186:189], 0
	v_mfma_i32_16x16x64_i8 v[78:81], v[130:133], v[186:189], 0
	v_mfma_i32_16x16x64_i8 v[142:145], v[134:137], v[166:169], v[142:145]
	v_mfma_i32_16x16x64_i8 v[138:141], v[158:161], v[166:169], v[138:141]
	v_mfma_i32_16x16x64_i8 v[98:101], v[158:161], v[174:177], v[98:101]
	v_mfma_i32_16x16x64_i8 v[102:105], v[134:137], v[174:177], v[102:105]
	v_mfma_i32_16x16x64_i8 v[42:45], v[134:137], v[182:185], v[42:45]
	v_mfma_i32_16x16x64_i8 v[26:29], v[158:161], v[182:185], v[26:29]
	v_mfma_i32_16x16x64_i8 v[62:65], v[158:161], v[190:193], v[62:65]
	v_mfma_i32_16x16x64_i8 v[78:81], v[134:137], v[190:193], v[78:81]
	s_barrier
	s_add_i32 s0, vcc_hi, s69
	v_lshl_add_u64 v[198:199], s[6:7], 0, v[0:1]
	s_mov_b32 m0, s0
	ds_read_b128 v[162:165], v243 offset:16384
	ds_read_b128 v[166:169], v243 offset:17408
	ds_read_b128 v[170:173], v243 offset:18432
	ds_read_b128 v[174:177], v243 offset:19456
	ds_read_b128 v[178:181], v243 offset:20480
	ds_read_b128 v[182:185], v243 offset:21504
	ds_read_b128 v[186:189], v243 offset:22528
	ds_read_b128 v[190:193], v243 offset:23552
	global_load_lds_dwordx4 v[198:199], off
	s_add_i32 m0, s0, 0x2000
	s_add_u32 s0, s6, 0x40000
	v_lshl_add_u64 v[200:201], s[6:7], 0, v[214:215]
	s_addc_u32 s1, s7, 0
	s_add_i32 s4, s4, s69
	global_load_lds_dwordx4 v[200:201], off
	s_mov_b32 m0, s4
	v_lshl_add_u64 v[206:207], s[12:13], 0, v[210:211]
	global_load_lds_dwordx4 v0, s[0:1]
	s_add_i32 m0, s4, 0x2000
	v_lshl_add_u64 v[220:221], s[12:13], 0, v[212:213]
	global_load_lds_dwordx4 v214, s[0:1]
	s_mov_b32 m0, s11
	s_nop 0
	global_load_lds_dwordx4 v[206:207], off
	s_mov_b32 m0, s71
	s_nop 0
	global_load_lds_dwordx4 v[220:221], off
	s_waitcnt vmcnt(8) lgkmcnt(0)
	s_barrier
	v_mfma_i32_16x16x64_i8 v[106:109], v[18:21], v[162:165], 0
	v_mfma_i32_16x16x64_i8 v[46:49], v[34:37], v[162:165], 0
	v_mfma_i32_16x16x64_i8 v[6:9], v[34:37], v[170:173], 0
	v_mfma_i32_16x16x64_i8 v[14:17], v[18:21], v[170:173], 0
	v_mfma_i32_16x16x64_i8 v[90:93], v[18:21], v[178:181], 0
	v_mfma_i32_16x16x64_i8 v[86:89], v[34:37], v[178:181], 0
	v_mfma_i32_16x16x64_i8 v[18:21], v[18:21], v[186:189], 0
	v_mfma_i32_16x16x64_i8 v[106:109], v[22:25], v[166:169], v[106:109]
	v_mfma_i32_16x16x64_i8 v[46:49], v[38:41], v[166:169], v[46:49]
	v_mfma_i32_16x16x64_i8 v[6:9], v[38:41], v[174:177], v[6:9]
	v_mfma_i32_16x16x64_i8 v[14:17], v[22:25], v[174:177], v[14:17]
	v_mfma_i32_16x16x64_i8 v[90:93], v[22:25], v[182:185], v[90:93]
	v_mfma_i32_16x16x64_i8 v[86:89], v[38:41], v[182:185], v[86:89]
	v_mfma_i32_16x16x64_i8 v[18:21], v[22:25], v[190:193], v[18:21]
	v_mfma_i32_16x16x64_i8 v[22:25], v[34:37], v[186:189], 0
	v_mfma_i32_16x16x64_i8 v[22:25], v[38:41], v[190:193], v[22:25]
	v_mfma_i32_16x16x64_i8 v[38:41], v[154:157], v[162:165], 0
	v_mfma_i32_16x16x64_i8 v[2:5], v[154:157], v[170:173], 0
	v_mfma_i32_16x16x64_i8 v[10:13], v[130:133], v[170:173], 0
	v_mfma_i32_16x16x64_i8 v[50:53], v[130:133], v[178:181], 0
	v_mfma_i32_16x16x64_i8 v[34:37], v[130:133], v[162:165], 0
	v_mfma_i32_16x16x64_i8 v[82:85], v[134:137], v[182:185], v[50:53]
	v_mfma_i32_16x16x64_i8 v[50:53], v[154:157], v[178:181], 0
	v_mfma_i32_16x16x64_i8 v[2:5], v[158:161], v[174:177], v[2:5]
	v_mfma_i32_16x16x64_i8 v[10:13], v[134:137], v[174:177], v[10:13]
	v_mfma_i32_16x16x64_i8 v[38:41], v[158:161], v[166:169], v[38:41]
	v_mfma_i32_16x16x64_i8 v[34:37], v[134:137], v[166:169], v[34:37]
	v_mfma_i32_16x16x64_i8 v[74:77], v[158:161], v[182:185], v[50:53]
	v_mfma_i32_16x16x64_i8 v[50:53], v[130:133], v[186:189], 0
	v_mfma_i32_16x16x64_i8 v[122:125], v[134:137], v[190:193], v[50:53]
	v_mfma_i32_16x16x64_i8 v[50:53], v[154:157], v[186:189], 0
	v_mfma_i32_16x16x64_i8 v[70:73], v[158:161], v[190:193], v[50:53]
	s_barrier
; #define PG8_STAGE(bufoff, gbase, voff) do { _Pragma("unroll") for (int _i = 0; _i < 2; ++_i) \
;         __builtin_amdgcn_global_load_lds((const unsigned*)((const char*)(gbase) + (voff)[_i]), (PG8_LAS unsigned*)(lds + (bufoff) + ldsw + _i * 8192), 16, 0, 0); } while (0)
; #define PG8_LDA(dst, b, h) do { _Pragma("unroll") for (int m = 0; m < 4; ++m) _Pragma("unroll") for (int k = 0; k < 2; ++k) dst[m][k] = *(const PG8_LAS bf16x8*)(lds + PG8_SA(b, h) + aoff + m * 2048 + k * 1024); } while (0)
; #define PG8_LDB(dst, b, h) do { _Pragma("unroll") for (int n = 0; n < 2; ++n) _Pragma("unroll") for (int k = 0; k < 2; ++k) dst[n][k] = *(const PG8_LAS bf16x8*)(lds + PG8_SB(b, h) + boff + n * 2048 + k * 1024); } while (0)
; #define PG8_MMA(ai, bj, At, Bt) do { __builtin_amdgcn_s_setprio(1); _Pragma("unroll") for (int m = 0; m < 4; ++m) _Pragma("unroll") for (int n = 0; n < 2; ++n) _Pragma("unroll") for (int k = 0; k < 2; ++k) \
;         acc[ai][bj][m][n] = mma16<Epi::I8>(Bt[n][k], At[m][k], acc[ai][bj][m][n]); __builtin_amdgcn_s_setprio(0); } while (0)
; #define PG8_WAIT_V(n) asm volatile("s_waitcnt vmcnt(" #n ")" ::: "memory")
; #define PG8_WAIT_L(n) asm volatile("s_waitcnt lgkmcnt(" #n ")" ::: "memory")
; #define PG8_BAR __builtin_amdgcn_s_barrier()
; #define PG8_SCHED __builtin_amdgcn_sched_barrier(0)
; template <class Epi, class Sched, bool ALIGN_EPI = false, bool SP2 = false>
; __device__ __forceinline__ void gemm_phase(PG8_LAS unsigned char* lds, const Gemm g, const Sched& S, const Epi& E) {
;     ...
;             PG8_LDB(B0, 1, 0); PG8_LDB(B1, 1, 1); PG8_SCHED; PG8_LDA(At, 1, 0); PG8_STAGE(PG8_SA(0, 1), a2 + hstep, voffA);
;             PG8_WAIT_V(8); PG8_WAIT_L(0); PG8_BAR; PG8_MMA(0, 0, At, B0); PG8_MMA(0, 1, At, B1); PG8_BAR; PG8_SCHED;
;             PG8_LDA(At, 1, 1); PG8_STAGE(PG8_SB(1, 0), b3, voffB); PG8_STAGE(PG8_SB(1, 1), b3 + hstep, voffB); PG8_STAGE(PG8_SA(1, 0), a3, voffA);
;             PG8_WAIT_V(8); PG8_WAIT_L(0); PG8_BAR; PG8_MMA(1, 0, At, B0); PG8_MMA(1, 1, At, B1); PG8_BAR; PG8_SCHED;
	s_add_i32 s4, 0, 0x18000
	v_add_u32_e32 v126, s4, v242
	s_add_i32 s5, 0, 0x1c000
	ds_read_b128 v[50:53], v126
	ds_read_b128 v[66:69], v126 offset:1024
	ds_read_b128 v[114:117], v126 offset:2048
	ds_read_b128 v[130:133], v126 offset:3072
	v_add_u32_e32 v126, s5, v242
	ds_read_b128 v[134:137], v126
	ds_read_b128 v[154:157], v126 offset:1024
	ds_read_b128 v[158:161], v126 offset:2048
	ds_read_b128 v[162:165], v126 offset:3072
	s_add_u32 s0, s12, 0x40000
	s_addc_u32 s1, s13, 0
	s_mov_b32 m0, s80
	ds_read_b128 v[126:129], v243 offset:32768
	ds_read_b128 v[166:169], v243 offset:33792
	ds_read_b128 v[170:173], v243 offset:34816
	ds_read_b128 v[174:177], v243 offset:35840
	ds_read_b128 v[178:181], v243 offset:36864
	ds_read_b128 v[182:185], v243 offset:37888
	ds_read_b128 v[186:189], v243 offset:38912
	ds_read_b128 v[190:193], v243 offset:39936
	global_load_lds_dwordx4 v210, s[0:1]
	s_mov_b32 m0, s81
	s_nop 0
	global_load_lds_dwordx4 v212, s[0:1]
	s_waitcnt vmcnt(8) lgkmcnt(0)
	s_barrier
	v_mfma_i32_16x16x64_i8 v[150:153], v[50:53], v[126:129], v[150:153]
	v_mfma_i32_16x16x64_i8 v[146:149], v[114:117], v[126:129], v[146:149]
	v_mfma_i32_16x16x64_i8 v[110:113], v[114:117], v[170:173], v[110:113]
	v_mfma_i32_16x16x64_i8 v[118:121], v[50:53], v[170:173], v[118:121]
	v_mfma_i32_16x16x64_i8 v[54:57], v[50:53], v[178:181], v[54:57]
	v_mfma_i32_16x16x64_i8 v[30:33], v[114:117], v[178:181], v[30:33]
	v_mfma_i32_16x16x64_i8 v[58:61], v[114:117], v[186:189], v[58:61]
	v_mfma_i32_16x16x64_i8 v[94:97], v[50:53], v[186:189], v[94:97]
	v_mfma_i32_16x16x64_i8 v[150:153], v[66:69], v[166:169], v[150:153]
	v_mfma_i32_16x16x64_i8 v[146:149], v[130:133], v[166:169], v[146:149]
	v_mfma_i32_16x16x64_i8 v[110:113], v[130:133], v[174:177], v[110:113]
	v_mfma_i32_16x16x64_i8 v[118:121], v[66:69], v[174:177], v[118:121]
	v_mfma_i32_16x16x64_i8 v[54:57], v[66:69], v[182:185], v[54:57]
	v_mfma_i32_16x16x64_i8 v[30:33], v[130:133], v[182:185], v[30:33]
	v_mfma_i32_16x16x64_i8 v[58:61], v[130:133], v[190:193], v[58:61]
	v_mfma_i32_16x16x64_i8 v[94:97], v[66:69], v[190:193], v[94:97]
	v_mfma_i32_16x16x64_i8 v[142:145], v[134:137], v[126:129], v[142:145]
	v_mfma_i32_16x16x64_i8 v[126:129], v[158:161], v[126:129], v[138:141]
	v_mfma_i32_16x16x64_i8 v[98:101], v[158:161], v[170:173], v[98:101]
	v_mfma_i32_16x16x64_i8 v[102:105], v[134:137], v[170:173], v[102:105]
	v_mfma_i32_16x16x64_i8 v[42:45], v[134:137], v[178:181], v[42:45]
	v_mfma_i32_16x16x64_i8 v[26:29], v[158:161], v[178:181], v[26:29]
	v_mfma_i32_16x16x64_i8 v[62:65], v[158:161], v[186:189], v[62:65]
	v_mfma_i32_16x16x64_i8 v[78:81], v[134:137], v[186:189], v[78:81]
	v_mfma_i32_16x16x64_i8 v[142:145], v[154:157], v[166:169], v[142:145]
	v_mfma_i32_16x16x64_i8 v[138:141], v[162:165], v[166:169], v[126:129]
	v_mfma_i32_16x16x64_i8 v[98:101], v[162:165], v[174:177], v[98:101]
	v_mfma_i32_16x16x64_i8 v[102:105], v[154:157], v[174:177], v[102:105]
	v_mfma_i32_16x16x64_i8 v[42:45], v[154:157], v[182:185], v[42:45]
	v_mfma_i32_16x16x64_i8 v[26:29], v[162:165], v[182:185], v[26:29]
	v_mfma_i32_16x16x64_i8 v[62:65], v[162:165], v[190:193], v[62:65]
	v_mfma_i32_16x16x64_i8 v[78:81], v[154:157], v[190:193], v[78:81]
	s_barrier
	s_add_i32 s0, s4, s69
	v_lshl_add_u64 v[126:127], v[198:199], 0, s[92:93]
	s_mov_b32 m0, s0
	ds_read_b128 v[166:169], v243 offset:49152
	ds_read_b128 v[170:173], v243 offset:50176
	ds_read_b128 v[174:177], v243 offset:51200
	ds_read_b128 v[178:181], v243 offset:52224
	ds_read_b128 v[182:185], v243 offset:53248
	ds_read_b128 v[186:189], v243 offset:54272
	ds_read_b128 v[190:193], v243 offset:55296
	ds_read_b128 v[194:197], v243 offset:56320
	global_load_lds_dwordx4 v[126:127], off
	s_add_i32 m0, s0, 0x2000
	s_add_u32 s0, s6, 0x40080
	v_lshl_add_u64 v[126:127], v[200:201], 0, s[92:93]
	s_addc_u32 s1, s7, 0
	s_add_i32 s4, s5, s69
	global_load_lds_dwordx4 v[126:127], off
	s_mov_b32 m0, s4
	s_nop 0
	global_load_lds_dwordx4 v0, s[0:1]
	s_add_i32 m0, s4, 0x2000
	s_nop 0
	global_load_lds_dwordx4 v214, s[0:1]
	v_lshl_add_u64 v[126:127], v[206:207], 0, s[92:93]
	s_mov_b32 m0, s84
	s_nop 0
	global_load_lds_dwordx4 v[126:127], off
	v_lshl_add_u64 v[126:127], v[220:221], 0, s[92:93]
	s_mov_b32 m0, s85
	s_nop 0
	global_load_lds_dwordx4 v[126:127], off
	s_waitcnt vmcnt(8) lgkmcnt(0)
	s_barrier
	v_mfma_i32_16x16x64_i8 v[18:21], v[50:53], v[190:193], v[18:21]
	v_mfma_i32_16x16x64_i8 v[106:109], v[50:53], v[166:169], v[106:109]
	v_mfma_i32_16x16x64_i8 v[46:49], v[114:117], v[166:169], v[46:49]
	v_mfma_i32_16x16x64_i8 v[6:9], v[114:117], v[174:177], v[6:9]
	v_mfma_i32_16x16x64_i8 v[14:17], v[50:53], v[174:177], v[14:17]
	v_mfma_i32_16x16x64_i8 v[90:93], v[50:53], v[182:185], v[90:93]
	v_mfma_i32_16x16x64_i8 v[86:89], v[114:117], v[182:185], v[86:89]
	v_mfma_i32_16x16x64_i8 v[126:129], v[66:69], v[194:197], v[18:21]
	v_mfma_i32_16x16x64_i8 v[106:109], v[66:69], v[170:173], v[106:109]
	v_mfma_i32_16x16x64_i8 v[46:49], v[130:133], v[170:173], v[46:49]
	v_mfma_i32_16x16x64_i8 v[6:9], v[130:133], v[178:181], v[6:9]
	v_mfma_i32_16x16x64_i8 v[14:17], v[66:69], v[178:181], v[14:17]
	v_mfma_i32_16x16x64_i8 v[90:93], v[66:69], v[186:189], v[90:93]
	v_mfma_i32_16x16x64_i8 v[86:89], v[130:133], v[186:189], v[86:89]
	v_mfma_i32_16x16x64_i8 v[18:21], v[114:117], v[190:193], v[22:25]
	v_mfma_i32_16x16x64_i8 v[66:69], v[130:133], v[194:197], v[18:21]
	v_mfma_i32_16x16x64_i8 v[18:21], v[134:137], v[166:169], v[34:37]
	v_mfma_i32_16x16x64_i8 v[10:13], v[134:137], v[174:177], v[10:13]
	v_mfma_i32_16x16x64_i8 v[2:5], v[158:161], v[174:177], v[2:5]
	v_mfma_i32_16x16x64_i8 v[114:117], v[154:157], v[170:173], v[18:21]
	v_mfma_i32_16x16x64_i8 v[18:21], v[158:161], v[166:169], v[38:41]
	v_mfma_i32_16x16x64_i8 v[50:53], v[162:165], v[170:173], v[18:21]
	v_mfma_i32_16x16x64_i8 v[18:21], v[134:137], v[182:185], v[82:85]
	v_mfma_i32_16x16x64_i8 v[10:13], v[154:157], v[178:181], v[10:13]
	v_mfma_i32_16x16x64_i8 v[2:5], v[162:165], v[178:181], v[2:5]
	v_mfma_i32_16x16x64_i8 v[82:85], v[154:157], v[186:189], v[18:21]
	v_mfma_i32_16x16x64_i8 v[18:21], v[158:161], v[182:185], v[74:77]
	v_mfma_i32_16x16x64_i8 v[74:77], v[162:165], v[186:189], v[18:21]
	v_mfma_i32_16x16x64_i8 v[18:21], v[134:137], v[190:193], v[122:125]
	v_mfma_i32_16x16x64_i8 v[122:125], v[154:157], v[194:197], v[18:21]
	v_mfma_i32_16x16x64_i8 v[18:21], v[158:161], v[190:193], v[70:73]
	v_mfma_i32_16x16x64_i8 v[70:73], v[162:165], v[194:197], v[18:21]
	s_barrier
	s_add_i32 vcc_lo, vcc_lo, 2
	s_add_u32 s96, s96, 0x100
	s_addc_u32 s97, s97, 0
	s_cmp_gt_u32 vcc_lo, 13
	s_mov_b64 s[0:1], s[8:9]
	s_cbranch_scc0 .LBB0_80
	s_branch .Lpeelx80
; #define PG8_STAGE(bufoff, gbase, voff) do { _Pragma("unroll") for (int _i = 0; _i < 2; ++_i) \
;         __builtin_amdgcn_global_load_lds((const unsigned*)((const char*)(gbase) + (voff)[_i]), (PG8_LAS unsigned*)(lds + (bufoff) + ldsw + _i * 8192), 16, 0, 0); } while (0)
; #define PG8_LDA(dst, b, h) do { _Pragma("unroll") for (int m = 0; m < 4; ++m) _Pragma("unroll") for (int k = 0; k < 2; ++k) dst[m][k] = *(const PG8_LAS bf16x8*)(lds + PG8_SA(b, h) + aoff + m * 2048 + k * 1024); } while (0)
; #define PG8_LDB(dst, b, h) do { _Pragma("unroll") for (int n = 0; n < 2; ++n) _Pragma("unroll") for (int k = 0; k < 2; ++k) dst[n][k] = *(const PG8_LAS bf16x8*)(lds + PG8_SB(b, h) + boff + n * 2048 + k * 1024); } while (0)
; #define PG8_MMA(ai, bj, At, Bt) do { __builtin_amdgcn_s_setprio(1); _Pragma("unroll") for (int m = 0; m < 4; ++m) _Pragma("unroll") for (int n = 0; n < 2; ++n) _Pragma("unroll") for (int k = 0; k < 2; ++k) \
;         acc[ai][bj][m][n] = mma16<Epi::I8>(Bt[n][k], At[m][k], acc[ai][bj][m][n]); __builtin_amdgcn_s_setprio(0); } while (0)
; #define PG8_WAIT_V(n) asm volatile("s_waitcnt vmcnt(" #n ")" ::: "memory")
; #define PG8_WAIT_L(n) asm volatile("s_waitcnt lgkmcnt(" #n ")" ::: "memory")
; #define PG8_BAR __builtin_amdgcn_s_barrier()
; #define PG8_SCHED __builtin_amdgcn_sched_barrier(0)
; template <class Epi, class Sched, bool ALIGN_EPI = false, bool SP2 = false>
; __device__ __forceinline__ void gemm_phase(PG8_LAS unsigned char* lds, const Gemm g, const Sched& S, const Epi& E) {
;     ...
;             PG8_LDB(B0, 0, 0); PG8_LDB(B1, 0, 1); PG8_SCHED; PG8_LDA(At, 0, 0); PG8_STAGE(PG8_SA(1, 1), a1 + hstep, voffA);
;             PG8_WAIT_V(8); PG8_WAIT_L(0); PG8_BAR; PG8_MMA(0, 0, At, B0); PG8_MMA(0, 1, At, B1); PG8_BAR; PG8_SCHED;
;             PG8_LDA(At, 0, 1); PG8_STAGE(PG8_SB(0, 0), b2, voffB); PG8_STAGE(PG8_SB(0, 1), b2 + hstep, voffB); PG8_STAGE(PG8_SA(0, 0), a2, voffA);
;             PG8_WAIT_V(8); PG8_WAIT_L(0); PG8_BAR; PG8_MMA(1, 0, At, B0); PG8_MMA(1, 1, At, B1); PG8_BAR; PG8_SCHED;
.LBB0_80:
	s_add_u32 s8, s0, 0x100
	s_addc_u32 s9, s1, 0
	s_add_i32 vcc_hi, 0, 0x10000
	s_cmp_eq_u32 vcc_lo, 12
	s_cselect_b32 s13, s66, s9
	s_cselect_b32 s12, s67, s8
	s_cselect_b32 s7, s82, s97
	s_cselect_b32 s6, s83, s96
	s_add_i32 s4, 0, 0x14000
	v_add_u32_e32 v38, vcc_hi, v242
	v_add_u32_e32 v158, s4, v242
	ds_read_b128 v[18:21], v38
	ds_read_b128 v[22:25], v38 offset:1024
	ds_read_b128 v[34:37], v38 offset:2048
	ds_read_b128 v[38:41], v38 offset:3072
	ds_read_b128 v[130:133], v158
	ds_read_b128 v[134:137], v158 offset:1024
	ds_read_b128 v[154:157], v158 offset:2048
	ds_read_b128 v[158:161], v158 offset:3072
	s_add_i32 m0, s11, 0xc000
	ds_read_b128 v[162:165], v243
	ds_read_b128 v[166:169], v243 offset:1024
	ds_read_b128 v[170:173], v243 offset:2048
	ds_read_b128 v[174:177], v243 offset:3072
	ds_read_b128 v[178:181], v243 offset:4096
	ds_read_b128 v[182:185], v243 offset:5120
	ds_read_b128 v[186:189], v243 offset:6144
	ds_read_b128 v[190:193], v243 offset:7168
	global_load_lds_dwordx4 v216, s[0:1]
	s_add_i32 m0, s11, 0xe000
	s_nop 0
	global_load_lds_dwordx4 v218, s[0:1]
	s_waitcnt vmcnt(8) lgkmcnt(0)
	s_barrier
	v_mfma_i32_16x16x64_i8 v[150:153], v[18:21], v[162:165], v[150:153]
	v_mfma_i32_16x16x64_i8 v[146:149], v[34:37], v[162:165], v[146:149]
	v_mfma_i32_16x16x64_i8 v[110:113], v[34:37], v[170:173], v[110:113]
	v_mfma_i32_16x16x64_i8 v[118:121], v[18:21], v[170:173], v[118:121]
	v_mfma_i32_16x16x64_i8 v[54:57], v[18:21], v[178:181], v[54:57]
	v_mfma_i32_16x16x64_i8 v[30:33], v[34:37], v[178:181], v[30:33]
	v_mfma_i32_16x16x64_i8 v[58:61], v[34:37], v[186:189], v[58:61]
	v_mfma_i32_16x16x64_i8 v[94:97], v[18:21], v[186:189], v[94:97]
	v_mfma_i32_16x16x64_i8 v[150:153], v[22:25], v[166:169], v[150:153]
	v_mfma_i32_16x16x64_i8 v[146:149], v[38:41], v[166:169], v[146:149]
	v_mfma_i32_16x16x64_i8 v[110:113], v[38:41], v[174:177], v[110:113]
	v_mfma_i32_16x16x64_i8 v[118:121], v[22:25], v[174:177], v[118:121]
	v_mfma_i32_16x16x64_i8 v[54:57], v[22:25], v[182:185], v[54:57]
	v_mfma_i32_16x16x64_i8 v[30:33], v[38:41], v[182:185], v[30:33]
	v_mfma_i32_16x16x64_i8 v[58:61], v[38:41], v[190:193], v[58:61]
	v_mfma_i32_16x16x64_i8 v[94:97], v[22:25], v[190:193], v[94:97]
	v_mfma_i32_16x16x64_i8 v[142:145], v[130:133], v[162:165], v[142:145]
	v_mfma_i32_16x16x64_i8 v[138:141], v[154:157], v[162:165], v[138:141]
	v_mfma_i32_16x16x64_i8 v[98:101], v[154:157], v[170:173], v[98:101]
	v_mfma_i32_16x16x64_i8 v[102:105], v[130:133], v[170:173], v[102:105]
	v_mfma_i32_16x16x64_i8 v[42:45], v[130:133], v[178:181], v[42:45]
	v_mfma_i32_16x16x64_i8 v[26:29], v[154:157], v[178:181], v[26:29]
	v_mfma_i32_16x16x64_i8 v[62:65], v[154:157], v[186:189], v[62:65]
	v_mfma_i32_16x16x64_i8 v[78:81], v[130:133], v[186:189], v[78:81]
	v_mfma_i32_16x16x64_i8 v[142:145], v[134:137], v[166:169], v[142:145]
	v_mfma_i32_16x16x64_i8 v[138:141], v[158:161], v[166:169], v[138:141]
	v_mfma_i32_16x16x64_i8 v[98:101], v[158:161], v[174:177], v[98:101]
	v_mfma_i32_16x16x64_i8 v[102:105], v[134:137], v[174:177], v[102:105]
	v_mfma_i32_16x16x64_i8 v[42:45], v[134:137], v[182:185], v[42:45]
	v_mfma_i32_16x16x64_i8 v[26:29], v[158:161], v[182:185], v[26:29]
	v_mfma_i32_16x16x64_i8 v[62:65], v[158:161], v[190:193], v[62:65]
	v_mfma_i32_16x16x64_i8 v[78:81], v[134:137], v[190:193], v[78:81]
	s_barrier
	s_add_i32 s0, vcc_hi, s69
	v_lshl_add_u64 v[198:199], s[6:7], 0, v[0:1]
	s_mov_b32 m0, s0
	ds_read_b128 v[162:165], v243 offset:16384
	ds_read_b128 v[166:169], v243 offset:17408
	ds_read_b128 v[170:173], v243 offset:18432
	ds_read_b128 v[174:177], v243 offset:19456
	ds_read_b128 v[178:181], v243 offset:20480
	ds_read_b128 v[182:185], v243 offset:21504
	ds_read_b128 v[186:189], v243 offset:22528
	ds_read_b128 v[190:193], v243 offset:23552
	global_load_lds_dwordx4 v[198:199], off
	s_add_i32 m0, s0, 0x2000
	s_add_u32 s0, s6, 0x40000
	v_lshl_add_u64 v[200:201], s[6:7], 0, v[214:215]
	s_addc_u32 s1, s7, 0
	s_add_i32 s4, s4, s69
	global_load_lds_dwordx4 v[200:201], off
	s_mov_b32 m0, s4
	v_lshl_add_u64 v[206:207], s[12:13], 0, v[210:211]
	global_load_lds_dwordx4 v0, s[0:1]
	s_add_i32 m0, s4, 0x2000
	v_lshl_add_u64 v[220:221], s[12:13], 0, v[212:213]
	global_load_lds_dwordx4 v214, s[0:1]
	s_mov_b32 m0, s11
	s_nop 0
	global_load_lds_dwordx4 v[206:207], off
	s_mov_b32 m0, s71
	s_nop 0
	global_load_lds_dwordx4 v[220:221], off
	s_waitcnt vmcnt(8) lgkmcnt(0)
	s_barrier
	v_mfma_i32_16x16x64_i8 v[106:109], v[18:21], v[162:165], v[106:109]
	v_mfma_i32_16x16x64_i8 v[46:49], v[34:37], v[162:165], v[46:49]
	v_mfma_i32_16x16x64_i8 v[6:9], v[34:37], v[170:173], v[6:9]
	v_mfma_i32_16x16x64_i8 v[14:17], v[18:21], v[170:173], v[14:17]
	v_mfma_i32_16x16x64_i8 v[90:93], v[18:21], v[178:181], v[90:93]
	v_mfma_i32_16x16x64_i8 v[86:89], v[34:37], v[178:181], v[86:89]
	v_mfma_i32_16x16x64_i8 v[18:21], v[18:21], v[186:189], v[126:129]
	v_mfma_i32_16x16x64_i8 v[106:109], v[22:25], v[166:169], v[106:109]
	v_mfma_i32_16x16x64_i8 v[46:49], v[38:41], v[166:169], v[46:49]
	v_mfma_i32_16x16x64_i8 v[6:9], v[38:41], v[174:177], v[6:9]
	v_mfma_i32_16x16x64_i8 v[14:17], v[22:25], v[174:177], v[14:17]
	v_mfma_i32_16x16x64_i8 v[90:93], v[22:25], v[182:185], v[90:93]
	v_mfma_i32_16x16x64_i8 v[86:89], v[38:41], v[182:185], v[86:89]
	v_mfma_i32_16x16x64_i8 v[18:21], v[22:25], v[190:193], v[18:21]
	v_mfma_i32_16x16x64_i8 v[22:25], v[34:37], v[186:189], v[66:69]
	v_mfma_i32_16x16x64_i8 v[22:25], v[38:41], v[190:193], v[22:25]
	v_mfma_i32_16x16x64_i8 v[38:41], v[154:157], v[162:165], v[50:53]
	v_mfma_i32_16x16x64_i8 v[2:5], v[154:157], v[170:173], v[2:5]
	v_mfma_i32_16x16x64_i8 v[10:13], v[130:133], v[170:173], v[10:13]
	v_mfma_i32_16x16x64_i8 v[50:53], v[130:133], v[178:181], v[82:85]
	v_mfma_i32_16x16x64_i8 v[34:37], v[130:133], v[162:165], v[114:117]
	v_mfma_i32_16x16x64_i8 v[82:85], v[134:137], v[182:185], v[50:53]
	v_mfma_i32_16x16x64_i8 v[50:53], v[154:157], v[178:181], v[74:77]
	v_mfma_i32_16x16x64_i8 v[2:5], v[158:161], v[174:177], v[2:5]
	v_mfma_i32_16x16x64_i8 v[10:13], v[134:137], v[174:177], v[10:13]
	v_mfma_i32_16x16x64_i8 v[38:41], v[158:161], v[166:169], v[38:41]
	v_mfma_i32_16x16x64_i8 v[34:37], v[134:137], v[166:169], v[34:37]
	v_mfma_i32_16x16x64_i8 v[74:77], v[158:161], v[182:185], v[50:53]
	v_mfma_i32_16x16x64_i8 v[50:53], v[130:133], v[186:189], v[122:125]
	v_mfma_i32_16x16x64_i8 v[122:125], v[134:137], v[190:193], v[50:53]
	v_mfma_i32_16x16x64_i8 v[50:53], v[154:157], v[186:189], v[70:73]
	v_mfma_i32_16x16x64_i8 v[70:73], v[158:161], v[190:193], v[50:53]
	s_barrier
; #define PG8_STAGE(bufoff, gbase, voff) do { _Pragma("unroll") for (int _i = 0; _i < 2; ++_i) \
;         __builtin_amdgcn_global_load_lds((const unsigned*)((const char*)(gbase) + (voff)[_i]), (PG8_LAS unsigned*)(lds + (bufoff) + ldsw + _i * 8192), 16, 0, 0); } while (0)
; #define PG8_LDA(dst, b, h) do { _Pragma("unroll") for (int m = 0; m < 4; ++m) _Pragma("unroll") for (int k = 0; k < 2; ++k) dst[m][k] = *(const PG8_LAS bf16x8*)(lds + PG8_SA(b, h) + aoff + m * 2048 + k * 1024); } while (0)
; #define PG8_LDB(dst, b, h) do { _Pragma("unroll") for (int n = 0; n < 2; ++n) _Pragma("unroll") for (int k = 0; k < 2; ++k) dst[n][k] = *(const PG8_LAS bf16x8*)(lds + PG8_SB(b, h) + boff + n * 2048 + k * 1024); } while (0)
; #define PG8_MMA(ai, bj, At, Bt) do { __builtin_amdgcn_s_setprio(1); _Pragma("unroll") for (int m = 0; m < 4; ++m) _Pragma("unroll") for (int n = 0; n < 2; ++n) _Pragma("unroll") for (int k = 0; k < 2; ++k) \
;         acc[ai][bj][m][n] = mma16<Epi::I8>(Bt[n][k], At[m][k], acc[ai][bj][m][n]); __builtin_amdgcn_s_setprio(0); } while (0)
; #define PG8_WAIT_V(n) asm volatile("s_waitcnt vmcnt(" #n ")" ::: "memory")
; #define PG8_WAIT_L(n) asm volatile("s_waitcnt lgkmcnt(" #n ")" ::: "memory")
; #define PG8_BAR __builtin_amdgcn_s_barrier()
; #define PG8_SCHED __builtin_amdgcn_sched_barrier(0)
; template <class Epi, class Sched, bool ALIGN_EPI = false, bool SP2 = false>
; __device__ __forceinline__ void gemm_phase(PG8_LAS unsigned char* lds, const Gemm g, const Sched& S, const Epi& E) {
;     ...
;             PG8_LDB(B0, 1, 0); PG8_LDB(B1, 1, 1); PG8_SCHED; PG8_LDA(At, 1, 0); PG8_STAGE(PG8_SA(0, 1), a2 + hstep, voffA);
;             PG8_WAIT_V(8); PG8_WAIT_L(0); PG8_BAR; PG8_MMA(0, 0, At, B0); PG8_MMA(0, 1, At, B1); PG8_BAR; PG8_SCHED;
;             PG8_LDA(At, 1, 1); PG8_STAGE(PG8_SB(1, 0), b3, voffB); PG8_STAGE(PG8_SB(1, 1), b3 + hstep, voffB); PG8_STAGE(PG8_SA(1, 0), a3, voffA);
;             PG8_WAIT_V(8); PG8_WAIT_L(0); PG8_BAR; PG8_MMA(1, 0, At, B0); PG8_MMA(1, 1, At, B1); PG8_BAR; PG8_SCHED;
	s_add_i32 s4, 0, 0x18000
	v_add_u32_e32 v126, s4, v242
	s_add_i32 s5, 0, 0x1c000
	ds_read_b128 v[50:53], v126
	ds_read_b128 v[66:69], v126 offset:1024
	ds_read_b128 v[114:117], v126 offset:2048
	ds_read_b128 v[130:133], v126 offset:3072
	v_add_u32_e32 v126, s5, v242
	ds_read_b128 v[134:137], v126
	ds_read_b128 v[154:157], v126 offset:1024
	ds_read_b128 v[158:161], v126 offset:2048
	ds_read_b128 v[162:165], v126 offset:3072
	s_add_u32 s0, s12, 0x40000
	s_addc_u32 s1, s13, 0
	s_mov_b32 m0, s80
	ds_read_b128 v[126:129], v243 offset:32768
	ds_read_b128 v[166:169], v243 offset:33792
	ds_read_b128 v[170:173], v243 offset:34816
	ds_read_b128 v[174:177], v243 offset:35840
	ds_read_b128 v[178:181], v243 offset:36864
	ds_read_b128 v[182:185], v243 offset:37888
	ds_read_b128 v[186:189], v243 offset:38912
	ds_read_b128 v[190:193], v243 offset:39936
	global_load_lds_dwordx4 v210, s[0:1]
	s_mov_b32 m0, s81
	s_nop 0
	global_load_lds_dwordx4 v212, s[0:1]
	s_waitcnt vmcnt(8) lgkmcnt(0)
	s_barrier
	v_mfma_i32_16x16x64_i8 v[150:153], v[50:53], v[126:129], v[150:153]
	v_mfma_i32_16x16x64_i8 v[146:149], v[114:117], v[126:129], v[146:149]
	v_mfma_i32_16x16x64_i8 v[110:113], v[114:117], v[170:173], v[110:113]
	v_mfma_i32_16x16x64_i8 v[118:121], v[50:53], v[170:173], v[118:121]
	v_mfma_i32_16x16x64_i8 v[54:57], v[50:53], v[178:181], v[54:57]
	v_mfma_i32_16x16x64_i8 v[30:33], v[114:117], v[178:181], v[30:33]
	v_mfma_i32_16x16x64_i8 v[58:61], v[114:117], v[186:189], v[58:61]
	v_mfma_i32_16x16x64_i8 v[94:97], v[50:53], v[186:189], v[94:97]
	v_mfma_i32_16x16x64_i8 v[150:153], v[66:69], v[166:169], v[150:153]
	v_mfma_i32_16x16x64_i8 v[146:149], v[130:133], v[166:169], v[146:149]
	v_mfma_i32_16x16x64_i8 v[110:113], v[130:133], v[174:177], v[110:113]
	v_mfma_i32_16x16x64_i8 v[118:121], v[66:69], v[174:177], v[118:121]
	v_mfma_i32_16x16x64_i8 v[54:57], v[66:69], v[182:185], v[54:57]
	v_mfma_i32_16x16x64_i8 v[30:33], v[130:133], v[182:185], v[30:33]
	v_mfma_i32_16x16x64_i8 v[58:61], v[130:133], v[190:193], v[58:61]
	v_mfma_i32_16x16x64_i8 v[94:97], v[66:69], v[190:193], v[94:97]
	v_mfma_i32_16x16x64_i8 v[142:145], v[134:137], v[126:129], v[142:145]
	v_mfma_i32_16x16x64_i8 v[126:129], v[158:161], v[126:129], v[138:141]
	v_mfma_i32_16x16x64_i8 v[98:101], v[158:161], v[170:173], v[98:101]
	v_mfma_i32_16x16x64_i8 v[102:105], v[134:137], v[170:173], v[102:105]
	v_mfma_i32_16x16x64_i8 v[42:45], v[134:137], v[178:181], v[42:45]
	v_mfma_i32_16x16x64_i8 v[26:29], v[158:161], v[178:181], v[26:29]
	v_mfma_i32_16x16x64_i8 v[62:65], v[158:161], v[186:189], v[62:65]
	v_mfma_i32_16x16x64_i8 v[78:81], v[134:137], v[186:189], v[78:81]
	v_mfma_i32_16x16x64_i8 v[142:145], v[154:157], v[166:169], v[142:145]
	v_mfma_i32_16x16x64_i8 v[138:141], v[162:165], v[166:169], v[126:129]
	v_mfma_i32_16x16x64_i8 v[98:101], v[162:165], v[174:177], v[98:101]
	v_mfma_i32_16x16x64_i8 v[102:105], v[154:157], v[174:177], v[102:105]
	v_mfma_i32_16x16x64_i8 v[42:45], v[154:157], v[182:185], v[42:45]
	v_mfma_i32_16x16x64_i8 v[26:29], v[162:165], v[182:185], v[26:29]
	v_mfma_i32_16x16x64_i8 v[62:65], v[162:165], v[190:193], v[62:65]
	v_mfma_i32_16x16x64_i8 v[78:81], v[154:157], v[190:193], v[78:81]
	s_barrier
	s_add_i32 s0, s4, s69
	v_lshl_add_u64 v[126:127], v[198:199], 0, s[92:93]
	s_mov_b32 m0, s0
	ds_read_b128 v[166:169], v243 offset:49152
	ds_read_b128 v[170:173], v243 offset:50176
	ds_read_b128 v[174:177], v243 offset:51200
	ds_read_b128 v[178:181], v243 offset:52224
	ds_read_b128 v[182:185], v243 offset:53248
	ds_read_b128 v[186:189], v243 offset:54272
	ds_read_b128 v[190:193], v243 offset:55296
	ds_read_b128 v[194:197], v243 offset:56320
	global_load_lds_dwordx4 v[126:127], off
	s_add_i32 m0, s0, 0x2000
	s_add_u32 s0, s6, 0x40080
	v_lshl_add_u64 v[126:127], v[200:201], 0, s[92:93]
	s_addc_u32 s1, s7, 0
	s_add_i32 s4, s5, s69
	global_load_lds_dwordx4 v[126:127], off
	s_mov_b32 m0, s4
	s_nop 0
	global_load_lds_dwordx4 v0, s[0:1]
	s_add_i32 m0, s4, 0x2000
	s_nop 0
	global_load_lds_dwordx4 v214, s[0:1]
	v_lshl_add_u64 v[126:127], v[206:207], 0, s[92:93]
	s_mov_b32 m0, s84
	s_nop 0
	global_load_lds_dwordx4 v[126:127], off
	v_lshl_add_u64 v[126:127], v[220:221], 0, s[92:93]
	s_mov_b32 m0, s85
	s_nop 0
	global_load_lds_dwordx4 v[126:127], off
	s_waitcnt vmcnt(8) lgkmcnt(0)
	s_barrier
	v_mfma_i32_16x16x64_i8 v[18:21], v[50:53], v[190:193], v[18:21]
	v_mfma_i32_16x16x64_i8 v[106:109], v[50:53], v[166:169], v[106:109]
	v_mfma_i32_16x16x64_i8 v[46:49], v[114:117], v[166:169], v[46:49]
	v_mfma_i32_16x16x64_i8 v[6:9], v[114:117], v[174:177], v[6:9]
	v_mfma_i32_16x16x64_i8 v[14:17], v[50:53], v[174:177], v[14:17]
	v_mfma_i32_16x16x64_i8 v[90:93], v[50:53], v[182:185], v[90:93]
	v_mfma_i32_16x16x64_i8 v[86:89], v[114:117], v[182:185], v[86:89]
	v_mfma_i32_16x16x64_i8 v[126:129], v[66:69], v[194:197], v[18:21]
	v_mfma_i32_16x16x64_i8 v[106:109], v[66:69], v[170:173], v[106:109]
	v_mfma_i32_16x16x64_i8 v[46:49], v[130:133], v[170:173], v[46:49]
	v_mfma_i32_16x16x64_i8 v[6:9], v[130:133], v[178:181], v[6:9]
	v_mfma_i32_16x16x64_i8 v[14:17], v[66:69], v[178:181], v[14:17]
	v_mfma_i32_16x16x64_i8 v[90:93], v[66:69], v[186:189], v[90:93]
	v_mfma_i32_16x16x64_i8 v[86:89], v[130:133], v[186:189], v[86:89]
	v_mfma_i32_16x16x64_i8 v[18:21], v[114:117], v[190:193], v[22:25]
	v_mfma_i32_16x16x64_i8 v[66:69], v[130:133], v[194:197], v[18:21]
	v_mfma_i32_16x16x64_i8 v[18:21], v[134:137], v[166:169], v[34:37]
	v_mfma_i32_16x16x64_i8 v[10:13], v[134:137], v[174:177], v[10:13]
	v_mfma_i32_16x16x64_i8 v[2:5], v[158:161], v[174:177], v[2:5]
	v_mfma_i32_16x16x64_i8 v[114:117], v[154:157], v[170:173], v[18:21]
	v_mfma_i32_16x16x64_i8 v[18:21], v[158:161], v[166:169], v[38:41]
	v_mfma_i32_16x16x64_i8 v[50:53], v[162:165], v[170:173], v[18:21]
	v_mfma_i32_16x16x64_i8 v[18:21], v[134:137], v[182:185], v[82:85]
	v_mfma_i32_16x16x64_i8 v[10:13], v[154:157], v[178:181], v[10:13]
	v_mfma_i32_16x16x64_i8 v[2:5], v[162:165], v[178:181], v[2:5]
	v_mfma_i32_16x16x64_i8 v[82:85], v[154:157], v[186:189], v[18:21]
	v_mfma_i32_16x16x64_i8 v[18:21], v[158:161], v[182:185], v[74:77]
	v_mfma_i32_16x16x64_i8 v[74:77], v[162:165], v[186:189], v[18:21]
	v_mfma_i32_16x16x64_i8 v[18:21], v[134:137], v[190:193], v[122:125]
	v_mfma_i32_16x16x64_i8 v[122:125], v[154:157], v[194:197], v[18:21]
	v_mfma_i32_16x16x64_i8 v[18:21], v[158:161], v[190:193], v[70:73]
	v_mfma_i32_16x16x64_i8 v[70:73], v[162:165], v[194:197], v[18:21]
	s_barrier
	s_add_i32 vcc_lo, vcc_lo, 2
	s_add_u32 s96, s96, 0x100
	s_addc_u32 s97, s97, 0
	s_cmp_gt_u32 vcc_lo, 13
	s_mov_b64 s[0:1], s[8:9]
	s_cbranch_scc0 .LBB0_80

; #define PG8_STAGE(bufoff, gbase, voff) do { _Pragma("unroll") for (int _i = 0; _i < 2; ++_i) \
;         __builtin_amdgcn_global_load_lds((const unsigned*)((const char*)(gbase) + (voff)[_i]), (PG8_LAS unsigned*)(lds + (bufoff) + ldsw + _i * 8192), 16, 0, 0); } while (0)
; #define PG8_LDA(dst, b, h) do { _Pragma("unroll") for (int m = 0; m < 4; ++m) _Pragma("unroll") for (int k = 0; k < 2; ++k) dst[m][k] = *(const PG8_LAS bf16x8*)(lds + PG8_SA(b, h) + aoff + m * 2048 + k * 1024); } while (0)
; #define PG8_LDB(dst, b, h) do { _Pragma("unroll") for (int n = 0; n < 2; ++n) _Pragma("unroll") for (int k = 0; k < 2; ++k) dst[n][k] = *(const PG8_LAS bf16x8*)(lds + PG8_SB(b, h) + boff + n * 2048 + k * 1024); } while (0)
; #define PG8_MMA(ai, bj, At, Bt) do { __builtin_amdgcn_s_setprio(1); _Pragma("unroll") for (int m = 0; m < 4; ++m) _Pragma("unroll") for (int n = 0; n < 2; ++n) _Pragma("unroll") for (int k = 0; k < 2; ++k) \
;         acc[ai][bj][m][n] = mma16<Epi::I8>(Bt[n][k], At[m][k], acc[ai][bj][m][n]); __builtin_amdgcn_s_setprio(0); } while (0)
; #define PG8_WAIT_V(n) asm volatile("s_waitcnt vmcnt(" #n ")" ::: "memory")
; #define PG8_WAIT_L(n) asm volatile("s_waitcnt lgkmcnt(" #n ")" ::: "memory")
; #define PG8_BAR __builtin_amdgcn_s_barrier()
; template <class Epi, class Sched, bool ALIGN_EPI = false, bool SP2 = false>
; __device__ __forceinline__ void gemm_phase(PG8_LAS unsigned char* lds, const Gemm g, const Sched& S, const Epi& E) {
;     ...
;             const bool last = (t == nt - 2);
;             const char* a1 = cA + (size_t)(t + 1) * kstep;
;             const char* a2 = last ? nA : cA + (size_t)(t + 2) * kstep; const char* b2 = last ? nB : cB + (size_t)(t + 2) * kstep;
;             const char* a3 = a2 + kstep; const char* b3 = b2 + kstep;
;             if (last && has_next) S.a_ready(nxt);
;             if constexpr (SP2) {
;             PG8_LDB(B0, 0, 0); PG8_LDB(B1, 0, 1); PG8_SCHED; PG8_LDA(At, 0, 0); PG8_STAGE(PG8_SA(1, 1), a1 + hstep, voffA);
;             PG8_WAIT_V(8); PG8_WAIT_L(0); PG8_BAR; PG8_MMA(0, 0, At, B0); PG8_MMA(0, 1, At, B1); PG8_BAR; PG8_SCHED;
;             PG8_LDA(At, 0, 1); PG8_STAGE(PG8_SB(0, 0), b2, voffB); PG8_STAGE(PG8_SB(0, 1), b2 + hstep, voffB); PG8_STAGE(PG8_SA(0, 0), a2, voffA);
;             PG8_WAIT_V(8); PG8_WAIT_L(0); PG8_BAR; PG8_MMA(1, 0, At, B0); PG8_MMA(1, 1, At, B1); PG8_BAR; PG8_SCHED;
.Lpeel175:
	s_add_i32 vcc_lo, s8, 2
	s_add_u32 s4, s6, s98
	s_addc_u32 s5, s7, 0
	s_add_i32 vcc_hi, 0, 0x10000
	s_cmp_eq_u32 s13, s8
	s_cselect_b32 s9, s1, s5
	s_cselect_b32 s8, s0, s4
	s_cselect_b32 s5, s97, s85
	s_cselect_b32 s4, s96, s67
	s_add_i32 s84, 0, 0x14000
	v_add_u32_e32 v122, vcc_hi, v248
	v_add_u32_e32 v154, s84, v248
	ds_read_b128 v[98:101], v122
	ds_read_b128 v[102:105], v122 offset:1024
	ds_read_b128 v[114:117], v122 offset:2048
	ds_read_b128 v[122:125], v122 offset:3072
	ds_read_b128 v[130:133], v154
	ds_read_b128 v[138:141], v154 offset:1024
	ds_read_b128 v[146:149], v154 offset:2048
	ds_read_b128 v[154:157], v154 offset:3072
	v_lshl_add_u64 v[206:207], s[6:7], 0, v[200:201]
	s_add_i32 m0, s81, 0xc000
	ds_read_b128 v[162:165], v249
	ds_read_b128 v[166:169], v249 offset:1024
	ds_read_b128 v[170:173], v249 offset:2048
	ds_read_b128 v[174:177], v249 offset:3072
	ds_read_b128 v[178:181], v249 offset:4096
	ds_read_b128 v[182:185], v249 offset:5120
	ds_read_b128 v[186:189], v249 offset:6144
	ds_read_b128 v[190:193], v249 offset:7168
	global_load_lds_dwordx4 v[206:207], off
	v_lshl_add_u64 v[206:207], s[6:7], 0, v[210:211]
	s_add_i32 m0, s81, 0xe000
	s_nop 0
	global_load_lds_dwordx4 v[206:207], off
	s_waitcnt vmcnt(8) lgkmcnt(0)
	s_barrier
	v_mfma_f32_16x16x32_bf16 v[158:161], v[98:101], v[162:165], 0
	v_mfma_f32_16x16x32_bf16 v[150:153], v[114:117], v[162:165], 0
	v_mfma_f32_16x16x32_bf16 v[118:121], v[114:117], v[170:173], 0
	v_mfma_f32_16x16x32_bf16 v[126:129], v[98:101], v[170:173], 0
	v_mfma_f32_16x16x32_bf16 v[94:97], v[98:101], v[178:181], 0
	v_mfma_f32_16x16x32_bf16 v[90:93], v[114:117], v[178:181], 0
	v_mfma_f32_16x16x32_bf16 v[74:77], v[114:117], v[186:189], 0
	v_mfma_f32_16x16x32_bf16 v[78:81], v[98:101], v[186:189], 0
	v_mfma_f32_16x16x32_bf16 v[158:161], v[102:105], v[166:169], v[158:161]
	v_mfma_f32_16x16x32_bf16 v[150:153], v[122:125], v[166:169], v[150:153]
	v_mfma_f32_16x16x32_bf16 v[118:121], v[122:125], v[174:177], v[118:121]
	v_mfma_f32_16x16x32_bf16 v[126:129], v[102:105], v[174:177], v[126:129]
	v_mfma_f32_16x16x32_bf16 v[94:97], v[102:105], v[182:185], v[94:97]
	v_mfma_f32_16x16x32_bf16 v[90:93], v[122:125], v[182:185], v[90:93]
	v_mfma_f32_16x16x32_bf16 v[74:77], v[122:125], v[190:193], v[74:77]
	v_mfma_f32_16x16x32_bf16 v[78:81], v[102:105], v[190:193], v[78:81]
	v_mfma_f32_16x16x32_bf16 v[142:145], v[130:133], v[162:165], 0
	v_mfma_f32_16x16x32_bf16 v[134:137], v[146:149], v[162:165], 0
	v_mfma_f32_16x16x32_bf16 v[106:109], v[146:149], v[170:173], 0
	v_mfma_f32_16x16x32_bf16 v[110:113], v[130:133], v[170:173], 0
	v_mfma_f32_16x16x32_bf16 v[86:89], v[130:133], v[178:181], 0
	v_mfma_f32_16x16x32_bf16 v[82:85], v[146:149], v[178:181], 0
	v_mfma_f32_16x16x32_bf16 v[66:69], v[146:149], v[186:189], 0
	v_mfma_f32_16x16x32_bf16 v[70:73], v[130:133], v[186:189], 0
	v_mfma_f32_16x16x32_bf16 v[142:145], v[138:141], v[166:169], v[142:145]
	v_mfma_f32_16x16x32_bf16 v[134:137], v[154:157], v[166:169], v[134:137]
	v_mfma_f32_16x16x32_bf16 v[106:109], v[154:157], v[174:177], v[106:109]
	v_mfma_f32_16x16x32_bf16 v[110:113], v[138:141], v[174:177], v[110:113]
	v_mfma_f32_16x16x32_bf16 v[86:89], v[138:141], v[182:185], v[86:89]
	v_mfma_f32_16x16x32_bf16 v[82:85], v[154:157], v[182:185], v[82:85]
	v_mfma_f32_16x16x32_bf16 v[66:69], v[154:157], v[190:193], v[66:69]
	v_mfma_f32_16x16x32_bf16 v[70:73], v[138:141], v[190:193], v[70:73]
	s_barrier
	s_add_i32 vcc_hi, vcc_hi, s80
	v_lshl_add_u64 v[206:207], s[4:5], 0, v[0:1]
	s_mov_b32 m0, vcc_hi
	ds_read_b128 v[162:165], v249 offset:16384
	ds_read_b128 v[166:169], v249 offset:17408
	ds_read_b128 v[170:173], v249 offset:18432
	ds_read_b128 v[174:177], v249 offset:19456
	ds_read_b128 v[178:181], v249 offset:20480
	ds_read_b128 v[182:185], v249 offset:21504
	ds_read_b128 v[186:189], v249 offset:22528
	ds_read_b128 v[190:193], v249 offset:23552
	global_load_lds_dwordx4 v[206:207], off
	s_add_i32 m0, vcc_hi, 0x2000
	v_lshl_add_u64 v[212:213], s[4:5], 0, v[198:199]
	s_add_u32 s4, s4, s100
	s_addc_u32 s5, s5, 0
	s_add_i32 s84, s84, s80
	global_load_lds_dwordx4 v[212:213], off
	v_lshl_add_u64 v[214:215], s[4:5], 0, v[0:1]
	s_mov_b32 m0, s84
	v_lshl_add_u64 v[216:217], s[4:5], 0, v[198:199]
	global_load_lds_dwordx4 v[214:215], off
	s_add_i32 m0, s84, 0x2000
	v_lshl_add_u64 v[218:219], s[8:9], 0, v[194:195]
	global_load_lds_dwordx4 v[216:217], off
	s_mov_b32 m0, s81
	v_lshl_add_u64 v[220:221], s[8:9], 0, v[196:197]
	global_load_lds_dwordx4 v[218:219], off
	s_mov_b32 m0, s70
	s_nop 0
	global_load_lds_dwordx4 v[220:221], off
	s_waitcnt vmcnt(8) lgkmcnt(0)
	s_barrier
; #define PG8_STAGE(bufoff, gbase, voff) do { _Pragma("unroll") for (int _i = 0; _i < 2; ++_i) \
;         __builtin_amdgcn_global_load_lds((const unsigned*)((const char*)(gbase) + (voff)[_i]), (PG8_LAS unsigned*)(lds + (bufoff) + ldsw + _i * 8192), 16, 0, 0); } while (0)
; #define PG8_LDA(dst, b, h) do { _Pragma("unroll") for (int m = 0; m < 4; ++m) _Pragma("unroll") for (int k = 0; k < 2; ++k) dst[m][k] = *(const PG8_LAS bf16x8*)(lds + PG8_SA(b, h) + aoff + m * 2048 + k * 1024); } while (0)
; #define PG8_LDB(dst, b, h) do { _Pragma("unroll") for (int n = 0; n < 2; ++n) _Pragma("unroll") for (int k = 0; k < 2; ++k) dst[n][k] = *(const PG8_LAS bf16x8*)(lds + PG8_SB(b, h) + boff + n * 2048 + k * 1024); } while (0)
; #define PG8_MMA(ai, bj, At, Bt) do { __builtin_amdgcn_s_setprio(1); _Pragma("unroll") for (int m = 0; m < 4; ++m) _Pragma("unroll") for (int n = 0; n < 2; ++n) _Pragma("unroll") for (int k = 0; k < 2; ++k) \
;         acc[ai][bj][m][n] = mma16<Epi::I8>(Bt[n][k], At[m][k], acc[ai][bj][m][n]); __builtin_amdgcn_s_setprio(0); } while (0)
; #define PG8_WAIT_V(n) asm volatile("s_waitcnt vmcnt(" #n ")" ::: "memory")
; #define PG8_WAIT_L(n) asm volatile("s_waitcnt lgkmcnt(" #n ")" ::: "memory")
; #define PG8_BAR __builtin_amdgcn_s_barrier()
; #define PG8_SCHED __builtin_amdgcn_sched_barrier(0)
; template <class Epi, class Sched, bool ALIGN_EPI = false, bool SP2 = false>
; __device__ __forceinline__ void gemm_phase(PG8_LAS unsigned char* lds, const Gemm g, const Sched& S, const Epi& E) {
;     ...
;             PG8_WAIT_V(8); PG8_WAIT_L(0); PG8_BAR; PG8_MMA(1, 0, At, B0); PG8_MMA(1, 1, At, B1); PG8_BAR; PG8_SCHED;
;             PG8_LDB(B0, 1, 0); PG8_LDB(B1, 1, 1); PG8_SCHED; PG8_LDA(At, 1, 0); PG8_STAGE(PG8_SA(0, 1), a2 + hstep, voffA);
;             PG8_WAIT_V(8); PG8_WAIT_L(0); PG8_BAR; PG8_MMA(0, 0, At, B0); PG8_MMA(0, 1, At, B1); PG8_BAR; PG8_SCHED;
	v_mfma_f32_16x16x32_bf16 v[62:65], v[98:101], v[162:165], 0
	v_mfma_f32_16x16x32_bf16 v[58:61], v[114:117], v[162:165], 0
	v_mfma_f32_16x16x32_bf16 v[42:45], v[114:117], v[170:173], 0
	v_mfma_f32_16x16x32_bf16 v[46:49], v[98:101], v[170:173], 0
	v_mfma_f32_16x16x32_bf16 v[30:33], v[98:101], v[178:181], 0
	v_mfma_f32_16x16x32_bf16 v[26:29], v[114:117], v[178:181], 0
	v_mfma_f32_16x16x32_bf16 v[10:13], v[114:117], v[186:189], 0
	v_mfma_f32_16x16x32_bf16 v[14:17], v[98:101], v[186:189], 0
	v_mfma_f32_16x16x32_bf16 v[62:65], v[102:105], v[166:169], v[62:65]
	v_mfma_f32_16x16x32_bf16 v[58:61], v[122:125], v[166:169], v[58:61]
	v_mfma_f32_16x16x32_bf16 v[42:45], v[122:125], v[174:177], v[42:45]
	v_mfma_f32_16x16x32_bf16 v[46:49], v[102:105], v[174:177], v[46:49]
	v_mfma_f32_16x16x32_bf16 v[30:33], v[102:105], v[182:185], v[30:33]
	v_mfma_f32_16x16x32_bf16 v[26:29], v[122:125], v[182:185], v[26:29]
	v_mfma_f32_16x16x32_bf16 v[10:13], v[122:125], v[190:193], v[10:13]
	v_mfma_f32_16x16x32_bf16 v[14:17], v[102:105], v[190:193], v[14:17]
	v_mfma_f32_16x16x32_bf16 v[54:57], v[130:133], v[162:165], 0
	v_mfma_f32_16x16x32_bf16 v[50:53], v[146:149], v[162:165], 0
	v_mfma_f32_16x16x32_bf16 v[34:37], v[146:149], v[170:173], 0
	v_mfma_f32_16x16x32_bf16 v[38:41], v[130:133], v[170:173], 0
	v_mfma_f32_16x16x32_bf16 v[22:25], v[130:133], v[178:181], 0
	v_mfma_f32_16x16x32_bf16 v[18:21], v[146:149], v[178:181], 0
	v_mfma_f32_16x16x32_bf16 v[2:5], v[146:149], v[186:189], 0
	v_mfma_f32_16x16x32_bf16 v[6:9], v[130:133], v[186:189], 0
	v_mfma_f32_16x16x32_bf16 v[54:57], v[138:141], v[166:169], v[54:57]
	v_mfma_f32_16x16x32_bf16 v[50:53], v[154:157], v[166:169], v[50:53]
	v_mfma_f32_16x16x32_bf16 v[34:37], v[154:157], v[174:177], v[34:37]
	v_mfma_f32_16x16x32_bf16 v[38:41], v[138:141], v[174:177], v[38:41]
	v_mfma_f32_16x16x32_bf16 v[22:25], v[138:141], v[182:185], v[22:25]
	v_mfma_f32_16x16x32_bf16 v[18:21], v[154:157], v[182:185], v[18:21]
	v_mfma_f32_16x16x32_bf16 v[2:5], v[154:157], v[190:193], v[2:5]
	v_mfma_f32_16x16x32_bf16 v[6:9], v[138:141], v[190:193], v[6:9]
	s_barrier
	s_add_i32 s84, 0, 0x18000
	s_add_i32 vcc_hi, 0, 0x1c000
	v_add_u32_e32 v122, s84, v248
	v_add_u32_e32 v154, vcc_hi, v248
	ds_read_b128 v[98:101], v122
	ds_read_b128 v[102:105], v122 offset:1024
	ds_read_b128 v[114:117], v122 offset:2048
	ds_read_b128 v[122:125], v122 offset:3072
	ds_read_b128 v[130:133], v154
	ds_read_b128 v[138:141], v154 offset:1024
	ds_read_b128 v[146:149], v154 offset:2048
	ds_read_b128 v[154:157], v154 offset:3072
	s_add_u32 s4, s8, s100
	s_addc_u32 s5, s9, 0
	s_mov_b32 m0, s71
	v_lshl_add_u64 v[222:223], s[4:5], 0, v[194:195]
	ds_read_b128 v[162:165], v249 offset:32768
	ds_read_b128 v[166:169], v249 offset:33792
	ds_read_b128 v[170:173], v249 offset:34816
	ds_read_b128 v[174:177], v249 offset:35840
	ds_read_b128 v[178:181], v249 offset:36864
	ds_read_b128 v[182:185], v249 offset:37888
	ds_read_b128 v[186:189], v249 offset:38912
	ds_read_b128 v[190:193], v249 offset:39936
	global_load_lds_dwordx4 v[222:223], off
	v_lshl_add_u64 v[222:223], s[4:5], 0, v[196:197]
	s_mov_b32 m0, s12
	s_nop 0
	global_load_lds_dwordx4 v[222:223], off
	s_waitcnt vmcnt(8) lgkmcnt(0)
	s_barrier
	v_mfma_f32_16x16x32_bf16 v[158:161], v[98:101], v[162:165], v[158:161]
	v_mfma_f32_16x16x32_bf16 v[150:153], v[114:117], v[162:165], v[150:153]
	v_mfma_f32_16x16x32_bf16 v[118:121], v[114:117], v[170:173], v[118:121]
	v_mfma_f32_16x16x32_bf16 v[126:129], v[98:101], v[170:173], v[126:129]
	v_mfma_f32_16x16x32_bf16 v[94:97], v[98:101], v[178:181], v[94:97]
	v_mfma_f32_16x16x32_bf16 v[90:93], v[114:117], v[178:181], v[90:93]
	v_mfma_f32_16x16x32_bf16 v[74:77], v[114:117], v[186:189], v[74:77]
	v_mfma_f32_16x16x32_bf16 v[78:81], v[98:101], v[186:189], v[78:81]
	v_mfma_f32_16x16x32_bf16 v[158:161], v[102:105], v[166:169], v[158:161]
	v_mfma_f32_16x16x32_bf16 v[150:153], v[122:125], v[166:169], v[150:153]
	v_mfma_f32_16x16x32_bf16 v[118:121], v[122:125], v[174:177], v[118:121]
	v_mfma_f32_16x16x32_bf16 v[126:129], v[102:105], v[174:177], v[126:129]
	v_mfma_f32_16x16x32_bf16 v[94:97], v[102:105], v[182:185], v[94:97]
	v_mfma_f32_16x16x32_bf16 v[90:93], v[122:125], v[182:185], v[90:93]
	v_mfma_f32_16x16x32_bf16 v[74:77], v[122:125], v[190:193], v[74:77]
	v_mfma_f32_16x16x32_bf16 v[78:81], v[102:105], v[190:193], v[78:81]
	v_mfma_f32_16x16x32_bf16 v[142:145], v[130:133], v[162:165], v[142:145]
	v_mfma_f32_16x16x32_bf16 v[134:137], v[146:149], v[162:165], v[134:137]
	v_mfma_f32_16x16x32_bf16 v[106:109], v[146:149], v[170:173], v[106:109]
	v_mfma_f32_16x16x32_bf16 v[110:113], v[130:133], v[170:173], v[110:113]
	v_mfma_f32_16x16x32_bf16 v[86:89], v[130:133], v[178:181], v[86:89]
	v_mfma_f32_16x16x32_bf16 v[82:85], v[146:149], v[178:181], v[82:85]
	v_mfma_f32_16x16x32_bf16 v[66:69], v[146:149], v[186:189], v[66:69]
	v_mfma_f32_16x16x32_bf16 v[70:73], v[130:133], v[186:189], v[70:73]
	v_mfma_f32_16x16x32_bf16 v[142:145], v[138:141], v[166:169], v[142:145]
	v_mfma_f32_16x16x32_bf16 v[134:137], v[154:157], v[166:169], v[134:137]
	v_mfma_f32_16x16x32_bf16 v[106:109], v[154:157], v[174:177], v[106:109]
	v_mfma_f32_16x16x32_bf16 v[110:113], v[138:141], v[174:177], v[110:113]
	v_mfma_f32_16x16x32_bf16 v[86:89], v[138:141], v[182:185], v[86:89]
	v_mfma_f32_16x16x32_bf16 v[82:85], v[154:157], v[182:185], v[82:85]
	v_mfma_f32_16x16x32_bf16 v[66:69], v[154:157], v[190:193], v[66:69]
	v_mfma_f32_16x16x32_bf16 v[70:73], v[138:141], v[190:193], v[70:73]
	s_barrier
; #define PG8_STAGE(bufoff, gbase, voff) do { _Pragma("unroll") for (int _i = 0; _i < 2; ++_i) \
;         __builtin_amdgcn_global_load_lds((const unsigned*)((const char*)(gbase) + (voff)[_i]), (PG8_LAS unsigned*)(lds + (bufoff) + ldsw + _i * 8192), 16, 0, 0); } while (0)
; #define PG8_LDA(dst, b, h) do { _Pragma("unroll") for (int m = 0; m < 4; ++m) _Pragma("unroll") for (int k = 0; k < 2; ++k) dst[m][k] = *(const PG8_LAS bf16x8*)(lds + PG8_SA(b, h) + aoff + m * 2048 + k * 1024); } while (0)
; #define PG8_LDB(dst, b, h) do { _Pragma("unroll") for (int n = 0; n < 2; ++n) _Pragma("unroll") for (int k = 0; k < 2; ++k) dst[n][k] = *(const PG8_LAS bf16x8*)(lds + PG8_SB(b, h) + boff + n * 2048 + k * 1024); } while (0)
; #define PG8_MMA(ai, bj, At, Bt) do { __builtin_amdgcn_s_setprio(1); _Pragma("unroll") for (int m = 0; m < 4; ++m) _Pragma("unroll") for (int n = 0; n < 2; ++n) _Pragma("unroll") for (int k = 0; k < 2; ++k) \
;         acc[ai][bj][m][n] = mma16<Epi::I8>(Bt[n][k], At[m][k], acc[ai][bj][m][n]); __builtin_amdgcn_s_setprio(0); } while (0)
; #define PG8_WAIT_V(n) asm volatile("s_waitcnt vmcnt(" #n ")" ::: "memory")
; #define PG8_WAIT_L(n) asm volatile("s_waitcnt lgkmcnt(" #n ")" ::: "memory")
; #define PG8_BAR __builtin_amdgcn_s_barrier()
; template <class Epi, class Sched, bool ALIGN_EPI = false, bool SP2 = false>
; __device__ __forceinline__ void gemm_phase(PG8_LAS unsigned char* lds, const Gemm g, const Sched& S, const Epi& E) {
;     ...
;             const bool last = (t == nt - 2);
;             const char* a1 = cA + (size_t)(t + 1) * kstep;
;             const char* a2 = last ? nA : cA + (size_t)(t + 2) * kstep; const char* b2 = last ? nB : cB + (size_t)(t + 2) * kstep;
;             const char* a3 = a2 + kstep; const char* b3 = b2 + kstep;
;             if (last && has_next) S.a_ready(nxt);
;             if constexpr (SP2) {
;             PG8_LDB(B0, 0, 0); PG8_LDB(B1, 0, 1); PG8_SCHED; PG8_LDA(At, 0, 0); PG8_STAGE(PG8_SA(1, 1), a1 + hstep, voffA);
;             PG8_WAIT_V(8); PG8_WAIT_L(0); PG8_BAR; PG8_MMA(0, 0, At, B0); PG8_MMA(0, 1, At, B1); PG8_BAR; PG8_SCHED;
;     ...
;             PG8_LDA(At, 1, 1); PG8_STAGE(PG8_SB(1, 0), b3, voffB); PG8_STAGE(PG8_SB(1, 1), b3 + hstep, voffB); PG8_STAGE(PG8_SA(1, 0), a3, voffA);
;             PG8_WAIT_V(8); PG8_WAIT_L(0); PG8_BAR; PG8_MMA(1, 0, At, B0); PG8_MMA(1, 1, At, B1); PG8_BAR; PG8_SCHED;
	s_add_i32 s4, s84, s80
	v_lshl_add_u64 v[206:207], v[206:207], 0, s[98:99]
	s_mov_b32 m0, s4
	ds_read_b128 v[162:165], v249 offset:49152
	ds_read_b128 v[166:169], v249 offset:50176
	ds_read_b128 v[170:173], v249 offset:51200
	ds_read_b128 v[174:177], v249 offset:52224
	ds_read_b128 v[178:181], v249 offset:53248
	ds_read_b128 v[182:185], v249 offset:54272
	ds_read_b128 v[186:189], v249 offset:55296
	ds_read_b128 v[190:193], v249 offset:56320
	global_load_lds_dwordx4 v[206:207], off
	v_lshl_add_u64 v[206:207], v[212:213], 0, s[98:99]
	s_add_i32 m0, s4, 0x2000
	s_add_i32 s4, vcc_hi, s80
	global_load_lds_dwordx4 v[206:207], off
	v_lshl_add_u64 v[206:207], v[214:215], 0, s[98:99]
	s_mov_b32 m0, s4
	s_nop 0
	global_load_lds_dwordx4 v[206:207], off
	v_lshl_add_u64 v[206:207], v[216:217], 0, s[98:99]
	s_add_i32 m0, s4, 0x2000
	s_nop 0
	global_load_lds_dwordx4 v[206:207], off
	v_lshl_add_u64 v[206:207], v[218:219], 0, s[98:99]
	s_mov_b32 m0, s10
	s_nop 0
	global_load_lds_dwordx4 v[206:207], off
	v_lshl_add_u64 v[206:207], v[220:221], 0, s[98:99]
	s_mov_b32 m0, s11
	s_nop 0
	global_load_lds_dwordx4 v[206:207], off
	s_waitcnt vmcnt(8) lgkmcnt(0)
	s_barrier
	v_mfma_f32_16x16x32_bf16 v[62:65], v[98:101], v[162:165], v[62:65]
	v_mfma_f32_16x16x32_bf16 v[58:61], v[114:117], v[162:165], v[58:61]
	v_mfma_f32_16x16x32_bf16 v[42:45], v[114:117], v[170:173], v[42:45]
	v_mfma_f32_16x16x32_bf16 v[46:49], v[98:101], v[170:173], v[46:49]
	v_mfma_f32_16x16x32_bf16 v[30:33], v[98:101], v[178:181], v[30:33]
	v_mfma_f32_16x16x32_bf16 v[26:29], v[114:117], v[178:181], v[26:29]
	v_mfma_f32_16x16x32_bf16 v[10:13], v[114:117], v[186:189], v[10:13]
	v_mfma_f32_16x16x32_bf16 v[14:17], v[98:101], v[186:189], v[14:17]
	v_mfma_f32_16x16x32_bf16 v[62:65], v[102:105], v[166:169], v[62:65]
	v_mfma_f32_16x16x32_bf16 v[58:61], v[122:125], v[166:169], v[58:61]
	v_mfma_f32_16x16x32_bf16 v[42:45], v[122:125], v[174:177], v[42:45]
	v_mfma_f32_16x16x32_bf16 v[46:49], v[102:105], v[174:177], v[46:49]
	v_mfma_f32_16x16x32_bf16 v[30:33], v[102:105], v[182:185], v[30:33]
	v_mfma_f32_16x16x32_bf16 v[26:29], v[122:125], v[182:185], v[26:29]
	v_mfma_f32_16x16x32_bf16 v[10:13], v[122:125], v[190:193], v[10:13]
	v_mfma_f32_16x16x32_bf16 v[14:17], v[102:105], v[190:193], v[14:17]
	v_mfma_f32_16x16x32_bf16 v[54:57], v[130:133], v[162:165], v[54:57]
	v_mfma_f32_16x16x32_bf16 v[50:53], v[146:149], v[162:165], v[50:53]
	v_mfma_f32_16x16x32_bf16 v[34:37], v[146:149], v[170:173], v[34:37]
	v_mfma_f32_16x16x32_bf16 v[38:41], v[130:133], v[170:173], v[38:41]
	v_mfma_f32_16x16x32_bf16 v[22:25], v[130:133], v[178:181], v[22:25]
	v_mfma_f32_16x16x32_bf16 v[18:21], v[146:149], v[178:181], v[18:21]
	v_mfma_f32_16x16x32_bf16 v[2:5], v[146:149], v[186:189], v[2:5]
	v_mfma_f32_16x16x32_bf16 v[6:9], v[130:133], v[186:189], v[6:9]
	v_mfma_f32_16x16x32_bf16 v[54:57], v[138:141], v[166:169], v[54:57]
	v_mfma_f32_16x16x32_bf16 v[50:53], v[154:157], v[166:169], v[50:53]
	v_mfma_f32_16x16x32_bf16 v[34:37], v[154:157], v[174:177], v[34:37]
	v_mfma_f32_16x16x32_bf16 v[38:41], v[138:141], v[174:177], v[38:41]
	v_mfma_f32_16x16x32_bf16 v[22:25], v[138:141], v[182:185], v[22:25]
	v_mfma_f32_16x16x32_bf16 v[18:21], v[154:157], v[182:185], v[18:21]
	v_mfma_f32_16x16x32_bf16 v[2:5], v[154:157], v[190:193], v[2:5]
	v_mfma_f32_16x16x32_bf16 v[6:9], v[138:141], v[190:193], v[6:9]
	s_barrier
	s_add_u32 s6, s6, s98
	s_addc_u32 s7, s7, 0
	s_add_u32 s6, s6, s98
	s_addc_u32 s7, s7, 0
	s_add_u32 s67, s67, s98
	s_addc_u32 s85, s85, 0
	s_add_u32 s67, s67, s98
	s_addc_u32 s85, s85, 0
	s_cmp_ge_u32 vcc_lo, s69
	s_mov_b32 s8, vcc_lo
	s_cbranch_scc0 .LBB0_175
	s_branch .Lpeelx175
.LBB0_175:
	s_add_i32 vcc_lo, s8, 2
	s_add_u32 s4, s6, s98
	s_addc_u32 s5, s7, 0
	s_add_i32 vcc_hi, 0, 0x10000
	s_cmp_eq_u32 s13, s8
	s_cselect_b32 s9, s1, s5
	s_cselect_b32 s8, s0, s4
	s_cselect_b32 s5, s97, s85
	s_cselect_b32 s4, s96, s67
	s_add_i32 s84, 0, 0x14000
	v_add_u32_e32 v122, vcc_hi, v248
	v_add_u32_e32 v154, s84, v248
	ds_read_b128 v[98:101], v122
	ds_read_b128 v[102:105], v122 offset:1024
	ds_read_b128 v[114:117], v122 offset:2048
	ds_read_b128 v[122:125], v122 offset:3072
	ds_read_b128 v[130:133], v154
	ds_read_b128 v[138:141], v154 offset:1024
	ds_read_b128 v[146:149], v154 offset:2048
	ds_read_b128 v[154:157], v154 offset:3072
	v_lshl_add_u64 v[206:207], s[6:7], 0, v[200:201]
	s_add_i32 m0, s81, 0xc000
	ds_read_b128 v[162:165], v249
	ds_read_b128 v[166:169], v249 offset:1024
	ds_read_b128 v[170:173], v249 offset:2048
	ds_read_b128 v[174:177], v249 offset:3072
	ds_read_b128 v[178:181], v249 offset:4096
	ds_read_b128 v[182:185], v249 offset:5120
	ds_read_b128 v[186:189], v249 offset:6144
	ds_read_b128 v[190:193], v249 offset:7168
	global_load_lds_dwordx4 v[206:207], off
	v_lshl_add_u64 v[206:207], s[6:7], 0, v[210:211]
	s_add_i32 m0, s81, 0xe000
	s_nop 0
	global_load_lds_dwordx4 v[206:207], off
	s_waitcnt vmcnt(8) lgkmcnt(0)
	s_barrier
; #define PG8_STAGE(bufoff, gbase, voff) do { _Pragma("unroll") for (int _i = 0; _i < 2; ++_i) \
;         __builtin_amdgcn_global_load_lds((const unsigned*)((const char*)(gbase) + (voff)[_i]), (PG8_LAS unsigned*)(lds + (bufoff) + ldsw + _i * 8192), 16, 0, 0); } while (0)
; #define PG8_LDA(dst, b, h) do { _Pragma("unroll") for (int m = 0; m < 4; ++m) _Pragma("unroll") for (int k = 0; k < 2; ++k) dst[m][k] = *(const PG8_LAS bf16x8*)(lds + PG8_SA(b, h) + aoff + m * 2048 + k * 1024); } while (0)
; #define PG8_MMA(ai, bj, At, Bt) do { __builtin_amdgcn_s_setprio(1); _Pragma("unroll") for (int m = 0; m < 4; ++m) _Pragma("unroll") for (int n = 0; n < 2; ++n) _Pragma("unroll") for (int k = 0; k < 2; ++k) \
;         acc[ai][bj][m][n] = mma16<Epi::I8>(Bt[n][k], At[m][k], acc[ai][bj][m][n]); __builtin_amdgcn_s_setprio(0); } while (0)
; #define PG8_WAIT_V(n) asm volatile("s_waitcnt vmcnt(" #n ")" ::: "memory")
; #define PG8_WAIT_L(n) asm volatile("s_waitcnt lgkmcnt(" #n ")" ::: "memory")
; #define PG8_BAR __builtin_amdgcn_s_barrier()
; #define PG8_SCHED __builtin_amdgcn_sched_barrier(0)
; template <class Epi, class Sched, bool ALIGN_EPI = false, bool SP2 = false>
; __device__ __forceinline__ void gemm_phase(PG8_LAS unsigned char* lds, const Gemm g, const Sched& S, const Epi& E) {
;     ...
;             PG8_WAIT_V(8); PG8_WAIT_L(0); PG8_BAR; PG8_MMA(0, 0, At, B0); PG8_MMA(0, 1, At, B1); PG8_BAR; PG8_SCHED;
;             PG8_LDA(At, 0, 1); PG8_STAGE(PG8_SB(0, 0), b2, voffB); PG8_STAGE(PG8_SB(0, 1), b2 + hstep, voffB); PG8_STAGE(PG8_SA(0, 0), a2, voffA);
;             PG8_WAIT_V(8); PG8_WAIT_L(0); PG8_BAR; PG8_MMA(1, 0, At, B0); PG8_MMA(1, 1, At, B1); PG8_BAR; PG8_SCHED;
	v_mfma_f32_16x16x32_bf16 v[158:161], v[98:101], v[162:165], v[158:161]
	v_mfma_f32_16x16x32_bf16 v[150:153], v[114:117], v[162:165], v[150:153]
	v_mfma_f32_16x16x32_bf16 v[118:121], v[114:117], v[170:173], v[118:121]
	v_mfma_f32_16x16x32_bf16 v[126:129], v[98:101], v[170:173], v[126:129]
	v_mfma_f32_16x16x32_bf16 v[94:97], v[98:101], v[178:181], v[94:97]
	v_mfma_f32_16x16x32_bf16 v[90:93], v[114:117], v[178:181], v[90:93]
	v_mfma_f32_16x16x32_bf16 v[74:77], v[114:117], v[186:189], v[74:77]
	v_mfma_f32_16x16x32_bf16 v[78:81], v[98:101], v[186:189], v[78:81]
	v_mfma_f32_16x16x32_bf16 v[158:161], v[102:105], v[166:169], v[158:161]
	v_mfma_f32_16x16x32_bf16 v[150:153], v[122:125], v[166:169], v[150:153]
	v_mfma_f32_16x16x32_bf16 v[118:121], v[122:125], v[174:177], v[118:121]
	v_mfma_f32_16x16x32_bf16 v[126:129], v[102:105], v[174:177], v[126:129]
	v_mfma_f32_16x16x32_bf16 v[94:97], v[102:105], v[182:185], v[94:97]
	v_mfma_f32_16x16x32_bf16 v[90:93], v[122:125], v[182:185], v[90:93]
	v_mfma_f32_16x16x32_bf16 v[74:77], v[122:125], v[190:193], v[74:77]
	v_mfma_f32_16x16x32_bf16 v[78:81], v[102:105], v[190:193], v[78:81]
	v_mfma_f32_16x16x32_bf16 v[142:145], v[130:133], v[162:165], v[142:145]
	v_mfma_f32_16x16x32_bf16 v[134:137], v[146:149], v[162:165], v[134:137]
	v_mfma_f32_16x16x32_bf16 v[106:109], v[146:149], v[170:173], v[106:109]
	v_mfma_f32_16x16x32_bf16 v[110:113], v[130:133], v[170:173], v[110:113]
	v_mfma_f32_16x16x32_bf16 v[86:89], v[130:133], v[178:181], v[86:89]
	v_mfma_f32_16x16x32_bf16 v[82:85], v[146:149], v[178:181], v[82:85]
	v_mfma_f32_16x16x32_bf16 v[66:69], v[146:149], v[186:189], v[66:69]
	v_mfma_f32_16x16x32_bf16 v[70:73], v[130:133], v[186:189], v[70:73]
	v_mfma_f32_16x16x32_bf16 v[142:145], v[138:141], v[166:169], v[142:145]
	v_mfma_f32_16x16x32_bf16 v[134:137], v[154:157], v[166:169], v[134:137]
	v_mfma_f32_16x16x32_bf16 v[106:109], v[154:157], v[174:177], v[106:109]
	v_mfma_f32_16x16x32_bf16 v[110:113], v[138:141], v[174:177], v[110:113]
	v_mfma_f32_16x16x32_bf16 v[86:89], v[138:141], v[182:185], v[86:89]
	v_mfma_f32_16x16x32_bf16 v[82:85], v[154:157], v[182:185], v[82:85]
	v_mfma_f32_16x16x32_bf16 v[66:69], v[154:157], v[190:193], v[66:69]
	v_mfma_f32_16x16x32_bf16 v[70:73], v[138:141], v[190:193], v[70:73]
	s_barrier
	s_add_i32 vcc_hi, vcc_hi, s80
	v_lshl_add_u64 v[206:207], s[4:5], 0, v[0:1]
	s_mov_b32 m0, vcc_hi
	ds_read_b128 v[162:165], v249 offset:16384
	ds_read_b128 v[166:169], v249 offset:17408
	ds_read_b128 v[170:173], v249 offset:18432
	ds_read_b128 v[174:177], v249 offset:19456
	ds_read_b128 v[178:181], v249 offset:20480
	ds_read_b128 v[182:185], v249 offset:21504
	ds_read_b128 v[186:189], v249 offset:22528
	ds_read_b128 v[190:193], v249 offset:23552
	global_load_lds_dwordx4 v[206:207], off
	s_add_i32 m0, vcc_hi, 0x2000
	v_lshl_add_u64 v[212:213], s[4:5], 0, v[198:199]
	s_add_u32 s4, s4, s100
	s_addc_u32 s5, s5, 0
	s_add_i32 s84, s84, s80
	global_load_lds_dwordx4 v[212:213], off
	v_lshl_add_u64 v[214:215], s[4:5], 0, v[0:1]
	s_mov_b32 m0, s84
	v_lshl_add_u64 v[216:217], s[4:5], 0, v[198:199]
	global_load_lds_dwordx4 v[214:215], off
	s_add_i32 m0, s84, 0x2000
	v_lshl_add_u64 v[218:219], s[8:9], 0, v[194:195]
	global_load_lds_dwordx4 v[216:217], off
	s_mov_b32 m0, s81
	v_lshl_add_u64 v[220:221], s[8:9], 0, v[196:197]
	global_load_lds_dwordx4 v[218:219], off
	s_mov_b32 m0, s70
	s_nop 0
	global_load_lds_dwordx4 v[220:221], off
	s_waitcnt vmcnt(8) lgkmcnt(0)
	s_barrier
	v_mfma_f32_16x16x32_bf16 v[62:65], v[98:101], v[162:165], v[62:65]
	v_mfma_f32_16x16x32_bf16 v[58:61], v[114:117], v[162:165], v[58:61]
	v_mfma_f32_16x16x32_bf16 v[42:45], v[114:117], v[170:173], v[42:45]
	v_mfma_f32_16x16x32_bf16 v[46:49], v[98:101], v[170:173], v[46:49]
	v_mfma_f32_16x16x32_bf16 v[30:33], v[98:101], v[178:181], v[30:33]
	v_mfma_f32_16x16x32_bf16 v[26:29], v[114:117], v[178:181], v[26:29]
	v_mfma_f32_16x16x32_bf16 v[10:13], v[114:117], v[186:189], v[10:13]
	v_mfma_f32_16x16x32_bf16 v[14:17], v[98:101], v[186:189], v[14:17]
	v_mfma_f32_16x16x32_bf16 v[62:65], v[102:105], v[166:169], v[62:65]
	v_mfma_f32_16x16x32_bf16 v[58:61], v[122:125], v[166:169], v[58:61]
	v_mfma_f32_16x16x32_bf16 v[42:45], v[122:125], v[174:177], v[42:45]
	v_mfma_f32_16x16x32_bf16 v[46:49], v[102:105], v[174:177], v[46:49]
	v_mfma_f32_16x16x32_bf16 v[30:33], v[102:105], v[182:185], v[30:33]
	v_mfma_f32_16x16x32_bf16 v[26:29], v[122:125], v[182:185], v[26:29]
	v_mfma_f32_16x16x32_bf16 v[10:13], v[122:125], v[190:193], v[10:13]
	v_mfma_f32_16x16x32_bf16 v[14:17], v[102:105], v[190:193], v[14:17]
	v_mfma_f32_16x16x32_bf16 v[54:57], v[130:133], v[162:165], v[54:57]
	v_mfma_f32_16x16x32_bf16 v[50:53], v[146:149], v[162:165], v[50:53]
	v_mfma_f32_16x16x32_bf16 v[34:37], v[146:149], v[170:173], v[34:37]
	v_mfma_f32_16x16x32_bf16 v[38:41], v[130:133], v[170:173], v[38:41]
	v_mfma_f32_16x16x32_bf16 v[22:25], v[130:133], v[178:181], v[22:25]
	v_mfma_f32_16x16x32_bf16 v[18:21], v[146:149], v[178:181], v[18:21]
	v_mfma_f32_16x16x32_bf16 v[2:5], v[146:149], v[186:189], v[2:5]
	v_mfma_f32_16x16x32_bf16 v[6:9], v[130:133], v[186:189], v[6:9]
	v_mfma_f32_16x16x32_bf16 v[54:57], v[138:141], v[166:169], v[54:57]
	v_mfma_f32_16x16x32_bf16 v[50:53], v[154:157], v[166:169], v[50:53]
	v_mfma_f32_16x16x32_bf16 v[34:37], v[154:157], v[174:177], v[34:37]
	v_mfma_f32_16x16x32_bf16 v[38:41], v[138:141], v[174:177], v[38:41]
	v_mfma_f32_16x16x32_bf16 v[22:25], v[138:141], v[182:185], v[22:25]
	v_mfma_f32_16x16x32_bf16 v[18:21], v[154:157], v[182:185], v[18:21]
	v_mfma_f32_16x16x32_bf16 v[2:5], v[154:157], v[190:193], v[2:5]
	v_mfma_f32_16x16x32_bf16 v[6:9], v[138:141], v[190:193], v[6:9]
	s_barrier
; #define PG8_STAGE(bufoff, gbase, voff) do { _Pragma("unroll") for (int _i = 0; _i < 2; ++_i) \
;         __builtin_amdgcn_global_load_lds((const unsigned*)((const char*)(gbase) + (voff)[_i]), (PG8_LAS unsigned*)(lds + (bufoff) + ldsw + _i * 8192), 16, 0, 0); } while (0)
; #define PG8_LDA(dst, b, h) do { _Pragma("unroll") for (int m = 0; m < 4; ++m) _Pragma("unroll") for (int k = 0; k < 2; ++k) dst[m][k] = *(const PG8_LAS bf16x8*)(lds + PG8_SA(b, h) + aoff + m * 2048 + k * 1024); } while (0)
; #define PG8_LDB(dst, b, h) do { _Pragma("unroll") for (int n = 0; n < 2; ++n) _Pragma("unroll") for (int k = 0; k < 2; ++k) dst[n][k] = *(const PG8_LAS bf16x8*)(lds + PG8_SB(b, h) + boff + n * 2048 + k * 1024); } while (0)
; #define PG8_MMA(ai, bj, At, Bt) do { __builtin_amdgcn_s_setprio(1); _Pragma("unroll") for (int m = 0; m < 4; ++m) _Pragma("unroll") for (int n = 0; n < 2; ++n) _Pragma("unroll") for (int k = 0; k < 2; ++k) \
;         acc[ai][bj][m][n] = mma16<Epi::I8>(Bt[n][k], At[m][k], acc[ai][bj][m][n]); __builtin_amdgcn_s_setprio(0); } while (0)
; #define PG8_WAIT_V(n) asm volatile("s_waitcnt vmcnt(" #n ")" ::: "memory")
; #define PG8_WAIT_L(n) asm volatile("s_waitcnt lgkmcnt(" #n ")" ::: "memory")
; #define PG8_BAR __builtin_amdgcn_s_barrier()
; #define PG8_SCHED __builtin_amdgcn_sched_barrier(0)
; template <class Epi, class Sched, bool ALIGN_EPI = false, bool SP2 = false>
; __device__ __forceinline__ void gemm_phase(PG8_LAS unsigned char* lds, const Gemm g, const Sched& S, const Epi& E) {
;     ...
;             PG8_LDB(B0, 1, 0); PG8_LDB(B1, 1, 1); PG8_SCHED; PG8_LDA(At, 1, 0); PG8_STAGE(PG8_SA(0, 1), a2 + hstep, voffA);
;             PG8_WAIT_V(8); PG8_WAIT_L(0); PG8_BAR; PG8_MMA(0, 0, At, B0); PG8_MMA(0, 1, At, B1); PG8_BAR; PG8_SCHED;
;             PG8_LDA(At, 1, 1); PG8_STAGE(PG8_SB(1, 0), b3, voffB); PG8_STAGE(PG8_SB(1, 1), b3 + hstep, voffB); PG8_STAGE(PG8_SA(1, 0), a3, voffA);
;             PG8_WAIT_V(8); PG8_WAIT_L(0); PG8_BAR; PG8_MMA(1, 0, At, B0); PG8_MMA(1, 1, At, B1); PG8_BAR; PG8_SCHED;
	s_add_i32 s84, 0, 0x18000
	s_add_i32 vcc_hi, 0, 0x1c000
	v_add_u32_e32 v122, s84, v248
	v_add_u32_e32 v154, vcc_hi, v248
	ds_read_b128 v[98:101], v122
	ds_read_b128 v[102:105], v122 offset:1024
	ds_read_b128 v[114:117], v122 offset:2048
	ds_read_b128 v[122:125], v122 offset:3072
	ds_read_b128 v[130:133], v154
	ds_read_b128 v[138:141], v154 offset:1024
	ds_read_b128 v[146:149], v154 offset:2048
	ds_read_b128 v[154:157], v154 offset:3072
	s_add_u32 s4, s8, s100
	s_addc_u32 s5, s9, 0
	s_mov_b32 m0, s71
	v_lshl_add_u64 v[222:223], s[4:5], 0, v[194:195]
	ds_read_b128 v[162:165], v249 offset:32768
	ds_read_b128 v[166:169], v249 offset:33792
	ds_read_b128 v[170:173], v249 offset:34816
	ds_read_b128 v[174:177], v249 offset:35840
	ds_read_b128 v[178:181], v249 offset:36864
	ds_read_b128 v[182:185], v249 offset:37888
	ds_read_b128 v[186:189], v249 offset:38912
	ds_read_b128 v[190:193], v249 offset:39936
	global_load_lds_dwordx4 v[222:223], off
	v_lshl_add_u64 v[222:223], s[4:5], 0, v[196:197]
	s_mov_b32 m0, s12
	s_nop 0
	global_load_lds_dwordx4 v[222:223], off
	s_waitcnt vmcnt(8) lgkmcnt(0)
	s_barrier
	v_mfma_f32_16x16x32_bf16 v[158:161], v[98:101], v[162:165], v[158:161]
	v_mfma_f32_16x16x32_bf16 v[150:153], v[114:117], v[162:165], v[150:153]
	v_mfma_f32_16x16x32_bf16 v[118:121], v[114:117], v[170:173], v[118:121]
	v_mfma_f32_16x16x32_bf16 v[126:129], v[98:101], v[170:173], v[126:129]
	v_mfma_f32_16x16x32_bf16 v[94:97], v[98:101], v[178:181], v[94:97]
	v_mfma_f32_16x16x32_bf16 v[90:93], v[114:117], v[178:181], v[90:93]
	v_mfma_f32_16x16x32_bf16 v[74:77], v[114:117], v[186:189], v[74:77]
	v_mfma_f32_16x16x32_bf16 v[78:81], v[98:101], v[186:189], v[78:81]
	v_mfma_f32_16x16x32_bf16 v[158:161], v[102:105], v[166:169], v[158:161]
	v_mfma_f32_16x16x32_bf16 v[150:153], v[122:125], v[166:169], v[150:153]
	v_mfma_f32_16x16x32_bf16 v[118:121], v[122:125], v[174:177], v[118:121]
	v_mfma_f32_16x16x32_bf16 v[126:129], v[102:105], v[174:177], v[126:129]
	v_mfma_f32_16x16x32_bf16 v[94:97], v[102:105], v[182:185], v[94:97]
	v_mfma_f32_16x16x32_bf16 v[90:93], v[122:125], v[182:185], v[90:93]
	v_mfma_f32_16x16x32_bf16 v[74:77], v[122:125], v[190:193], v[74:77]
	v_mfma_f32_16x16x32_bf16 v[78:81], v[102:105], v[190:193], v[78:81]
	v_mfma_f32_16x16x32_bf16 v[142:145], v[130:133], v[162:165], v[142:145]
	v_mfma_f32_16x16x32_bf16 v[134:137], v[146:149], v[162:165], v[134:137]
	v_mfma_f32_16x16x32_bf16 v[106:109], v[146:149], v[170:173], v[106:109]
	v_mfma_f32_16x16x32_bf16 v[110:113], v[130:133], v[170:173], v[110:113]
	v_mfma_f32_16x16x32_bf16 v[86:89], v[130:133], v[178:181], v[86:89]
	v_mfma_f32_16x16x32_bf16 v[82:85], v[146:149], v[178:181], v[82:85]
	v_mfma_f32_16x16x32_bf16 v[66:69], v[146:149], v[186:189], v[66:69]
	v_mfma_f32_16x16x32_bf16 v[70:73], v[130:133], v[186:189], v[70:73]
	v_mfma_f32_16x16x32_bf16 v[142:145], v[138:141], v[166:169], v[142:145]
	v_mfma_f32_16x16x32_bf16 v[134:137], v[154:157], v[166:169], v[134:137]
	v_mfma_f32_16x16x32_bf16 v[106:109], v[154:157], v[174:177], v[106:109]
	v_mfma_f32_16x16x32_bf16 v[110:113], v[138:141], v[174:177], v[110:113]
	v_mfma_f32_16x16x32_bf16 v[86:89], v[138:141], v[182:185], v[86:89]
	v_mfma_f32_16x16x32_bf16 v[82:85], v[154:157], v[182:185], v[82:85]
	v_mfma_f32_16x16x32_bf16 v[66:69], v[154:157], v[190:193], v[66:69]
	v_mfma_f32_16x16x32_bf16 v[70:73], v[138:141], v[190:193], v[70:73]
	s_barrier
	s_add_i32 s4, s84, s80
	v_lshl_add_u64 v[206:207], v[206:207], 0, s[98:99]
	s_mov_b32 m0, s4
	ds_read_b128 v[162:165], v249 offset:49152
	ds_read_b128 v[166:169], v249 offset:50176
	ds_read_b128 v[170:173], v249 offset:51200
	ds_read_b128 v[174:177], v249 offset:52224
	ds_read_b128 v[178:181], v249 offset:53248
	ds_read_b128 v[182:185], v249 offset:54272
	ds_read_b128 v[186:189], v249 offset:55296
	ds_read_b128 v[190:193], v249 offset:56320
	global_load_lds_dwordx4 v[206:207], off
	v_lshl_add_u64 v[206:207], v[212:213], 0, s[98:99]
	s_add_i32 m0, s4, 0x2000
	s_add_i32 s4, vcc_hi, s80
	global_load_lds_dwordx4 v[206:207], off
	v_lshl_add_u64 v[206:207], v[214:215], 0, s[98:99]
	s_mov_b32 m0, s4
	s_nop 0
	global_load_lds_dwordx4 v[206:207], off
	v_lshl_add_u64 v[206:207], v[216:217], 0, s[98:99]
	s_add_i32 m0, s4, 0x2000
	s_nop 0
	global_load_lds_dwordx4 v[206:207], off
	v_lshl_add_u64 v[206:207], v[218:219], 0, s[98:99]
	s_mov_b32 m0, s10
	s_nop 0
	global_load_lds_dwordx4 v[206:207], off
	v_lshl_add_u64 v[206:207], v[220:221], 0, s[98:99]
	s_mov_b32 m0, s11
	s_nop 0
	global_load_lds_dwordx4 v[206:207], off
	s_waitcnt vmcnt(8) lgkmcnt(0)
	s_barrier
	v_mfma_f32_16x16x32_bf16 v[62:65], v[98:101], v[162:165], v[62:65]
	v_mfma_f32_16x16x32_bf16 v[58:61], v[114:117], v[162:165], v[58:61]
	v_mfma_f32_16x16x32_bf16 v[42:45], v[114:117], v[170:173], v[42:45]
	v_mfma_f32_16x16x32_bf16 v[46:49], v[98:101], v[170:173], v[46:49]
	v_mfma_f32_16x16x32_bf16 v[30:33], v[98:101], v[178:181], v[30:33]
	v_mfma_f32_16x16x32_bf16 v[26:29], v[114:117], v[178:181], v[26:29]
	v_mfma_f32_16x16x32_bf16 v[10:13], v[114:117], v[186:189], v[10:13]
	v_mfma_f32_16x16x32_bf16 v[14:17], v[98:101], v[186:189], v[14:17]
	v_mfma_f32_16x16x32_bf16 v[62:65], v[102:105], v[166:169], v[62:65]
	v_mfma_f32_16x16x32_bf16 v[58:61], v[122:125], v[166:169], v[58:61]
	v_mfma_f32_16x16x32_bf16 v[42:45], v[122:125], v[174:177], v[42:45]
	v_mfma_f32_16x16x32_bf16 v[46:49], v[102:105], v[174:177], v[46:49]
	v_mfma_f32_16x16x32_bf16 v[30:33], v[102:105], v[182:185], v[30:33]
	v_mfma_f32_16x16x32_bf16 v[26:29], v[122:125], v[182:185], v[26:29]
	v_mfma_f32_16x16x32_bf16 v[10:13], v[122:125], v[190:193], v[10:13]
	v_mfma_f32_16x16x32_bf16 v[14:17], v[102:105], v[190:193], v[14:17]
	v_mfma_f32_16x16x32_bf16 v[54:57], v[130:133], v[162:165], v[54:57]
	v_mfma_f32_16x16x32_bf16 v[50:53], v[146:149], v[162:165], v[50:53]
	v_mfma_f32_16x16x32_bf16 v[34:37], v[146:149], v[170:173], v[34:37]
	v_mfma_f32_16x16x32_bf16 v[38:41], v[130:133], v[170:173], v[38:41]
	v_mfma_f32_16x16x32_bf16 v[22:25], v[130:133], v[178:181], v[22:25]
	v_mfma_f32_16x16x32_bf16 v[18:21], v[146:149], v[178:181], v[18:21]
	v_mfma_f32_16x16x32_bf16 v[2:5], v[146:149], v[186:189], v[2:5]
	v_mfma_f32_16x16x32_bf16 v[6:9], v[130:133], v[186:189], v[6:9]
	v_mfma_f32_16x16x32_bf16 v[54:57], v[138:141], v[166:169], v[54:57]
	v_mfma_f32_16x16x32_bf16 v[50:53], v[154:157], v[166:169], v[50:53]
	v_mfma_f32_16x16x32_bf16 v[34:37], v[154:157], v[174:177], v[34:37]
	v_mfma_f32_16x16x32_bf16 v[38:41], v[138:141], v[174:177], v[38:41]
	v_mfma_f32_16x16x32_bf16 v[22:25], v[138:141], v[182:185], v[22:25]
	v_mfma_f32_16x16x32_bf16 v[18:21], v[154:157], v[182:185], v[18:21]
	v_mfma_f32_16x16x32_bf16 v[2:5], v[154:157], v[190:193], v[2:5]
	v_mfma_f32_16x16x32_bf16 v[6:9], v[138:141], v[190:193], v[6:9]
	s_barrier
	s_add_u32 s6, s6, s98
	s_addc_u32 s7, s7, 0
	s_add_u32 s6, s6, s98
	s_addc_u32 s7, s7, 0
	s_add_u32 s67, s67, s98
	s_addc_u32 s85, s85, 0
	s_add_u32 s67, s67, s98
	s_addc_u32 s85, s85, 0
	s_cmp_ge_u32 vcc_lo, s69
	s_mov_b32 s8, vcc_lo
	s_cbranch_scc0 .LBB0_175

; #define PG8_STAGE(bufoff, gbase, voff) do { _Pragma("unroll") for (int _i = 0; _i < 2; ++_i) \
;         __builtin_amdgcn_global_load_lds((const unsigned*)((const char*)(gbase) + (voff)[_i]), (PG8_LAS unsigned*)(lds + (bufoff) + ldsw + _i * 8192), 16, 0, 0); } while (0)
; #define PG8_LDA(dst, b, h) do { _Pragma("unroll") for (int m = 0; m < 4; ++m) _Pragma("unroll") for (int k = 0; k < 2; ++k) dst[m][k] = *(const PG8_LAS bf16x8*)(lds + PG8_SA(b, h) + aoff + m * 2048 + k * 1024); } while (0)
; #define PG8_LDB(dst, b, h) do { _Pragma("unroll") for (int n = 0; n < 2; ++n) _Pragma("unroll") for (int k = 0; k < 2; ++k) dst[n][k] = *(const PG8_LAS bf16x8*)(lds + PG8_SB(b, h) + boff + n * 2048 + k * 1024); } while (0)
; #define PG8_MMA(ai, bj, At, Bt) do { __builtin_amdgcn_s_setprio(1); _Pragma("unroll") for (int m = 0; m < 4; ++m) _Pragma("unroll") for (int n = 0; n < 2; ++n) _Pragma("unroll") for (int k = 0; k < 2; ++k) \
;         acc[ai][bj][m][n] = mma16<Epi::I8>(Bt[n][k], At[m][k], acc[ai][bj][m][n]); __builtin_amdgcn_s_setprio(0); } while (0)
; #define PG8_WAIT_V(n) asm volatile("s_waitcnt vmcnt(" #n ")" ::: "memory")
; #define PG8_WAIT_L(n) asm volatile("s_waitcnt lgkmcnt(" #n ")" ::: "memory")
; #define PG8_BAR __builtin_amdgcn_s_barrier()
; template <class Epi, class Sched, bool ALIGN_EPI = false, bool SP2 = false>
; __device__ __forceinline__ void gemm_phase(PG8_LAS unsigned char* lds, const Gemm g, const Sched& S, const Epi& E) {
;     ...
;             const bool last = (t == nt - 2);
;             const char* a1 = cA + (size_t)(t + 1) * kstep;
;             const char* a2 = last ? nA : cA + (size_t)(t + 2) * kstep; const char* b2 = last ? nB : cB + (size_t)(t + 2) * kstep;
;             const char* a3 = a2 + kstep; const char* b3 = b2 + kstep;
;             if (last && has_next) S.a_ready(nxt);
;             if constexpr (SP2) {
;             PG8_LDB(B0, 0, 0); PG8_LDB(B1, 0, 1); PG8_SCHED; PG8_LDA(At, 0, 0); PG8_STAGE(PG8_SA(1, 1), a1 + hstep, voffA);
;             PG8_WAIT_V(8); PG8_WAIT_L(0); PG8_BAR; PG8_MMA(0, 0, At, B0); PG8_MMA(0, 1, At, B1); PG8_BAR; PG8_SCHED;
;             PG8_LDA(At, 0, 1); PG8_STAGE(PG8_SB(0, 0), b2, voffB); PG8_STAGE(PG8_SB(0, 1), b2 + hstep, voffB); PG8_STAGE(PG8_SA(0, 0), a2, voffA);
;             PG8_WAIT_V(8); PG8_WAIT_L(0); PG8_BAR; PG8_MMA(1, 0, At, B0); PG8_MMA(1, 1, At, B1); PG8_BAR; PG8_SCHED;
.Lpeel291:
	s_add_u32 s84, s8, 0x100
	s_addc_u32 s85, s9, 0
	s_add_i32 s66, 0, 0x10000
	s_cmp_eq_u32 s10, 12
	s_cselect_b32 vcc_hi, s5, s85
	s_cselect_b32 vcc_lo, s7, s84
	s_cselect_b32 s97, s11, s68
	s_cselect_b32 s96, s67, s69
	s_add_i32 s70, 0, 0x14000
	v_add_u32_e32 v110, s66, v175
	v_add_u32_e32 v168, s70, v175
	s_waitcnt vmcnt(0)
	ds_read_b128 v[66:69], v110
	ds_read_b128 v[70:73], v110 offset:1024
	ds_read_b128 v[106:109], v110 offset:2048
	ds_read_b128 v[110:113], v110 offset:3072
	ds_read_b128 v[114:117], v168
	ds_read_b128 v[118:121], v168 offset:1024
	ds_read_b128 v[126:129], v168 offset:2048
	ds_read_b128 v[178:181], v168 offset:3072
	v_lshl_add_u64 v[168:169], s[8:9], 0, v[164:165]
	s_add_i32 m0, s1, 0xc000
	ds_read_b128 v[182:185], v177
	ds_read_b128 v[186:189], v177 offset:1024
	ds_read_b128 v[190:193], v177 offset:2048
	ds_read_b128 v[194:197], v177 offset:3072
	ds_read_b128 v[198:201], v177 offset:4096
	ds_read_b128 v[210:213], v177 offset:5120
	ds_read_b128 v[214:217], v177 offset:6144
	ds_read_b128 v[218:221], v177 offset:7168
	global_load_lds_dwordx4 v[168:169], off
	v_lshl_add_u64 v[168:169], s[8:9], 0, v[166:167]
	s_add_i32 m0, s1, 0xe000
	s_nop 0
	global_load_lds_dwordx4 v[168:169], off
	s_waitcnt vmcnt(8) lgkmcnt(0)
	s_barrier
	v_mfma_i32_16x16x64_i8 v[154:157], v[66:69], v[182:185], 0
	v_mfma_i32_16x16x64_i8 v[146:149], v[106:109], v[182:185], 0
	v_mfma_i32_16x16x64_i8 v[138:141], v[106:109], v[190:193], 0
	v_mfma_i32_16x16x64_i8 v[150:153], v[66:69], v[190:193], 0
	v_mfma_i32_16x16x64_i8 v[142:145], v[66:69], v[198:201], 0
	v_mfma_i32_16x16x64_i8 v[130:133], v[106:109], v[198:201], 0
	v_mfma_i32_16x16x64_i8 v[122:125], v[106:109], v[214:217], 0
	v_mfma_i32_16x16x64_i8 v[134:137], v[66:69], v[214:217], 0
	v_mfma_i32_16x16x64_i8 v[154:157], v[70:73], v[186:189], v[154:157]
	v_mfma_i32_16x16x64_i8 v[146:149], v[110:113], v[186:189], v[146:149]
	v_mfma_i32_16x16x64_i8 v[138:141], v[110:113], v[194:197], v[138:141]
	v_mfma_i32_16x16x64_i8 v[150:153], v[70:73], v[194:197], v[150:153]
	v_mfma_i32_16x16x64_i8 v[142:145], v[70:73], v[210:213], v[142:145]
	v_mfma_i32_16x16x64_i8 v[130:133], v[110:113], v[210:213], v[130:133]
	v_mfma_i32_16x16x64_i8 v[122:125], v[110:113], v[218:221], v[122:125]
	v_mfma_i32_16x16x64_i8 v[134:137], v[70:73], v[218:221], v[134:137]
	v_mfma_i32_16x16x64_i8 v[102:105], v[114:117], v[182:185], 0
	v_mfma_i32_16x16x64_i8 v[94:97], v[126:129], v[182:185], 0
	v_mfma_i32_16x16x64_i8 v[86:89], v[126:129], v[190:193], 0
	v_mfma_i32_16x16x64_i8 v[98:101], v[114:117], v[190:193], 0
	v_mfma_i32_16x16x64_i8 v[90:93], v[114:117], v[198:201], 0
	v_mfma_i32_16x16x64_i8 v[78:81], v[126:129], v[198:201], 0
	v_mfma_i32_16x16x64_i8 v[74:77], v[126:129], v[214:217], 0
	v_mfma_i32_16x16x64_i8 v[82:85], v[114:117], v[214:217], 0
	v_mfma_i32_16x16x64_i8 v[102:105], v[118:121], v[186:189], v[102:105]
	v_mfma_i32_16x16x64_i8 v[94:97], v[178:181], v[186:189], v[94:97]
	v_mfma_i32_16x16x64_i8 v[86:89], v[178:181], v[194:197], v[86:89]
	v_mfma_i32_16x16x64_i8 v[98:101], v[118:121], v[194:197], v[98:101]
	v_mfma_i32_16x16x64_i8 v[90:93], v[118:121], v[210:213], v[90:93]
	v_mfma_i32_16x16x64_i8 v[78:81], v[178:181], v[210:213], v[78:81]
	v_mfma_i32_16x16x64_i8 v[74:77], v[178:181], v[218:221], v[74:77]
	v_mfma_i32_16x16x64_i8 v[82:85], v[118:121], v[218:221], v[82:85]
	s_barrier
	s_add_i32 s8, s66, s81
	v_lshl_add_u64 v[168:169], s[96:97], 0, v[0:1]
	s_mov_b32 m0, s8
	ds_read_b128 v[182:185], v177 offset:16384
	ds_read_b128 v[186:189], v177 offset:17408
	ds_read_b128 v[190:193], v177 offset:18432
	ds_read_b128 v[194:197], v177 offset:19456
	ds_read_b128 v[198:201], v177 offset:20480
	ds_read_b128 v[210:213], v177 offset:21504
	ds_read_b128 v[214:217], v177 offset:22528
	ds_read_b128 v[218:221], v177 offset:23552
	global_load_lds_dwordx4 v[168:169], off
	s_add_i32 m0, s8, 0x2000
	s_add_u32 s8, s96, 0x40000
	v_lshl_add_u64 v[206:207], s[96:97], 0, v[158:159]
	s_addc_u32 s9, s97, 0
	s_add_i32 s66, s70, s81
	global_load_lds_dwordx4 v[206:207], off
	v_lshl_add_u64 v[222:223], s[8:9], 0, v[0:1]
	s_mov_b32 m0, s66
	v_lshl_add_u64 v[224:225], vcc, 0, v[160:161]
	global_load_lds_dwordx4 v[222:223], off
	v_lshl_add_u64 v[222:223], s[8:9], 0, v[158:159]
	s_add_i32 m0, s66, 0x2000
	s_nop 0
	global_load_lds_dwordx4 v[222:223], off
	v_lshl_add_u64 v[222:223], vcc, 0, v[162:163]
	s_mov_b32 m0, s1
	s_nop 0
	global_load_lds_dwordx4 v[222:223], off
	s_mov_b32 m0, s58
	s_nop 0
	global_load_lds_dwordx4 v[224:225], off
	s_waitcnt vmcnt(8) lgkmcnt(0)
	s_barrier
	v_mfma_i32_16x16x64_i8 v[62:65], v[66:69], v[182:185], 0
	v_mfma_i32_16x16x64_i8 v[54:57], v[106:109], v[182:185], 0
	v_mfma_i32_16x16x64_i8 v[46:49], v[106:109], v[190:193], 0
	v_mfma_i32_16x16x64_i8 v[58:61], v[66:69], v[190:193], 0
	v_mfma_i32_16x16x64_i8 v[50:53], v[66:69], v[198:201], 0
	v_mfma_i32_16x16x64_i8 v[38:41], v[106:109], v[198:201], 0
	v_mfma_i32_16x16x64_i8 v[34:37], v[106:109], v[214:217], 0
	v_mfma_i32_16x16x64_i8 v[42:45], v[66:69], v[214:217], 0
	v_mfma_i32_16x16x64_i8 v[62:65], v[70:73], v[186:189], v[62:65]
	v_mfma_i32_16x16x64_i8 v[54:57], v[110:113], v[186:189], v[54:57]
	v_mfma_i32_16x16x64_i8 v[46:49], v[110:113], v[194:197], v[46:49]
	v_mfma_i32_16x16x64_i8 v[58:61], v[70:73], v[194:197], v[58:61]
	v_mfma_i32_16x16x64_i8 v[50:53], v[70:73], v[210:213], v[50:53]
	v_mfma_i32_16x16x64_i8 v[38:41], v[110:113], v[210:213], v[38:41]
	v_mfma_i32_16x16x64_i8 v[34:37], v[110:113], v[218:221], v[34:37]
	v_mfma_i32_16x16x64_i8 v[42:45], v[70:73], v[218:221], v[42:45]
	v_mfma_i32_16x16x64_i8 v[30:33], v[114:117], v[182:185], 0
	v_mfma_i32_16x16x64_i8 v[22:25], v[126:129], v[182:185], 0
	v_mfma_i32_16x16x64_i8 v[14:17], v[126:129], v[190:193], 0
	v_mfma_i32_16x16x64_i8 v[26:29], v[114:117], v[190:193], 0
	v_mfma_i32_16x16x64_i8 v[18:21], v[114:117], v[198:201], 0
	v_mfma_i32_16x16x64_i8 v[6:9], v[126:129], v[198:201], 0
	v_mfma_i32_16x16x64_i8 v[2:5], v[126:129], v[214:217], 0
	v_mfma_i32_16x16x64_i8 v[10:13], v[114:117], v[214:217], 0
	v_mfma_i32_16x16x64_i8 v[30:33], v[118:121], v[186:189], v[30:33]
	v_mfma_i32_16x16x64_i8 v[22:25], v[178:181], v[186:189], v[22:25]
	v_mfma_i32_16x16x64_i8 v[14:17], v[178:181], v[194:197], v[14:17]
	v_mfma_i32_16x16x64_i8 v[26:29], v[118:121], v[194:197], v[26:29]
	v_mfma_i32_16x16x64_i8 v[18:21], v[118:121], v[210:213], v[18:21]
	v_mfma_i32_16x16x64_i8 v[6:9], v[178:181], v[210:213], v[6:9]
	v_mfma_i32_16x16x64_i8 v[2:5], v[178:181], v[218:221], v[2:5]
	v_mfma_i32_16x16x64_i8 v[10:13], v[118:121], v[218:221], v[10:13]
	s_barrier
; #define PG8_STAGE(bufoff, gbase, voff) do { _Pragma("unroll") for (int _i = 0; _i < 2; ++_i) \
;         __builtin_amdgcn_global_load_lds((const unsigned*)((const char*)(gbase) + (voff)[_i]), (PG8_LAS unsigned*)(lds + (bufoff) + ldsw + _i * 8192), 16, 0, 0); } while (0)
; #define PG8_LDA(dst, b, h) do { _Pragma("unroll") for (int m = 0; m < 4; ++m) _Pragma("unroll") for (int k = 0; k < 2; ++k) dst[m][k] = *(const PG8_LAS bf16x8*)(lds + PG8_SA(b, h) + aoff + m * 2048 + k * 1024); } while (0)
; #define PG8_LDB(dst, b, h) do { _Pragma("unroll") for (int n = 0; n < 2; ++n) _Pragma("unroll") for (int k = 0; k < 2; ++k) dst[n][k] = *(const PG8_LAS bf16x8*)(lds + PG8_SB(b, h) + boff + n * 2048 + k * 1024); } while (0)
; #define PG8_MMA(ai, bj, At, Bt) do { __builtin_amdgcn_s_setprio(1); _Pragma("unroll") for (int m = 0; m < 4; ++m) _Pragma("unroll") for (int n = 0; n < 2; ++n) _Pragma("unroll") for (int k = 0; k < 2; ++k) \
;         acc[ai][bj][m][n] = mma16<Epi::I8>(Bt[n][k], At[m][k], acc[ai][bj][m][n]); __builtin_amdgcn_s_setprio(0); } while (0)
; #define PG8_WAIT_V(n) asm volatile("s_waitcnt vmcnt(" #n ")" ::: "memory")
; #define PG8_WAIT_L(n) asm volatile("s_waitcnt lgkmcnt(" #n ")" ::: "memory")
; #define PG8_BAR __builtin_amdgcn_s_barrier()
; #define PG8_SCHED __builtin_amdgcn_sched_barrier(0)
; template <class Epi, class Sched, bool ALIGN_EPI = false, bool SP2 = false>
; __device__ __forceinline__ void gemm_phase(PG8_LAS unsigned char* lds, const Gemm g, const Sched& S, const Epi& E) {
;     ...
;             PG8_LDB(B0, 1, 0); PG8_LDB(B1, 1, 1); PG8_SCHED; PG8_LDA(At, 1, 0); PG8_STAGE(PG8_SA(0, 1), a2 + hstep, voffA);
;             PG8_WAIT_V(8); PG8_WAIT_L(0); PG8_BAR; PG8_MMA(0, 0, At, B0); PG8_MMA(0, 1, At, B1); PG8_BAR; PG8_SCHED;
;             PG8_LDA(At, 1, 1); PG8_STAGE(PG8_SB(1, 0), b3, voffB); PG8_STAGE(PG8_SB(1, 1), b3 + hstep, voffB); PG8_STAGE(PG8_SA(1, 0), a3, voffA);
;             PG8_WAIT_V(8); PG8_WAIT_L(0); PG8_BAR; PG8_MMA(1, 0, At, B0); PG8_MMA(1, 1, At, B1); PG8_BAR; PG8_SCHED;
	s_add_i32 s66, 0, 0x18000
	s_add_i32 s70, 0, 0x1c000
	v_add_u32_e32 v110, s66, v175
	v_add_u32_e32 v170, s70, v175
	ds_read_b128 v[66:69], v110
	ds_read_b128 v[70:73], v110 offset:1024
	ds_read_b128 v[106:109], v110 offset:2048
	ds_read_b128 v[110:113], v110 offset:3072
	ds_read_b128 v[114:117], v170
	ds_read_b128 v[118:121], v170 offset:1024
	ds_read_b128 v[126:129], v170 offset:2048
	ds_read_b128 v[178:181], v170 offset:3072
	s_add_u32 s8, vcc_lo, 0x40000
	s_addc_u32 s9, vcc_hi, 0
	s_mov_b32 m0, s80
	v_lshl_add_u64 v[226:227], s[8:9], 0, v[162:163]
	ds_read_b128 v[182:185], v177 offset:32768
	ds_read_b128 v[186:189], v177 offset:33792
	ds_read_b128 v[190:193], v177 offset:34816
	ds_read_b128 v[194:197], v177 offset:35840
	ds_read_b128 v[198:201], v177 offset:36864
	ds_read_b128 v[210:213], v177 offset:37888
	ds_read_b128 v[214:217], v177 offset:38912
	ds_read_b128 v[218:221], v177 offset:39936
	global_load_lds_dwordx4 v[226:227], off
	v_lshl_add_u64 v[226:227], s[8:9], 0, v[160:161]
	s_mov_b32 m0, s0
	s_nop 0
	global_load_lds_dwordx4 v[226:227], off
	s_waitcnt vmcnt(8) lgkmcnt(0)
	s_barrier
	v_mfma_i32_16x16x64_i8 v[154:157], v[66:69], v[182:185], v[154:157]
	v_mfma_i32_16x16x64_i8 v[146:149], v[106:109], v[182:185], v[146:149]
	v_mfma_i32_16x16x64_i8 v[138:141], v[106:109], v[190:193], v[138:141]
	v_mfma_i32_16x16x64_i8 v[150:153], v[66:69], v[190:193], v[150:153]
	v_mfma_i32_16x16x64_i8 v[142:145], v[66:69], v[198:201], v[142:145]
	v_mfma_i32_16x16x64_i8 v[130:133], v[106:109], v[198:201], v[130:133]
	v_mfma_i32_16x16x64_i8 v[122:125], v[106:109], v[214:217], v[122:125]
	v_mfma_i32_16x16x64_i8 v[134:137], v[66:69], v[214:217], v[134:137]
	v_mfma_i32_16x16x64_i8 v[154:157], v[70:73], v[186:189], v[154:157]
	v_mfma_i32_16x16x64_i8 v[146:149], v[110:113], v[186:189], v[146:149]
	v_mfma_i32_16x16x64_i8 v[138:141], v[110:113], v[194:197], v[138:141]
	v_mfma_i32_16x16x64_i8 v[150:153], v[70:73], v[194:197], v[150:153]
	v_mfma_i32_16x16x64_i8 v[142:145], v[70:73], v[210:213], v[142:145]
	v_mfma_i32_16x16x64_i8 v[130:133], v[110:113], v[210:213], v[130:133]
	v_mfma_i32_16x16x64_i8 v[122:125], v[110:113], v[218:221], v[122:125]
	v_mfma_i32_16x16x64_i8 v[134:137], v[70:73], v[218:221], v[134:137]
	v_mfma_i32_16x16x64_i8 v[102:105], v[114:117], v[182:185], v[102:105]
	v_mfma_i32_16x16x64_i8 v[94:97], v[126:129], v[182:185], v[94:97]
	v_mfma_i32_16x16x64_i8 v[86:89], v[126:129], v[190:193], v[86:89]
	v_mfma_i32_16x16x64_i8 v[98:101], v[114:117], v[190:193], v[98:101]
	v_mfma_i32_16x16x64_i8 v[90:93], v[114:117], v[198:201], v[90:93]
	v_mfma_i32_16x16x64_i8 v[78:81], v[126:129], v[198:201], v[78:81]
	v_mfma_i32_16x16x64_i8 v[74:77], v[126:129], v[214:217], v[74:77]
	v_mfma_i32_16x16x64_i8 v[82:85], v[114:117], v[214:217], v[82:85]
	v_mfma_i32_16x16x64_i8 v[102:105], v[118:121], v[186:189], v[102:105]
	v_mfma_i32_16x16x64_i8 v[94:97], v[178:181], v[186:189], v[94:97]
	v_mfma_i32_16x16x64_i8 v[86:89], v[178:181], v[194:197], v[86:89]
	v_mfma_i32_16x16x64_i8 v[98:101], v[118:121], v[194:197], v[98:101]
	v_mfma_i32_16x16x64_i8 v[90:93], v[118:121], v[210:213], v[90:93]
	v_mfma_i32_16x16x64_i8 v[78:81], v[178:181], v[210:213], v[78:81]
	v_mfma_i32_16x16x64_i8 v[74:77], v[178:181], v[218:221], v[74:77]
	v_mfma_i32_16x16x64_i8 v[82:85], v[118:121], v[218:221], v[82:85]
	s_barrier
	s_add_i32 s8, s66, s81
	v_lshl_add_u64 v[168:169], v[168:169], 0, s[92:93]
	s_mov_b32 m0, s8
	ds_read_b128 v[182:185], v177 offset:49152
	ds_read_b128 v[186:189], v177 offset:50176
	ds_read_b128 v[190:193], v177 offset:51200
	ds_read_b128 v[194:197], v177 offset:52224
	ds_read_b128 v[198:201], v177 offset:53248
	ds_read_b128 v[210:213], v177 offset:54272
	ds_read_b128 v[214:217], v177 offset:55296
	ds_read_b128 v[218:221], v177 offset:56320
	global_load_lds_dwordx4 v[168:169], off
	s_add_i32 m0, s8, 0x2000
	s_add_u32 s8, s96, 0x40080
	v_lshl_add_u64 v[168:169], v[206:207], 0, s[92:93]
	s_addc_u32 s9, s97, 0
	s_add_i32 s66, s70, s81
	global_load_lds_dwordx4 v[168:169], off
	v_lshl_add_u64 v[168:169], s[8:9], 0, v[0:1]
	s_mov_b32 m0, s66
	s_nop 0
	global_load_lds_dwordx4 v[168:169], off
	v_lshl_add_u64 v[168:169], s[8:9], 0, v[158:159]
	s_add_i32 m0, s66, 0x2000
	s_nop 0
	global_load_lds_dwordx4 v[168:169], off
	v_lshl_add_u64 v[168:169], v[222:223], 0, s[92:93]
	s_mov_b32 m0, s13
	s_nop 0
	global_load_lds_dwordx4 v[168:169], off
	v_lshl_add_u64 v[168:169], v[224:225], 0, s[92:93]
	s_mov_b32 m0, s12
	s_nop 0
	global_load_lds_dwordx4 v[168:169], off
	s_waitcnt vmcnt(8) lgkmcnt(0)
	s_barrier
	v_mfma_i32_16x16x64_i8 v[62:65], v[66:69], v[182:185], v[62:65]
	v_mfma_i32_16x16x64_i8 v[54:57], v[106:109], v[182:185], v[54:57]
	v_mfma_i32_16x16x64_i8 v[46:49], v[106:109], v[190:193], v[46:49]
	v_mfma_i32_16x16x64_i8 v[58:61], v[66:69], v[190:193], v[58:61]
	v_mfma_i32_16x16x64_i8 v[50:53], v[66:69], v[198:201], v[50:53]
	v_mfma_i32_16x16x64_i8 v[38:41], v[106:109], v[198:201], v[38:41]
	v_mfma_i32_16x16x64_i8 v[34:37], v[106:109], v[214:217], v[34:37]
	v_mfma_i32_16x16x64_i8 v[42:45], v[66:69], v[214:217], v[42:45]
	v_mfma_i32_16x16x64_i8 v[62:65], v[70:73], v[186:189], v[62:65]
	v_mfma_i32_16x16x64_i8 v[54:57], v[110:113], v[186:189], v[54:57]
	v_mfma_i32_16x16x64_i8 v[46:49], v[110:113], v[194:197], v[46:49]
	v_mfma_i32_16x16x64_i8 v[58:61], v[70:73], v[194:197], v[58:61]
	v_mfma_i32_16x16x64_i8 v[50:53], v[70:73], v[210:213], v[50:53]
	v_mfma_i32_16x16x64_i8 v[38:41], v[110:113], v[210:213], v[38:41]
	v_mfma_i32_16x16x64_i8 v[34:37], v[110:113], v[218:221], v[34:37]
	v_mfma_i32_16x16x64_i8 v[42:45], v[70:73], v[218:221], v[42:45]
	v_mfma_i32_16x16x64_i8 v[30:33], v[114:117], v[182:185], v[30:33]
	v_mfma_i32_16x16x64_i8 v[22:25], v[126:129], v[182:185], v[22:25]
	v_mfma_i32_16x16x64_i8 v[14:17], v[126:129], v[190:193], v[14:17]
	v_mfma_i32_16x16x64_i8 v[26:29], v[114:117], v[190:193], v[26:29]
	v_mfma_i32_16x16x64_i8 v[18:21], v[114:117], v[198:201], v[18:21]
	v_mfma_i32_16x16x64_i8 v[6:9], v[126:129], v[198:201], v[6:9]
	v_mfma_i32_16x16x64_i8 v[2:5], v[126:129], v[214:217], v[2:5]
	v_mfma_i32_16x16x64_i8 v[10:13], v[114:117], v[214:217], v[10:13]
	v_mfma_i32_16x16x64_i8 v[30:33], v[118:121], v[186:189], v[30:33]
	v_mfma_i32_16x16x64_i8 v[22:25], v[178:181], v[186:189], v[22:25]
	v_mfma_i32_16x16x64_i8 v[14:17], v[178:181], v[194:197], v[14:17]
	v_mfma_i32_16x16x64_i8 v[26:29], v[118:121], v[194:197], v[26:29]
	v_mfma_i32_16x16x64_i8 v[18:21], v[118:121], v[210:213], v[18:21]
	v_mfma_i32_16x16x64_i8 v[6:9], v[178:181], v[210:213], v[6:9]
	v_mfma_i32_16x16x64_i8 v[2:5], v[178:181], v[218:221], v[2:5]
	v_mfma_i32_16x16x64_i8 v[10:13], v[118:121], v[218:221], v[10:13]
	s_barrier
	s_add_i32 s10, s10, 2
	s_add_u32 s69, s69, 0x100
	s_addc_u32 s68, s68, 0
	s_cmp_gt_u32 s10, 13
	s_mov_b64 s[8:9], s[84:85]
	s_cbranch_scc0 .LBB0_291
	s_branch .Lpeelx291
; #define PG8_STAGE(bufoff, gbase, voff) do { _Pragma("unroll") for (int _i = 0; _i < 2; ++_i) \
;         __builtin_amdgcn_global_load_lds((const unsigned*)((const char*)(gbase) + (voff)[_i]), (PG8_LAS unsigned*)(lds + (bufoff) + ldsw + _i * 8192), 16, 0, 0); } while (0)
; #define PG8_LDA(dst, b, h) do { _Pragma("unroll") for (int m = 0; m < 4; ++m) _Pragma("unroll") for (int k = 0; k < 2; ++k) dst[m][k] = *(const PG8_LAS bf16x8*)(lds + PG8_SA(b, h) + aoff + m * 2048 + k * 1024); } while (0)
; #define PG8_LDB(dst, b, h) do { _Pragma("unroll") for (int n = 0; n < 2; ++n) _Pragma("unroll") for (int k = 0; k < 2; ++k) dst[n][k] = *(const PG8_LAS bf16x8*)(lds + PG8_SB(b, h) + boff + n * 2048 + k * 1024); } while (0)
; #define PG8_MMA(ai, bj, At, Bt) do { __builtin_amdgcn_s_setprio(1); _Pragma("unroll") for (int m = 0; m < 4; ++m) _Pragma("unroll") for (int n = 0; n < 2; ++n) _Pragma("unroll") for (int k = 0; k < 2; ++k) \
;         acc[ai][bj][m][n] = mma16<Epi::I8>(Bt[n][k], At[m][k], acc[ai][bj][m][n]); __builtin_amdgcn_s_setprio(0); } while (0)
; #define PG8_WAIT_V(n) asm volatile("s_waitcnt vmcnt(" #n ")" ::: "memory")
; #define PG8_WAIT_L(n) asm volatile("s_waitcnt lgkmcnt(" #n ")" ::: "memory")
; #define PG8_BAR __builtin_amdgcn_s_barrier()
; template <class Epi, class Sched, bool ALIGN_EPI = false, bool SP2 = false>
; __device__ __forceinline__ void gemm_phase(PG8_LAS unsigned char* lds, const Gemm g, const Sched& S, const Epi& E) {
;     ...
;             const bool last = (t == nt - 2);
;             const char* a1 = cA + (size_t)(t + 1) * kstep;
;             const char* a2 = last ? nA : cA + (size_t)(t + 2) * kstep; const char* b2 = last ? nB : cB + (size_t)(t + 2) * kstep;
;             const char* a3 = a2 + kstep; const char* b3 = b2 + kstep;
;             if (last && has_next) S.a_ready(nxt);
;             if constexpr (SP2) {
;             PG8_LDB(B0, 0, 0); PG8_LDB(B1, 0, 1); PG8_SCHED; PG8_LDA(At, 0, 0); PG8_STAGE(PG8_SA(1, 1), a1 + hstep, voffA);
;             PG8_WAIT_V(8); PG8_WAIT_L(0); PG8_BAR; PG8_MMA(0, 0, At, B0); PG8_MMA(0, 1, At, B1); PG8_BAR; PG8_SCHED;
;             PG8_LDA(At, 0, 1); PG8_STAGE(PG8_SB(0, 0), b2, voffB); PG8_STAGE(PG8_SB(0, 1), b2 + hstep, voffB); PG8_STAGE(PG8_SA(0, 0), a2, voffA);
;             PG8_WAIT_V(8); PG8_WAIT_L(0); PG8_BAR; PG8_MMA(1, 0, At, B0); PG8_MMA(1, 1, At, B1); PG8_BAR; PG8_SCHED;
.LBB0_291:
	s_add_u32 s84, s8, 0x100
	s_addc_u32 s85, s9, 0
	s_add_i32 s66, 0, 0x10000
	s_cmp_eq_u32 s10, 12
	s_cselect_b32 vcc_hi, s5, s85
	s_cselect_b32 vcc_lo, s7, s84
	s_cselect_b32 s97, s11, s68
	s_cselect_b32 s96, s67, s69
	s_add_i32 s70, 0, 0x14000
	v_add_u32_e32 v110, s66, v175
	v_add_u32_e32 v168, s70, v175
	s_waitcnt vmcnt(0)
	ds_read_b128 v[66:69], v110
	ds_read_b128 v[70:73], v110 offset:1024
	ds_read_b128 v[106:109], v110 offset:2048
	ds_read_b128 v[110:113], v110 offset:3072
	ds_read_b128 v[114:117], v168
	ds_read_b128 v[118:121], v168 offset:1024
	ds_read_b128 v[126:129], v168 offset:2048
	ds_read_b128 v[178:181], v168 offset:3072
	v_lshl_add_u64 v[168:169], s[8:9], 0, v[164:165]
	s_add_i32 m0, s1, 0xc000
	ds_read_b128 v[182:185], v177
	ds_read_b128 v[186:189], v177 offset:1024
	ds_read_b128 v[190:193], v177 offset:2048
	ds_read_b128 v[194:197], v177 offset:3072
	ds_read_b128 v[198:201], v177 offset:4096
	ds_read_b128 v[210:213], v177 offset:5120
	ds_read_b128 v[214:217], v177 offset:6144
	ds_read_b128 v[218:221], v177 offset:7168
	global_load_lds_dwordx4 v[168:169], off
	v_lshl_add_u64 v[168:169], s[8:9], 0, v[166:167]
	s_add_i32 m0, s1, 0xe000
	s_nop 0
	global_load_lds_dwordx4 v[168:169], off
	s_waitcnt vmcnt(8) lgkmcnt(0)
	s_barrier
	v_mfma_i32_16x16x64_i8 v[154:157], v[66:69], v[182:185], v[154:157]
	v_mfma_i32_16x16x64_i8 v[146:149], v[106:109], v[182:185], v[146:149]
	v_mfma_i32_16x16x64_i8 v[138:141], v[106:109], v[190:193], v[138:141]
	v_mfma_i32_16x16x64_i8 v[150:153], v[66:69], v[190:193], v[150:153]
	v_mfma_i32_16x16x64_i8 v[142:145], v[66:69], v[198:201], v[142:145]
	v_mfma_i32_16x16x64_i8 v[130:133], v[106:109], v[198:201], v[130:133]
	v_mfma_i32_16x16x64_i8 v[122:125], v[106:109], v[214:217], v[122:125]
	v_mfma_i32_16x16x64_i8 v[134:137], v[66:69], v[214:217], v[134:137]
	v_mfma_i32_16x16x64_i8 v[154:157], v[70:73], v[186:189], v[154:157]
	v_mfma_i32_16x16x64_i8 v[146:149], v[110:113], v[186:189], v[146:149]
	v_mfma_i32_16x16x64_i8 v[138:141], v[110:113], v[194:197], v[138:141]
	v_mfma_i32_16x16x64_i8 v[150:153], v[70:73], v[194:197], v[150:153]
	v_mfma_i32_16x16x64_i8 v[142:145], v[70:73], v[210:213], v[142:145]
	v_mfma_i32_16x16x64_i8 v[130:133], v[110:113], v[210:213], v[130:133]
	v_mfma_i32_16x16x64_i8 v[122:125], v[110:113], v[218:221], v[122:125]
	v_mfma_i32_16x16x64_i8 v[134:137], v[70:73], v[218:221], v[134:137]
	v_mfma_i32_16x16x64_i8 v[102:105], v[114:117], v[182:185], v[102:105]
	v_mfma_i32_16x16x64_i8 v[94:97], v[126:129], v[182:185], v[94:97]
	v_mfma_i32_16x16x64_i8 v[86:89], v[126:129], v[190:193], v[86:89]
	v_mfma_i32_16x16x64_i8 v[98:101], v[114:117], v[190:193], v[98:101]
	v_mfma_i32_16x16x64_i8 v[90:93], v[114:117], v[198:201], v[90:93]
	v_mfma_i32_16x16x64_i8 v[78:81], v[126:129], v[198:201], v[78:81]
	v_mfma_i32_16x16x64_i8 v[74:77], v[126:129], v[214:217], v[74:77]
	v_mfma_i32_16x16x64_i8 v[82:85], v[114:117], v[214:217], v[82:85]
	v_mfma_i32_16x16x64_i8 v[102:105], v[118:121], v[186:189], v[102:105]
	v_mfma_i32_16x16x64_i8 v[94:97], v[178:181], v[186:189], v[94:97]
	v_mfma_i32_16x16x64_i8 v[86:89], v[178:181], v[194:197], v[86:89]
	v_mfma_i32_16x16x64_i8 v[98:101], v[118:121], v[194:197], v[98:101]
	v_mfma_i32_16x16x64_i8 v[90:93], v[118:121], v[210:213], v[90:93]
	v_mfma_i32_16x16x64_i8 v[78:81], v[178:181], v[210:213], v[78:81]
	v_mfma_i32_16x16x64_i8 v[74:77], v[178:181], v[218:221], v[74:77]
	v_mfma_i32_16x16x64_i8 v[82:85], v[118:121], v[218:221], v[82:85]
	s_barrier
	s_add_i32 s8, s66, s81
	v_lshl_add_u64 v[168:169], s[96:97], 0, v[0:1]
	s_mov_b32 m0, s8
	ds_read_b128 v[182:185], v177 offset:16384
	ds_read_b128 v[186:189], v177 offset:17408
	ds_read_b128 v[190:193], v177 offset:18432
	ds_read_b128 v[194:197], v177 offset:19456
	ds_read_b128 v[198:201], v177 offset:20480
	ds_read_b128 v[210:213], v177 offset:21504
	ds_read_b128 v[214:217], v177 offset:22528
	ds_read_b128 v[218:221], v177 offset:23552
	global_load_lds_dwordx4 v[168:169], off
	s_add_i32 m0, s8, 0x2000
	s_add_u32 s8, s96, 0x40000
	v_lshl_add_u64 v[206:207], s[96:97], 0, v[158:159]
	s_addc_u32 s9, s97, 0
	s_add_i32 s66, s70, s81
	global_load_lds_dwordx4 v[206:207], off
	v_lshl_add_u64 v[222:223], s[8:9], 0, v[0:1]
	s_mov_b32 m0, s66
	v_lshl_add_u64 v[224:225], vcc, 0, v[160:161]
	global_load_lds_dwordx4 v[222:223], off
	v_lshl_add_u64 v[222:223], s[8:9], 0, v[158:159]
	s_add_i32 m0, s66, 0x2000
	s_nop 0
	global_load_lds_dwordx4 v[222:223], off
	v_lshl_add_u64 v[222:223], vcc, 0, v[162:163]
	s_mov_b32 m0, s1
	s_nop 0
	global_load_lds_dwordx4 v[222:223], off
	s_mov_b32 m0, s58
	s_nop 0
	global_load_lds_dwordx4 v[224:225], off
	s_waitcnt vmcnt(8) lgkmcnt(0)
	s_barrier
; #define PG8_STAGE(bufoff, gbase, voff) do { _Pragma("unroll") for (int _i = 0; _i < 2; ++_i) \
;         __builtin_amdgcn_global_load_lds((const unsigned*)((const char*)(gbase) + (voff)[_i]), (PG8_LAS unsigned*)(lds + (bufoff) + ldsw + _i * 8192), 16, 0, 0); } while (0)
; #define PG8_LDA(dst, b, h) do { _Pragma("unroll") for (int m = 0; m < 4; ++m) _Pragma("unroll") for (int k = 0; k < 2; ++k) dst[m][k] = *(const PG8_LAS bf16x8*)(lds + PG8_SA(b, h) + aoff + m * 2048 + k * 1024); } while (0)
; #define PG8_LDB(dst, b, h) do { _Pragma("unroll") for (int n = 0; n < 2; ++n) _Pragma("unroll") for (int k = 0; k < 2; ++k) dst[n][k] = *(const PG8_LAS bf16x8*)(lds + PG8_SB(b, h) + boff + n * 2048 + k * 1024); } while (0)
; #define PG8_MMA(ai, bj, At, Bt) do { __builtin_amdgcn_s_setprio(1); _Pragma("unroll") for (int m = 0; m < 4; ++m) _Pragma("unroll") for (int n = 0; n < 2; ++n) _Pragma("unroll") for (int k = 0; k < 2; ++k) \
;         acc[ai][bj][m][n] = mma16<Epi::I8>(Bt[n][k], At[m][k], acc[ai][bj][m][n]); __builtin_amdgcn_s_setprio(0); } while (0)
; #define PG8_WAIT_V(n) asm volatile("s_waitcnt vmcnt(" #n ")" ::: "memory")
; #define PG8_WAIT_L(n) asm volatile("s_waitcnt lgkmcnt(" #n ")" ::: "memory")
; #define PG8_BAR __builtin_amdgcn_s_barrier()
; #define PG8_SCHED __builtin_amdgcn_sched_barrier(0)
; template <class Epi, class Sched, bool ALIGN_EPI = false, bool SP2 = false>
; __device__ __forceinline__ void gemm_phase(PG8_LAS unsigned char* lds, const Gemm g, const Sched& S, const Epi& E) {
;     ...
;             PG8_WAIT_V(8); PG8_WAIT_L(0); PG8_BAR; PG8_MMA(1, 0, At, B0); PG8_MMA(1, 1, At, B1); PG8_BAR; PG8_SCHED;
;             PG8_LDB(B0, 1, 0); PG8_LDB(B1, 1, 1); PG8_SCHED; PG8_LDA(At, 1, 0); PG8_STAGE(PG8_SA(0, 1), a2 + hstep, voffA);
;             PG8_WAIT_V(8); PG8_WAIT_L(0); PG8_BAR; PG8_MMA(0, 0, At, B0); PG8_MMA(0, 1, At, B1); PG8_BAR; PG8_SCHED;
	v_mfma_i32_16x16x64_i8 v[62:65], v[66:69], v[182:185], v[62:65]
	v_mfma_i32_16x16x64_i8 v[54:57], v[106:109], v[182:185], v[54:57]
	v_mfma_i32_16x16x64_i8 v[46:49], v[106:109], v[190:193], v[46:49]
	v_mfma_i32_16x16x64_i8 v[58:61], v[66:69], v[190:193], v[58:61]
	v_mfma_i32_16x16x64_i8 v[50:53], v[66:69], v[198:201], v[50:53]
	v_mfma_i32_16x16x64_i8 v[38:41], v[106:109], v[198:201], v[38:41]
	v_mfma_i32_16x16x64_i8 v[34:37], v[106:109], v[214:217], v[34:37]
	v_mfma_i32_16x16x64_i8 v[42:45], v[66:69], v[214:217], v[42:45]
	v_mfma_i32_16x16x64_i8 v[62:65], v[70:73], v[186:189], v[62:65]
	v_mfma_i32_16x16x64_i8 v[54:57], v[110:113], v[186:189], v[54:57]
	v_mfma_i32_16x16x64_i8 v[46:49], v[110:113], v[194:197], v[46:49]
	v_mfma_i32_16x16x64_i8 v[58:61], v[70:73], v[194:197], v[58:61]
	v_mfma_i32_16x16x64_i8 v[50:53], v[70:73], v[210:213], v[50:53]
	v_mfma_i32_16x16x64_i8 v[38:41], v[110:113], v[210:213], v[38:41]
	v_mfma_i32_16x16x64_i8 v[34:37], v[110:113], v[218:221], v[34:37]
	v_mfma_i32_16x16x64_i8 v[42:45], v[70:73], v[218:221], v[42:45]
	v_mfma_i32_16x16x64_i8 v[30:33], v[114:117], v[182:185], v[30:33]
	v_mfma_i32_16x16x64_i8 v[22:25], v[126:129], v[182:185], v[22:25]
	v_mfma_i32_16x16x64_i8 v[14:17], v[126:129], v[190:193], v[14:17]
	v_mfma_i32_16x16x64_i8 v[26:29], v[114:117], v[190:193], v[26:29]
	v_mfma_i32_16x16x64_i8 v[18:21], v[114:117], v[198:201], v[18:21]
	v_mfma_i32_16x16x64_i8 v[6:9], v[126:129], v[198:201], v[6:9]
	v_mfma_i32_16x16x64_i8 v[2:5], v[126:129], v[214:217], v[2:5]
	v_mfma_i32_16x16x64_i8 v[10:13], v[114:117], v[214:217], v[10:13]
	v_mfma_i32_16x16x64_i8 v[30:33], v[118:121], v[186:189], v[30:33]
	v_mfma_i32_16x16x64_i8 v[22:25], v[178:181], v[186:189], v[22:25]
	v_mfma_i32_16x16x64_i8 v[14:17], v[178:181], v[194:197], v[14:17]
	v_mfma_i32_16x16x64_i8 v[26:29], v[118:121], v[194:197], v[26:29]
	v_mfma_i32_16x16x64_i8 v[18:21], v[118:121], v[210:213], v[18:21]
	v_mfma_i32_16x16x64_i8 v[6:9], v[178:181], v[210:213], v[6:9]
	v_mfma_i32_16x16x64_i8 v[2:5], v[178:181], v[218:221], v[2:5]
	v_mfma_i32_16x16x64_i8 v[10:13], v[118:121], v[218:221], v[10:13]
	s_barrier
	s_add_i32 s66, 0, 0x18000
	s_add_i32 s70, 0, 0x1c000
	v_add_u32_e32 v110, s66, v175
	v_add_u32_e32 v170, s70, v175
	ds_read_b128 v[66:69], v110
	ds_read_b128 v[70:73], v110 offset:1024
	ds_read_b128 v[106:109], v110 offset:2048
	ds_read_b128 v[110:113], v110 offset:3072
	ds_read_b128 v[114:117], v170
	ds_read_b128 v[118:121], v170 offset:1024
	ds_read_b128 v[126:129], v170 offset:2048
	ds_read_b128 v[178:181], v170 offset:3072
	s_add_u32 s8, vcc_lo, 0x40000
	s_addc_u32 s9, vcc_hi, 0
	s_mov_b32 m0, s80
	v_lshl_add_u64 v[226:227], s[8:9], 0, v[162:163]
	ds_read_b128 v[182:185], v177 offset:32768
	ds_read_b128 v[186:189], v177 offset:33792
	ds_read_b128 v[190:193], v177 offset:34816
	ds_read_b128 v[194:197], v177 offset:35840
	ds_read_b128 v[198:201], v177 offset:36864
	ds_read_b128 v[210:213], v177 offset:37888
	ds_read_b128 v[214:217], v177 offset:38912
	ds_read_b128 v[218:221], v177 offset:39936
	global_load_lds_dwordx4 v[226:227], off
	v_lshl_add_u64 v[226:227], s[8:9], 0, v[160:161]
	s_mov_b32 m0, s0
	s_nop 0
	global_load_lds_dwordx4 v[226:227], off
	s_waitcnt vmcnt(8) lgkmcnt(0)
	s_barrier
	v_mfma_i32_16x16x64_i8 v[154:157], v[66:69], v[182:185], v[154:157]
	v_mfma_i32_16x16x64_i8 v[146:149], v[106:109], v[182:185], v[146:149]
	v_mfma_i32_16x16x64_i8 v[138:141], v[106:109], v[190:193], v[138:141]
	v_mfma_i32_16x16x64_i8 v[150:153], v[66:69], v[190:193], v[150:153]
	v_mfma_i32_16x16x64_i8 v[142:145], v[66:69], v[198:201], v[142:145]
	v_mfma_i32_16x16x64_i8 v[130:133], v[106:109], v[198:201], v[130:133]
	v_mfma_i32_16x16x64_i8 v[122:125], v[106:109], v[214:217], v[122:125]
	v_mfma_i32_16x16x64_i8 v[134:137], v[66:69], v[214:217], v[134:137]
	v_mfma_i32_16x16x64_i8 v[154:157], v[70:73], v[186:189], v[154:157]
	v_mfma_i32_16x16x64_i8 v[146:149], v[110:113], v[186:189], v[146:149]
	v_mfma_i32_16x16x64_i8 v[138:141], v[110:113], v[194:197], v[138:141]
	v_mfma_i32_16x16x64_i8 v[150:153], v[70:73], v[194:197], v[150:153]
	v_mfma_i32_16x16x64_i8 v[142:145], v[70:73], v[210:213], v[142:145]
	v_mfma_i32_16x16x64_i8 v[130:133], v[110:113], v[210:213], v[130:133]
	v_mfma_i32_16x16x64_i8 v[122:125], v[110:113], v[218:221], v[122:125]
	v_mfma_i32_16x16x64_i8 v[134:137], v[70:73], v[218:221], v[134:137]
	v_mfma_i32_16x16x64_i8 v[102:105], v[114:117], v[182:185], v[102:105]
	v_mfma_i32_16x16x64_i8 v[94:97], v[126:129], v[182:185], v[94:97]
	v_mfma_i32_16x16x64_i8 v[86:89], v[126:129], v[190:193], v[86:89]
	v_mfma_i32_16x16x64_i8 v[98:101], v[114:117], v[190:193], v[98:101]
	v_mfma_i32_16x16x64_i8 v[90:93], v[114:117], v[198:201], v[90:93]
	v_mfma_i32_16x16x64_i8 v[78:81], v[126:129], v[198:201], v[78:81]
	v_mfma_i32_16x16x64_i8 v[74:77], v[126:129], v[214:217], v[74:77]
	v_mfma_i32_16x16x64_i8 v[82:85], v[114:117], v[214:217], v[82:85]
	v_mfma_i32_16x16x64_i8 v[102:105], v[118:121], v[186:189], v[102:105]
	v_mfma_i32_16x16x64_i8 v[94:97], v[178:181], v[186:189], v[94:97]
	v_mfma_i32_16x16x64_i8 v[86:89], v[178:181], v[194:197], v[86:89]
	v_mfma_i32_16x16x64_i8 v[98:101], v[118:121], v[194:197], v[98:101]
	v_mfma_i32_16x16x64_i8 v[90:93], v[118:121], v[210:213], v[90:93]
	v_mfma_i32_16x16x64_i8 v[78:81], v[178:181], v[210:213], v[78:81]
	v_mfma_i32_16x16x64_i8 v[74:77], v[178:181], v[218:221], v[74:77]
	v_mfma_i32_16x16x64_i8 v[82:85], v[118:121], v[218:221], v[82:85]
	s_barrier
; #define PG8_STAGE(bufoff, gbase, voff) do { _Pragma("unroll") for (int _i = 0; _i < 2; ++_i) \
;         __builtin_amdgcn_global_load_lds((const unsigned*)((const char*)(gbase) + (voff)[_i]), (PG8_LAS unsigned*)(lds + (bufoff) + ldsw + _i * 8192), 16, 0, 0); } while (0)
; #define PG8_LDA(dst, b, h) do { _Pragma("unroll") for (int m = 0; m < 4; ++m) _Pragma("unroll") for (int k = 0; k < 2; ++k) dst[m][k] = *(const PG8_LAS bf16x8*)(lds + PG8_SA(b, h) + aoff + m * 2048 + k * 1024); } while (0)
; #define PG8_MMA(ai, bj, At, Bt) do { __builtin_amdgcn_s_setprio(1); _Pragma("unroll") for (int m = 0; m < 4; ++m) _Pragma("unroll") for (int n = 0; n < 2; ++n) _Pragma("unroll") for (int k = 0; k < 2; ++k) \
;         acc[ai][bj][m][n] = mma16<Epi::I8>(Bt[n][k], At[m][k], acc[ai][bj][m][n]); __builtin_amdgcn_s_setprio(0); } while (0)
; #define PG8_WAIT_V(n) asm volatile("s_waitcnt vmcnt(" #n ")" ::: "memory")
; #define PG8_WAIT_L(n) asm volatile("s_waitcnt lgkmcnt(" #n ")" ::: "memory")
; #define PG8_BAR __builtin_amdgcn_s_barrier()
; #define PG8_SCHED __builtin_amdgcn_sched_barrier(0)
; template <class Epi, class Sched, bool ALIGN_EPI = false, bool SP2 = false>
; __device__ __forceinline__ void gemm_phase(PG8_LAS unsigned char* lds, const Gemm g, const Sched& S, const Epi& E) {
;     ...
;             PG8_LDA(At, 1, 1); PG8_STAGE(PG8_SB(1, 0), b3, voffB); PG8_STAGE(PG8_SB(1, 1), b3 + hstep, voffB); PG8_STAGE(PG8_SA(1, 0), a3, voffA);
;             PG8_WAIT_V(8); PG8_WAIT_L(0); PG8_BAR; PG8_MMA(1, 0, At, B0); PG8_MMA(1, 1, At, B1); PG8_BAR; PG8_SCHED;
	s_add_i32 s8, s66, s81
	v_lshl_add_u64 v[168:169], v[168:169], 0, s[92:93]
	s_mov_b32 m0, s8
	ds_read_b128 v[182:185], v177 offset:49152
	ds_read_b128 v[186:189], v177 offset:50176
	ds_read_b128 v[190:193], v177 offset:51200
	ds_read_b128 v[194:197], v177 offset:52224
	ds_read_b128 v[198:201], v177 offset:53248
	ds_read_b128 v[210:213], v177 offset:54272
	ds_read_b128 v[214:217], v177 offset:55296
	ds_read_b128 v[218:221], v177 offset:56320
	global_load_lds_dwordx4 v[168:169], off
	s_add_i32 m0, s8, 0x2000
	s_add_u32 s8, s96, 0x40080
	v_lshl_add_u64 v[168:169], v[206:207], 0, s[92:93]
	s_addc_u32 s9, s97, 0
	s_add_i32 s66, s70, s81
	global_load_lds_dwordx4 v[168:169], off
	v_lshl_add_u64 v[168:169], s[8:9], 0, v[0:1]
	s_mov_b32 m0, s66
	s_nop 0
	global_load_lds_dwordx4 v[168:169], off
	v_lshl_add_u64 v[168:169], s[8:9], 0, v[158:159]
	s_add_i32 m0, s66, 0x2000
	s_nop 0
	global_load_lds_dwordx4 v[168:169], off
	v_lshl_add_u64 v[168:169], v[222:223], 0, s[92:93]
	s_mov_b32 m0, s13
	s_nop 0
	global_load_lds_dwordx4 v[168:169], off
	v_lshl_add_u64 v[168:169], v[224:225], 0, s[92:93]
	s_mov_b32 m0, s12
	s_nop 0
	global_load_lds_dwordx4 v[168:169], off
	s_waitcnt vmcnt(8) lgkmcnt(0)
	s_barrier
	v_mfma_i32_16x16x64_i8 v[62:65], v[66:69], v[182:185], v[62:65]
	v_mfma_i32_16x16x64_i8 v[54:57], v[106:109], v[182:185], v[54:57]
	v_mfma_i32_16x16x64_i8 v[46:49], v[106:109], v[190:193], v[46:49]
	v_mfma_i32_16x16x64_i8 v[58:61], v[66:69], v[190:193], v[58:61]
	v_mfma_i32_16x16x64_i8 v[50:53], v[66:69], v[198:201], v[50:53]
	v_mfma_i32_16x16x64_i8 v[38:41], v[106:109], v[198:201], v[38:41]
	v_mfma_i32_16x16x64_i8 v[34:37], v[106:109], v[214:217], v[34:37]
	v_mfma_i32_16x16x64_i8 v[42:45], v[66:69], v[214:217], v[42:45]
	v_mfma_i32_16x16x64_i8 v[62:65], v[70:73], v[186:189], v[62:65]
	v_mfma_i32_16x16x64_i8 v[54:57], v[110:113], v[186:189], v[54:57]
	v_mfma_i32_16x16x64_i8 v[46:49], v[110:113], v[194:197], v[46:49]
	v_mfma_i32_16x16x64_i8 v[58:61], v[70:73], v[194:197], v[58:61]
	v_mfma_i32_16x16x64_i8 v[50:53], v[70:73], v[210:213], v[50:53]
	v_mfma_i32_16x16x64_i8 v[38:41], v[110:113], v[210:213], v[38:41]
	v_mfma_i32_16x16x64_i8 v[34:37], v[110:113], v[218:221], v[34:37]
	v_mfma_i32_16x16x64_i8 v[42:45], v[70:73], v[218:221], v[42:45]
	v_mfma_i32_16x16x64_i8 v[30:33], v[114:117], v[182:185], v[30:33]
	v_mfma_i32_16x16x64_i8 v[22:25], v[126:129], v[182:185], v[22:25]
	v_mfma_i32_16x16x64_i8 v[14:17], v[126:129], v[190:193], v[14:17]
	v_mfma_i32_16x16x64_i8 v[26:29], v[114:117], v[190:193], v[26:29]
	v_mfma_i32_16x16x64_i8 v[18:21], v[114:117], v[198:201], v[18:21]
	v_mfma_i32_16x16x64_i8 v[6:9], v[126:129], v[198:201], v[6:9]
	v_mfma_i32_16x16x64_i8 v[2:5], v[126:129], v[214:217], v[2:5]
	v_mfma_i32_16x16x64_i8 v[10:13], v[114:117], v[214:217], v[10:13]
	v_mfma_i32_16x16x64_i8 v[30:33], v[118:121], v[186:189], v[30:33]
	v_mfma_i32_16x16x64_i8 v[22:25], v[178:181], v[186:189], v[22:25]
	v_mfma_i32_16x16x64_i8 v[14:17], v[178:181], v[194:197], v[14:17]
	v_mfma_i32_16x16x64_i8 v[26:29], v[118:121], v[194:197], v[26:29]
	v_mfma_i32_16x16x64_i8 v[18:21], v[118:121], v[210:213], v[18:21]
	v_mfma_i32_16x16x64_i8 v[6:9], v[178:181], v[210:213], v[6:9]
	v_mfma_i32_16x16x64_i8 v[2:5], v[178:181], v[218:221], v[2:5]
	v_mfma_i32_16x16x64_i8 v[10:13], v[118:121], v[218:221], v[10:13]
	s_barrier
	s_add_i32 s10, s10, 2
	s_add_u32 s69, s69, 0x100
	s_addc_u32 s68, s68, 0
	s_cmp_gt_u32 s10, 13
	s_mov_b64 s[8:9], s[84:85]
	s_cbranch_scc0 .LBB0_291

; #define PG8_STAGE(bufoff, gbase, voff) do { _Pragma("unroll") for (int _i = 0; _i < 2; ++_i) \
;         __builtin_amdgcn_global_load_lds((const unsigned*)((const char*)(gbase) + (voff)[_i]), (PG8_LAS unsigned*)(lds + (bufoff) + ldsw + _i * 8192), 16, 0, 0); } while (0)
; #define PG8_LDA(dst, b, h) do { _Pragma("unroll") for (int m = 0; m < 4; ++m) _Pragma("unroll") for (int k = 0; k < 2; ++k) dst[m][k] = *(const PG8_LAS bf16x8*)(lds + PG8_SA(b, h) + aoff + m * 2048 + k * 1024); } while (0)
; #define PG8_LDB(dst, b, h) do { _Pragma("unroll") for (int n = 0; n < 2; ++n) _Pragma("unroll") for (int k = 0; k < 2; ++k) dst[n][k] = *(const PG8_LAS bf16x8*)(lds + PG8_SB(b, h) + boff + n * 2048 + k * 1024); } while (0)
; #define PG8_MMA(ai, bj, At, Bt) do { __builtin_amdgcn_s_setprio(1); _Pragma("unroll") for (int m = 0; m < 4; ++m) _Pragma("unroll") for (int n = 0; n < 2; ++n) _Pragma("unroll") for (int k = 0; k < 2; ++k) \
;         acc[ai][bj][m][n] = mma16<Epi::I8>(Bt[n][k], At[m][k], acc[ai][bj][m][n]); __builtin_amdgcn_s_setprio(0); } while (0)
; #define PG8_WAIT_V(n) asm volatile("s_waitcnt vmcnt(" #n ")" ::: "memory")
; #define PG8_WAIT_L(n) asm volatile("s_waitcnt lgkmcnt(" #n ")" ::: "memory")
; #define PG8_BAR __builtin_amdgcn_s_barrier()
; template <class Epi, class Sched, bool ALIGN_EPI = false, bool SP2 = false>
; __device__ __forceinline__ void gemm_phase(PG8_LAS unsigned char* lds, const Gemm g, const Sched& S, const Epi& E) {
;     ...
;             const bool last = (t == nt - 2);
;             const char* a1 = cA + (size_t)(t + 1) * kstep;
;             const char* a2 = last ? nA : cA + (size_t)(t + 2) * kstep; const char* b2 = last ? nB : cB + (size_t)(t + 2) * kstep;
;             const char* a3 = a2 + kstep; const char* b3 = b2 + kstep;
;             if (last && has_next) S.a_ready(nxt);
;             if constexpr (SP2) {
;             PG8_LDB(B0, 0, 0); PG8_LDB(B1, 0, 1); PG8_SCHED; PG8_LDA(At, 0, 0); PG8_STAGE(PG8_SA(1, 1), a1 + hstep, voffA);
;             PG8_WAIT_V(8); PG8_WAIT_L(0); PG8_BAR; PG8_MMA(0, 0, At, B0); PG8_MMA(0, 1, At, B1); PG8_BAR; PG8_SCHED;
;             PG8_LDA(At, 0, 1); PG8_STAGE(PG8_SB(0, 0), b2, voffB); PG8_STAGE(PG8_SB(0, 1), b2 + hstep, voffB); PG8_STAGE(PG8_SA(0, 0), a2, voffA);
;             PG8_WAIT_V(8); PG8_WAIT_L(0); PG8_BAR; PG8_MMA(1, 0, At, B0); PG8_MMA(1, 1, At, B1); PG8_BAR; PG8_SCHED;
.Lpeel327:
	s_add_u32 s68, s8, 0x100
	s_addc_u32 s69, s9, 0
	s_add_i32 s84, 0, 0x10000
	s_cmp_eq_u32 s4, 28
	s_cselect_b32 vcc_hi, s1, s69
	s_cselect_b32 vcc_lo, s5, s68
	v_add_u32_e32 v0, s84, v188
	s_cselect_b32 s71, s7, s96
	s_cselect_b32 s70, s85, s97
	s_add_i32 s10, 0, 0x14000
	ds_read_b128 v[52:55], v0
	ds_read_b128 v[56:59], v0 offset:1024
	ds_read_b128 v[76:79], v0 offset:2048
	ds_read_b128 v[80:83], v0 offset:3072
	v_add_u32_e32 v0, s10, v188
	ds_read_b128 v[116:119], v0
	ds_read_b128 v[120:123], v0 offset:1024
	ds_read_b128 v[168:171], v0 offset:2048
	ds_read_b128 v[172:175], v0 offset:3072
	v_lshl_add_u64 v[2:3], s[8:9], 0, v[164:165]
	s_add_i32 m0, s58, 0xc000
	ds_read_b128 v[176:179], v189
	ds_read_b128 v[180:183], v189 offset:1024
	ds_read_b128 v[190:193], v189 offset:2048
	ds_read_b128 v[194:197], v189 offset:3072
	ds_read_b128 v[198:201], v189 offset:4096
	ds_read_b128 v[210:213], v189 offset:5120
	ds_read_b128 v[214:217], v189 offset:6144
	ds_read_b128 v[218:221], v189 offset:7168
	global_load_lds_dwordx4 v[2:3], off
	v_lshl_add_u64 v[2:3], s[8:9], 0, v[166:167]
	s_add_i32 m0, s58, 0xe000
	s_nop 0
	global_load_lds_dwordx4 v[2:3], off
	s_waitcnt vmcnt(8) lgkmcnt(0)
	s_barrier
	v_mfma_f32_16x16x32_bf16 v[152:155], v[52:55], v[176:179], 0
	v_mfma_f32_16x16x32_bf16 v[144:147], v[76:79], v[176:179], 0
	v_mfma_f32_16x16x32_bf16 v[140:143], v[76:79], v[190:193], 0
	v_mfma_f32_16x16x32_bf16 v[148:151], v[52:55], v[190:193], 0
	v_mfma_f32_16x16x32_bf16 v[136:139], v[52:55], v[198:201], 0
	v_mfma_f32_16x16x32_bf16 v[132:135], v[76:79], v[198:201], 0
	v_mfma_f32_16x16x32_bf16 v[124:127], v[76:79], v[214:217], 0
	v_mfma_f32_16x16x32_bf16 v[128:131], v[52:55], v[214:217], 0
	v_mfma_f32_16x16x32_bf16 v[152:155], v[56:59], v[180:183], v[152:155]
	v_mfma_f32_16x16x32_bf16 v[144:147], v[80:83], v[180:183], v[144:147]
	v_mfma_f32_16x16x32_bf16 v[140:143], v[80:83], v[194:197], v[140:143]
	v_mfma_f32_16x16x32_bf16 v[148:151], v[56:59], v[194:197], v[148:151]
	v_mfma_f32_16x16x32_bf16 v[136:139], v[56:59], v[210:213], v[136:139]
	v_mfma_f32_16x16x32_bf16 v[132:135], v[80:83], v[210:213], v[132:135]
	v_mfma_f32_16x16x32_bf16 v[124:127], v[80:83], v[218:221], v[124:127]
	v_mfma_f32_16x16x32_bf16 v[128:131], v[56:59], v[218:221], v[128:131]
	v_mfma_f32_16x16x32_bf16 v[112:115], v[116:119], v[176:179], 0
	v_mfma_f32_16x16x32_bf16 v[104:107], v[168:171], v[176:179], 0
	v_mfma_f32_16x16x32_bf16 v[100:103], v[168:171], v[190:193], 0
	v_mfma_f32_16x16x32_bf16 v[108:111], v[116:119], v[190:193], 0
	v_mfma_f32_16x16x32_bf16 v[96:99], v[116:119], v[198:201], 0
	v_mfma_f32_16x16x32_bf16 v[92:95], v[168:171], v[198:201], 0
	v_mfma_f32_16x16x32_bf16 v[84:87], v[168:171], v[214:217], 0
	v_mfma_f32_16x16x32_bf16 v[88:91], v[116:119], v[214:217], 0
	v_mfma_f32_16x16x32_bf16 v[112:115], v[120:123], v[180:183], v[112:115]
	v_mfma_f32_16x16x32_bf16 v[104:107], v[172:175], v[180:183], v[104:107]
	v_mfma_f32_16x16x32_bf16 v[100:103], v[172:175], v[194:197], v[100:103]
	v_mfma_f32_16x16x32_bf16 v[108:111], v[120:123], v[194:197], v[108:111]
	v_mfma_f32_16x16x32_bf16 v[96:99], v[120:123], v[210:213], v[96:99]
	v_mfma_f32_16x16x32_bf16 v[92:95], v[172:175], v[210:213], v[92:95]
	v_mfma_f32_16x16x32_bf16 v[84:87], v[172:175], v[218:221], v[84:87]
	v_mfma_f32_16x16x32_bf16 v[88:91], v[120:123], v[218:221], v[88:91]
	s_barrier
	s_add_i32 s8, s84, s80
	v_lshl_add_u64 v[184:185], s[70:71], 0, v[158:159]
	s_mov_b32 m0, s8
	ds_read_b128 v[176:179], v189 offset:16384
	ds_read_b128 v[180:183], v189 offset:17408
	ds_read_b128 v[190:193], v189 offset:18432
	ds_read_b128 v[194:197], v189 offset:19456
	ds_read_b128 v[198:201], v189 offset:20480
	ds_read_b128 v[210:213], v189 offset:21504
	ds_read_b128 v[214:217], v189 offset:22528
	ds_read_b128 v[218:221], v189 offset:23552
	global_load_lds_dwordx4 v[184:185], off
	s_add_i32 m0, s8, 0x2000
	s_add_u32 s8, s70, 0x80000
	v_lshl_add_u64 v[206:207], s[70:71], 0, v[162:163]
	s_addc_u32 s9, s71, 0
	s_add_i32 s10, s10, s80
	global_load_lds_dwordx4 v[206:207], off
	v_lshl_add_u64 v[2:3], s[8:9], 0, v[158:159]
	s_mov_b32 m0, s10
	v_lshl_add_u64 v[222:223], vcc, 0, v[156:157]
	global_load_lds_dwordx4 v[2:3], off
	v_lshl_add_u64 v[2:3], s[8:9], 0, v[162:163]
	s_add_i32 m0, s10, 0x2000
	v_lshl_add_u64 v[224:225], vcc, 0, v[160:161]
	global_load_lds_dwordx4 v[2:3], off
	s_mov_b32 m0, s58
	s_nop 0
	global_load_lds_dwordx4 v[222:223], off
	s_mov_b32 m0, s12
	s_nop 0
	global_load_lds_dwordx4 v[224:225], off
	s_waitcnt vmcnt(8) lgkmcnt(0)
	s_barrier
	v_mfma_f32_16x16x32_bf16 v[72:75], v[52:55], v[176:179], 0
	v_mfma_f32_16x16x32_bf16 v[64:67], v[76:79], v[176:179], 0
	v_mfma_f32_16x16x32_bf16 v[60:63], v[76:79], v[190:193], 0
	v_mfma_f32_16x16x32_bf16 v[68:71], v[52:55], v[190:193], 0
	v_mfma_f32_16x16x32_bf16 v[48:51], v[52:55], v[198:201], 0
	v_mfma_f32_16x16x32_bf16 v[44:47], v[76:79], v[198:201], 0
	v_mfma_f32_16x16x32_bf16 v[36:39], v[76:79], v[214:217], 0
	v_mfma_f32_16x16x32_bf16 v[40:43], v[52:55], v[214:217], 0
	v_mfma_f32_16x16x32_bf16 v[72:75], v[56:59], v[180:183], v[72:75]
	v_mfma_f32_16x16x32_bf16 v[64:67], v[80:83], v[180:183], v[64:67]
	v_mfma_f32_16x16x32_bf16 v[60:63], v[80:83], v[194:197], v[60:63]
	v_mfma_f32_16x16x32_bf16 v[68:71], v[56:59], v[194:197], v[68:71]
	v_mfma_f32_16x16x32_bf16 v[48:51], v[56:59], v[210:213], v[48:51]
	v_mfma_f32_16x16x32_bf16 v[44:47], v[80:83], v[210:213], v[44:47]
	v_mfma_f32_16x16x32_bf16 v[36:39], v[80:83], v[218:221], v[36:39]
	v_mfma_f32_16x16x32_bf16 v[40:43], v[56:59], v[218:221], v[40:43]
	v_mfma_f32_16x16x32_bf16 v[32:35], v[116:119], v[176:179], 0
	v_mfma_f32_16x16x32_bf16 v[24:27], v[168:171], v[176:179], 0
	v_mfma_f32_16x16x32_bf16 v[20:23], v[168:171], v[190:193], 0
	v_mfma_f32_16x16x32_bf16 v[28:31], v[116:119], v[190:193], 0
	v_mfma_f32_16x16x32_bf16 v[16:19], v[116:119], v[198:201], 0
	v_mfma_f32_16x16x32_bf16 v[12:15], v[168:171], v[198:201], 0
	v_mfma_f32_16x16x32_bf16 v[2:5], v[168:171], v[214:217], 0
	v_mfma_f32_16x16x32_bf16 v[8:11], v[116:119], v[214:217], 0
	v_mfma_f32_16x16x32_bf16 v[32:35], v[120:123], v[180:183], v[32:35]
	v_mfma_f32_16x16x32_bf16 v[24:27], v[172:175], v[180:183], v[24:27]
	v_mfma_f32_16x16x32_bf16 v[20:23], v[172:175], v[194:197], v[20:23]
	v_mfma_f32_16x16x32_bf16 v[28:31], v[120:123], v[194:197], v[28:31]
	v_mfma_f32_16x16x32_bf16 v[16:19], v[120:123], v[210:213], v[16:19]
	v_mfma_f32_16x16x32_bf16 v[12:15], v[172:175], v[210:213], v[12:15]
	v_mfma_f32_16x16x32_bf16 v[2:5], v[172:175], v[218:221], v[2:5]
	v_mfma_f32_16x16x32_bf16 v[8:11], v[120:123], v[218:221], v[8:11]
	s_barrier
; #define PG8_STAGE(bufoff, gbase, voff) do { _Pragma("unroll") for (int _i = 0; _i < 2; ++_i) \
;         __builtin_amdgcn_global_load_lds((const unsigned*)((const char*)(gbase) + (voff)[_i]), (PG8_LAS unsigned*)(lds + (bufoff) + ldsw + _i * 8192), 16, 0, 0); } while (0)
; #define PG8_LDA(dst, b, h) do { _Pragma("unroll") for (int m = 0; m < 4; ++m) _Pragma("unroll") for (int k = 0; k < 2; ++k) dst[m][k] = *(const PG8_LAS bf16x8*)(lds + PG8_SA(b, h) + aoff + m * 2048 + k * 1024); } while (0)
; #define PG8_LDB(dst, b, h) do { _Pragma("unroll") for (int n = 0; n < 2; ++n) _Pragma("unroll") for (int k = 0; k < 2; ++k) dst[n][k] = *(const PG8_LAS bf16x8*)(lds + PG8_SB(b, h) + boff + n * 2048 + k * 1024); } while (0)
; #define PG8_MMA(ai, bj, At, Bt) do { __builtin_amdgcn_s_setprio(1); _Pragma("unroll") for (int m = 0; m < 4; ++m) _Pragma("unroll") for (int n = 0; n < 2; ++n) _Pragma("unroll") for (int k = 0; k < 2; ++k) \
;         acc[ai][bj][m][n] = mma16<Epi::I8>(Bt[n][k], At[m][k], acc[ai][bj][m][n]); __builtin_amdgcn_s_setprio(0); } while (0)
; #define PG8_WAIT_V(n) asm volatile("s_waitcnt vmcnt(" #n ")" ::: "memory")
; #define PG8_WAIT_L(n) asm volatile("s_waitcnt lgkmcnt(" #n ")" ::: "memory")
; #define PG8_BAR __builtin_amdgcn_s_barrier()
; #define PG8_SCHED __builtin_amdgcn_sched_barrier(0)
; template <class Epi, class Sched, bool ALIGN_EPI = false, bool SP2 = false>
; __device__ __forceinline__ void gemm_phase(PG8_LAS unsigned char* lds, const Gemm g, const Sched& S, const Epi& E) {
;     ...
;             PG8_LDB(B0, 1, 0); PG8_LDB(B1, 1, 1); PG8_SCHED; PG8_LDA(At, 1, 0); PG8_STAGE(PG8_SA(0, 1), a2 + hstep, voffA);
;             PG8_WAIT_V(8); PG8_WAIT_L(0); PG8_BAR; PG8_MMA(0, 0, At, B0); PG8_MMA(0, 1, At, B1); PG8_BAR; PG8_SCHED;
;             PG8_LDA(At, 1, 1); PG8_STAGE(PG8_SB(1, 0), b3, voffB); PG8_STAGE(PG8_SB(1, 1), b3 + hstep, voffB); PG8_STAGE(PG8_SA(1, 0), a3, voffA);
;             PG8_WAIT_V(8); PG8_WAIT_L(0); PG8_BAR; PG8_MMA(1, 0, At, B0); PG8_MMA(1, 1, At, B1); PG8_BAR; PG8_SCHED;
	s_add_i32 s10, 0, 0x18000
	v_add_u32_e32 v0, s10, v188
	s_add_i32 s11, 0, 0x1c000
	ds_read_b128 v[52:55], v0
	ds_read_b128 v[56:59], v0 offset:1024
	ds_read_b128 v[76:79], v0 offset:2048
	ds_read_b128 v[80:83], v0 offset:3072
	v_add_u32_e32 v0, s11, v188
	ds_read_b128 v[116:119], v0
	ds_read_b128 v[120:123], v0 offset:1024
	ds_read_b128 v[168:171], v0 offset:2048
	ds_read_b128 v[172:175], v0 offset:3072
	s_add_u32 s8, vcc_lo, 0x80000
	s_addc_u32 s9, vcc_hi, 0
	s_mov_b32 m0, s13
	v_lshl_add_u64 v[6:7], s[8:9], 0, v[156:157]
	ds_read_b128 v[176:179], v189 offset:32768
	ds_read_b128 v[180:183], v189 offset:33792
	ds_read_b128 v[190:193], v189 offset:34816
	ds_read_b128 v[194:197], v189 offset:35840
	ds_read_b128 v[198:201], v189 offset:36864
	ds_read_b128 v[210:213], v189 offset:37888
	ds_read_b128 v[214:217], v189 offset:38912
	ds_read_b128 v[218:221], v189 offset:39936
	global_load_lds_dwordx4 v[6:7], off
	v_lshl_add_u64 v[6:7], s[8:9], 0, v[160:161]
	s_mov_b32 m0, s66
	s_nop 0
	global_load_lds_dwordx4 v[6:7], off
	s_waitcnt vmcnt(8) lgkmcnt(0)
	s_barrier
	v_mfma_f32_16x16x32_bf16 v[152:155], v[52:55], v[176:179], v[152:155]
	v_mfma_f32_16x16x32_bf16 v[144:147], v[76:79], v[176:179], v[144:147]
	v_mfma_f32_16x16x32_bf16 v[140:143], v[76:79], v[190:193], v[140:143]
	v_mfma_f32_16x16x32_bf16 v[148:151], v[52:55], v[190:193], v[148:151]
	v_mfma_f32_16x16x32_bf16 v[136:139], v[52:55], v[198:201], v[136:139]
	v_mfma_f32_16x16x32_bf16 v[132:135], v[76:79], v[198:201], v[132:135]
	v_mfma_f32_16x16x32_bf16 v[124:127], v[76:79], v[214:217], v[124:127]
	v_mfma_f32_16x16x32_bf16 v[128:131], v[52:55], v[214:217], v[128:131]
	v_mfma_f32_16x16x32_bf16 v[152:155], v[56:59], v[180:183], v[152:155]
	v_mfma_f32_16x16x32_bf16 v[144:147], v[80:83], v[180:183], v[144:147]
	v_mfma_f32_16x16x32_bf16 v[140:143], v[80:83], v[194:197], v[140:143]
	v_mfma_f32_16x16x32_bf16 v[148:151], v[56:59], v[194:197], v[148:151]
	v_mfma_f32_16x16x32_bf16 v[136:139], v[56:59], v[210:213], v[136:139]
	v_mfma_f32_16x16x32_bf16 v[132:135], v[80:83], v[210:213], v[132:135]
	v_mfma_f32_16x16x32_bf16 v[124:127], v[80:83], v[218:221], v[124:127]
	v_mfma_f32_16x16x32_bf16 v[128:131], v[56:59], v[218:221], v[128:131]
	v_mfma_f32_16x16x32_bf16 v[112:115], v[116:119], v[176:179], v[112:115]
	v_mfma_f32_16x16x32_bf16 v[104:107], v[168:171], v[176:179], v[104:107]
	v_mfma_f32_16x16x32_bf16 v[100:103], v[168:171], v[190:193], v[100:103]
	v_mfma_f32_16x16x32_bf16 v[108:111], v[116:119], v[190:193], v[108:111]
	v_mfma_f32_16x16x32_bf16 v[96:99], v[116:119], v[198:201], v[96:99]
	v_mfma_f32_16x16x32_bf16 v[92:95], v[168:171], v[198:201], v[92:95]
	v_mfma_f32_16x16x32_bf16 v[84:87], v[168:171], v[214:217], v[84:87]
	v_mfma_f32_16x16x32_bf16 v[88:91], v[116:119], v[214:217], v[88:91]
	v_mfma_f32_16x16x32_bf16 v[112:115], v[120:123], v[180:183], v[112:115]
	v_mfma_f32_16x16x32_bf16 v[104:107], v[172:175], v[180:183], v[104:107]
	v_mfma_f32_16x16x32_bf16 v[100:103], v[172:175], v[194:197], v[100:103]
	v_mfma_f32_16x16x32_bf16 v[108:111], v[120:123], v[194:197], v[108:111]
	v_mfma_f32_16x16x32_bf16 v[96:99], v[120:123], v[210:213], v[96:99]
	v_mfma_f32_16x16x32_bf16 v[92:95], v[172:175], v[210:213], v[92:95]
	v_mfma_f32_16x16x32_bf16 v[84:87], v[172:175], v[218:221], v[84:87]
	v_mfma_f32_16x16x32_bf16 v[88:91], v[120:123], v[218:221], v[88:91]
	s_barrier
	s_add_i32 s8, s10, s80
	v_lshl_add_u64 v[6:7], v[184:185], 0, s[92:93]
	s_mov_b32 m0, s8
	ds_read_b128 v[176:179], v189 offset:49152
	ds_read_b128 v[180:183], v189 offset:50176
	ds_read_b128 v[190:193], v189 offset:51200
	ds_read_b128 v[194:197], v189 offset:52224
	ds_read_b128 v[198:201], v189 offset:53248
	ds_read_b128 v[210:213], v189 offset:54272
	ds_read_b128 v[214:217], v189 offset:55296
	ds_read_b128 v[218:221], v189 offset:56320
	global_load_lds_dwordx4 v[6:7], off
	s_add_i32 m0, s8, 0x2000
	s_add_u32 s8, s70, 0x80080
	v_lshl_add_u64 v[6:7], v[206:207], 0, s[92:93]
	s_addc_u32 s9, s71, 0
	s_add_i32 s10, s11, s80
	global_load_lds_dwordx4 v[6:7], off
	v_lshl_add_u64 v[6:7], s[8:9], 0, v[158:159]
	s_mov_b32 m0, s10
	s_nop 0
	global_load_lds_dwordx4 v[6:7], off
	v_lshl_add_u64 v[6:7], s[8:9], 0, v[162:163]
	s_add_i32 m0, s10, 0x2000
	s_nop 0
	global_load_lds_dwordx4 v[6:7], off
	v_lshl_add_u64 v[6:7], v[222:223], 0, s[92:93]
	s_mov_b32 m0, s67
	s_nop 0
	global_load_lds_dwordx4 v[6:7], off
	v_lshl_add_u64 v[6:7], v[224:225], 0, s[92:93]
	s_mov_b32 m0, s81
	s_nop 0
	global_load_lds_dwordx4 v[6:7], off
	s_waitcnt vmcnt(8) lgkmcnt(0)
	s_barrier
	v_mfma_f32_16x16x32_bf16 v[72:75], v[52:55], v[176:179], v[72:75]
	v_mfma_f32_16x16x32_bf16 v[64:67], v[76:79], v[176:179], v[64:67]
	v_mfma_f32_16x16x32_bf16 v[60:63], v[76:79], v[190:193], v[60:63]
	v_mfma_f32_16x16x32_bf16 v[68:71], v[52:55], v[190:193], v[68:71]
	v_mfma_f32_16x16x32_bf16 v[48:51], v[52:55], v[198:201], v[48:51]
	v_mfma_f32_16x16x32_bf16 v[44:47], v[76:79], v[198:201], v[44:47]
	v_mfma_f32_16x16x32_bf16 v[36:39], v[76:79], v[214:217], v[36:39]
	v_mfma_f32_16x16x32_bf16 v[40:43], v[52:55], v[214:217], v[40:43]
	v_mfma_f32_16x16x32_bf16 v[72:75], v[56:59], v[180:183], v[72:75]
	v_mfma_f32_16x16x32_bf16 v[64:67], v[80:83], v[180:183], v[64:67]
	v_mfma_f32_16x16x32_bf16 v[60:63], v[80:83], v[194:197], v[60:63]
	v_mfma_f32_16x16x32_bf16 v[68:71], v[56:59], v[194:197], v[68:71]
	v_mfma_f32_16x16x32_bf16 v[48:51], v[56:59], v[210:213], v[48:51]
	v_mfma_f32_16x16x32_bf16 v[44:47], v[80:83], v[210:213], v[44:47]
	v_mfma_f32_16x16x32_bf16 v[36:39], v[80:83], v[218:221], v[36:39]
	v_mfma_f32_16x16x32_bf16 v[40:43], v[56:59], v[218:221], v[40:43]
	v_mfma_f32_16x16x32_bf16 v[32:35], v[116:119], v[176:179], v[32:35]
	v_mfma_f32_16x16x32_bf16 v[24:27], v[168:171], v[176:179], v[24:27]
	v_mfma_f32_16x16x32_bf16 v[20:23], v[168:171], v[190:193], v[20:23]
	v_mfma_f32_16x16x32_bf16 v[28:31], v[116:119], v[190:193], v[28:31]
	v_mfma_f32_16x16x32_bf16 v[16:19], v[116:119], v[198:201], v[16:19]
	v_mfma_f32_16x16x32_bf16 v[12:15], v[168:171], v[198:201], v[12:15]
	v_mfma_f32_16x16x32_bf16 v[2:5], v[168:171], v[214:217], v[2:5]
	v_mfma_f32_16x16x32_bf16 v[6:9], v[116:119], v[214:217], v[8:11]
	v_mfma_f32_16x16x32_bf16 v[32:35], v[120:123], v[180:183], v[32:35]
	v_mfma_f32_16x16x32_bf16 v[24:27], v[172:175], v[180:183], v[24:27]
	v_mfma_f32_16x16x32_bf16 v[20:23], v[172:175], v[194:197], v[20:23]
	v_mfma_f32_16x16x32_bf16 v[28:31], v[120:123], v[194:197], v[28:31]
	v_mfma_f32_16x16x32_bf16 v[16:19], v[120:123], v[210:213], v[16:19]
	v_mfma_f32_16x16x32_bf16 v[12:15], v[172:175], v[210:213], v[12:15]
	v_mfma_f32_16x16x32_bf16 v[8:11], v[120:123], v[218:221], v[6:9]
	v_mfma_f32_16x16x32_bf16 v[4:7], v[172:175], v[218:221], v[2:5]
	s_barrier
	s_add_i32 s4, s4, 2
	s_add_u32 s97, s97, 0x100
	s_addc_u32 s96, s96, 0
	s_cmp_gt_u32 s4, 29
	s_mov_b64 s[8:9], s[68:69]
	s_cbranch_scc0 .LBB0_327
	s_branch .Lpeelx327
; #define PG8_STAGE(bufoff, gbase, voff) do { _Pragma("unroll") for (int _i = 0; _i < 2; ++_i) \
;         __builtin_amdgcn_global_load_lds((const unsigned*)((const char*)(gbase) + (voff)[_i]), (PG8_LAS unsigned*)(lds + (bufoff) + ldsw + _i * 8192), 16, 0, 0); } while (0)
; #define PG8_LDA(dst, b, h) do { _Pragma("unroll") for (int m = 0; m < 4; ++m) _Pragma("unroll") for (int k = 0; k < 2; ++k) dst[m][k] = *(const PG8_LAS bf16x8*)(lds + PG8_SA(b, h) + aoff + m * 2048 + k * 1024); } while (0)
; #define PG8_LDB(dst, b, h) do { _Pragma("unroll") for (int n = 0; n < 2; ++n) _Pragma("unroll") for (int k = 0; k < 2; ++k) dst[n][k] = *(const PG8_LAS bf16x8*)(lds + PG8_SB(b, h) + boff + n * 2048 + k * 1024); } while (0)
; #define PG8_MMA(ai, bj, At, Bt) do { __builtin_amdgcn_s_setprio(1); _Pragma("unroll") for (int m = 0; m < 4; ++m) _Pragma("unroll") for (int n = 0; n < 2; ++n) _Pragma("unroll") for (int k = 0; k < 2; ++k) \
;         acc[ai][bj][m][n] = mma16<Epi::I8>(Bt[n][k], At[m][k], acc[ai][bj][m][n]); __builtin_amdgcn_s_setprio(0); } while (0)
; #define PG8_WAIT_V(n) asm volatile("s_waitcnt vmcnt(" #n ")" ::: "memory")
; #define PG8_WAIT_L(n) asm volatile("s_waitcnt lgkmcnt(" #n ")" ::: "memory")
; #define PG8_BAR __builtin_amdgcn_s_barrier()
; template <class Epi, class Sched, bool ALIGN_EPI = false, bool SP2 = false>
; __device__ __forceinline__ void gemm_phase(PG8_LAS unsigned char* lds, const Gemm g, const Sched& S, const Epi& E) {
;     ...
;             const bool last = (t == nt - 2);
;             const char* a1 = cA + (size_t)(t + 1) * kstep;
;             const char* a2 = last ? nA : cA + (size_t)(t + 2) * kstep; const char* b2 = last ? nB : cB + (size_t)(t + 2) * kstep;
;             const char* a3 = a2 + kstep; const char* b3 = b2 + kstep;
;             if (last && has_next) S.a_ready(nxt);
;             if constexpr (SP2) {
;             PG8_LDB(B0, 0, 0); PG8_LDB(B1, 0, 1); PG8_SCHED; PG8_LDA(At, 0, 0); PG8_STAGE(PG8_SA(1, 1), a1 + hstep, voffA);
;             PG8_WAIT_V(8); PG8_WAIT_L(0); PG8_BAR; PG8_MMA(0, 0, At, B0); PG8_MMA(0, 1, At, B1); PG8_BAR; PG8_SCHED;
;             PG8_LDA(At, 0, 1); PG8_STAGE(PG8_SB(0, 0), b2, voffB); PG8_STAGE(PG8_SB(0, 1), b2 + hstep, voffB); PG8_STAGE(PG8_SA(0, 0), a2, voffA);
;             PG8_WAIT_V(8); PG8_WAIT_L(0); PG8_BAR; PG8_MMA(1, 0, At, B0); PG8_MMA(1, 1, At, B1); PG8_BAR; PG8_SCHED;
.LBB0_327:
	s_add_u32 s68, s8, 0x100
	s_addc_u32 s69, s9, 0
	s_add_i32 s84, 0, 0x10000
	s_cmp_eq_u32 s4, 28
	s_cselect_b32 vcc_hi, s1, s69
	s_cselect_b32 vcc_lo, s5, s68
	v_add_u32_e32 v0, s84, v188
	s_cselect_b32 s71, s7, s96
	s_cselect_b32 s70, s85, s97
	s_add_i32 s10, 0, 0x14000
	ds_read_b128 v[52:55], v0
	ds_read_b128 v[56:59], v0 offset:1024
	ds_read_b128 v[76:79], v0 offset:2048
	ds_read_b128 v[80:83], v0 offset:3072
	v_add_u32_e32 v0, s10, v188
	ds_read_b128 v[116:119], v0
	ds_read_b128 v[120:123], v0 offset:1024
	ds_read_b128 v[168:171], v0 offset:2048
	ds_read_b128 v[172:175], v0 offset:3072
	v_lshl_add_u64 v[2:3], s[8:9], 0, v[164:165]
	s_add_i32 m0, s58, 0xc000
	ds_read_b128 v[176:179], v189
	ds_read_b128 v[180:183], v189 offset:1024
	ds_read_b128 v[190:193], v189 offset:2048
	ds_read_b128 v[194:197], v189 offset:3072
	ds_read_b128 v[198:201], v189 offset:4096
	ds_read_b128 v[210:213], v189 offset:5120
	ds_read_b128 v[214:217], v189 offset:6144
	ds_read_b128 v[218:221], v189 offset:7168
	global_load_lds_dwordx4 v[2:3], off
	v_lshl_add_u64 v[2:3], s[8:9], 0, v[166:167]
	s_add_i32 m0, s58, 0xe000
	s_nop 0
	global_load_lds_dwordx4 v[2:3], off
	s_waitcnt vmcnt(8) lgkmcnt(0)
	s_barrier
	v_mfma_f32_16x16x32_bf16 v[152:155], v[52:55], v[176:179], v[152:155]
	v_mfma_f32_16x16x32_bf16 v[144:147], v[76:79], v[176:179], v[144:147]
	v_mfma_f32_16x16x32_bf16 v[140:143], v[76:79], v[190:193], v[140:143]
	v_mfma_f32_16x16x32_bf16 v[148:151], v[52:55], v[190:193], v[148:151]
	v_mfma_f32_16x16x32_bf16 v[136:139], v[52:55], v[198:201], v[136:139]
	v_mfma_f32_16x16x32_bf16 v[132:135], v[76:79], v[198:201], v[132:135]
	v_mfma_f32_16x16x32_bf16 v[124:127], v[76:79], v[214:217], v[124:127]
	v_mfma_f32_16x16x32_bf16 v[128:131], v[52:55], v[214:217], v[128:131]
	v_mfma_f32_16x16x32_bf16 v[152:155], v[56:59], v[180:183], v[152:155]
	v_mfma_f32_16x16x32_bf16 v[144:147], v[80:83], v[180:183], v[144:147]
	v_mfma_f32_16x16x32_bf16 v[140:143], v[80:83], v[194:197], v[140:143]
	v_mfma_f32_16x16x32_bf16 v[148:151], v[56:59], v[194:197], v[148:151]
	v_mfma_f32_16x16x32_bf16 v[136:139], v[56:59], v[210:213], v[136:139]
	v_mfma_f32_16x16x32_bf16 v[132:135], v[80:83], v[210:213], v[132:135]
	v_mfma_f32_16x16x32_bf16 v[124:127], v[80:83], v[218:221], v[124:127]
	v_mfma_f32_16x16x32_bf16 v[128:131], v[56:59], v[218:221], v[128:131]
	v_mfma_f32_16x16x32_bf16 v[112:115], v[116:119], v[176:179], v[112:115]
	v_mfma_f32_16x16x32_bf16 v[104:107], v[168:171], v[176:179], v[104:107]
	v_mfma_f32_16x16x32_bf16 v[100:103], v[168:171], v[190:193], v[100:103]
	v_mfma_f32_16x16x32_bf16 v[108:111], v[116:119], v[190:193], v[108:111]
	v_mfma_f32_16x16x32_bf16 v[96:99], v[116:119], v[198:201], v[96:99]
	v_mfma_f32_16x16x32_bf16 v[92:95], v[168:171], v[198:201], v[92:95]
	v_mfma_f32_16x16x32_bf16 v[84:87], v[168:171], v[214:217], v[84:87]
	v_mfma_f32_16x16x32_bf16 v[88:91], v[116:119], v[214:217], v[88:91]
	v_mfma_f32_16x16x32_bf16 v[112:115], v[120:123], v[180:183], v[112:115]
	v_mfma_f32_16x16x32_bf16 v[104:107], v[172:175], v[180:183], v[104:107]
	v_mfma_f32_16x16x32_bf16 v[100:103], v[172:175], v[194:197], v[100:103]
	v_mfma_f32_16x16x32_bf16 v[108:111], v[120:123], v[194:197], v[108:111]
	v_mfma_f32_16x16x32_bf16 v[96:99], v[120:123], v[210:213], v[96:99]
	v_mfma_f32_16x16x32_bf16 v[92:95], v[172:175], v[210:213], v[92:95]
	v_mfma_f32_16x16x32_bf16 v[84:87], v[172:175], v[218:221], v[84:87]
	v_mfma_f32_16x16x32_bf16 v[88:91], v[120:123], v[218:221], v[88:91]
	s_barrier
	s_add_i32 s8, s84, s80
	v_lshl_add_u64 v[184:185], s[70:71], 0, v[158:159]
	s_mov_b32 m0, s8
	ds_read_b128 v[176:179], v189 offset:16384
	ds_read_b128 v[180:183], v189 offset:17408
	ds_read_b128 v[190:193], v189 offset:18432
	ds_read_b128 v[194:197], v189 offset:19456
	ds_read_b128 v[198:201], v189 offset:20480
	ds_read_b128 v[210:213], v189 offset:21504
	ds_read_b128 v[214:217], v189 offset:22528
	ds_read_b128 v[218:221], v189 offset:23552
	global_load_lds_dwordx4 v[184:185], off
	s_add_i32 m0, s8, 0x2000
	s_add_u32 s8, s70, 0x80000
	v_lshl_add_u64 v[206:207], s[70:71], 0, v[162:163]
	s_addc_u32 s9, s71, 0
	s_add_i32 s10, s10, s80
	global_load_lds_dwordx4 v[206:207], off
	v_lshl_add_u64 v[2:3], s[8:9], 0, v[158:159]
	s_mov_b32 m0, s10
	v_lshl_add_u64 v[222:223], vcc, 0, v[156:157]
	global_load_lds_dwordx4 v[2:3], off
	v_lshl_add_u64 v[2:3], s[8:9], 0, v[162:163]
	s_add_i32 m0, s10, 0x2000
	v_lshl_add_u64 v[224:225], vcc, 0, v[160:161]
	global_load_lds_dwordx4 v[2:3], off
	s_mov_b32 m0, s58
	s_nop 0
	global_load_lds_dwordx4 v[222:223], off
	s_mov_b32 m0, s12
	s_nop 0
	global_load_lds_dwordx4 v[224:225], off
	s_waitcnt vmcnt(8) lgkmcnt(0)
	s_barrier
; #define PG8_STAGE(bufoff, gbase, voff) do { _Pragma("unroll") for (int _i = 0; _i < 2; ++_i) \
;         __builtin_amdgcn_global_load_lds((const unsigned*)((const char*)(gbase) + (voff)[_i]), (PG8_LAS unsigned*)(lds + (bufoff) + ldsw + _i * 8192), 16, 0, 0); } while (0)
; #define PG8_LDA(dst, b, h) do { _Pragma("unroll") for (int m = 0; m < 4; ++m) _Pragma("unroll") for (int k = 0; k < 2; ++k) dst[m][k] = *(const PG8_LAS bf16x8*)(lds + PG8_SA(b, h) + aoff + m * 2048 + k * 1024); } while (0)
; #define PG8_LDB(dst, b, h) do { _Pragma("unroll") for (int n = 0; n < 2; ++n) _Pragma("unroll") for (int k = 0; k < 2; ++k) dst[n][k] = *(const PG8_LAS bf16x8*)(lds + PG8_SB(b, h) + boff + n * 2048 + k * 1024); } while (0)
; #define PG8_MMA(ai, bj, At, Bt) do { __builtin_amdgcn_s_setprio(1); _Pragma("unroll") for (int m = 0; m < 4; ++m) _Pragma("unroll") for (int n = 0; n < 2; ++n) _Pragma("unroll") for (int k = 0; k < 2; ++k) \
;         acc[ai][bj][m][n] = mma16<Epi::I8>(Bt[n][k], At[m][k], acc[ai][bj][m][n]); __builtin_amdgcn_s_setprio(0); } while (0)
; #define PG8_WAIT_V(n) asm volatile("s_waitcnt vmcnt(" #n ")" ::: "memory")
; #define PG8_WAIT_L(n) asm volatile("s_waitcnt lgkmcnt(" #n ")" ::: "memory")
; #define PG8_BAR __builtin_amdgcn_s_barrier()
; #define PG8_SCHED __builtin_amdgcn_sched_barrier(0)
; template <class Epi, class Sched, bool ALIGN_EPI = false, bool SP2 = false>
; __device__ __forceinline__ void gemm_phase(PG8_LAS unsigned char* lds, const Gemm g, const Sched& S, const Epi& E) {
;     ...
;             PG8_WAIT_V(8); PG8_WAIT_L(0); PG8_BAR; PG8_MMA(1, 0, At, B0); PG8_MMA(1, 1, At, B1); PG8_BAR; PG8_SCHED;
;             PG8_LDB(B0, 1, 0); PG8_LDB(B1, 1, 1); PG8_SCHED; PG8_LDA(At, 1, 0); PG8_STAGE(PG8_SA(0, 1), a2 + hstep, voffA);
;             PG8_WAIT_V(8); PG8_WAIT_L(0); PG8_BAR; PG8_MMA(0, 0, At, B0); PG8_MMA(0, 1, At, B1); PG8_BAR; PG8_SCHED;
	v_mfma_f32_16x16x32_bf16 v[72:75], v[52:55], v[176:179], v[72:75]
	v_mfma_f32_16x16x32_bf16 v[64:67], v[76:79], v[176:179], v[64:67]
	v_mfma_f32_16x16x32_bf16 v[60:63], v[76:79], v[190:193], v[60:63]
	v_mfma_f32_16x16x32_bf16 v[68:71], v[52:55], v[190:193], v[68:71]
	v_mfma_f32_16x16x32_bf16 v[48:51], v[52:55], v[198:201], v[48:51]
	v_mfma_f32_16x16x32_bf16 v[44:47], v[76:79], v[198:201], v[44:47]
	v_mfma_f32_16x16x32_bf16 v[36:39], v[76:79], v[214:217], v[36:39]
	v_mfma_f32_16x16x32_bf16 v[40:43], v[52:55], v[214:217], v[40:43]
	v_mfma_f32_16x16x32_bf16 v[72:75], v[56:59], v[180:183], v[72:75]
	v_mfma_f32_16x16x32_bf16 v[64:67], v[80:83], v[180:183], v[64:67]
	v_mfma_f32_16x16x32_bf16 v[60:63], v[80:83], v[194:197], v[60:63]
	v_mfma_f32_16x16x32_bf16 v[68:71], v[56:59], v[194:197], v[68:71]
	v_mfma_f32_16x16x32_bf16 v[48:51], v[56:59], v[210:213], v[48:51]
	v_mfma_f32_16x16x32_bf16 v[44:47], v[80:83], v[210:213], v[44:47]
	v_mfma_f32_16x16x32_bf16 v[36:39], v[80:83], v[218:221], v[36:39]
	v_mfma_f32_16x16x32_bf16 v[40:43], v[56:59], v[218:221], v[40:43]
	v_mfma_f32_16x16x32_bf16 v[32:35], v[116:119], v[176:179], v[32:35]
	v_mfma_f32_16x16x32_bf16 v[24:27], v[168:171], v[176:179], v[24:27]
	v_mfma_f32_16x16x32_bf16 v[20:23], v[168:171], v[190:193], v[20:23]
	v_mfma_f32_16x16x32_bf16 v[28:31], v[116:119], v[190:193], v[28:31]
	v_mfma_f32_16x16x32_bf16 v[16:19], v[116:119], v[198:201], v[16:19]
	v_mfma_f32_16x16x32_bf16 v[12:15], v[168:171], v[198:201], v[12:15]
	v_mfma_f32_16x16x32_bf16 v[2:5], v[168:171], v[214:217], v[4:7]
	v_mfma_f32_16x16x32_bf16 v[8:11], v[116:119], v[214:217], v[8:11]
	v_mfma_f32_16x16x32_bf16 v[32:35], v[120:123], v[180:183], v[32:35]
	v_mfma_f32_16x16x32_bf16 v[24:27], v[172:175], v[180:183], v[24:27]
	v_mfma_f32_16x16x32_bf16 v[20:23], v[172:175], v[194:197], v[20:23]
	v_mfma_f32_16x16x32_bf16 v[28:31], v[120:123], v[194:197], v[28:31]
	v_mfma_f32_16x16x32_bf16 v[16:19], v[120:123], v[210:213], v[16:19]
	v_mfma_f32_16x16x32_bf16 v[12:15], v[172:175], v[210:213], v[12:15]
	v_mfma_f32_16x16x32_bf16 v[2:5], v[172:175], v[218:221], v[2:5]
	v_mfma_f32_16x16x32_bf16 v[8:11], v[120:123], v[218:221], v[8:11]
	s_barrier
	s_add_i32 s10, 0, 0x18000
	v_add_u32_e32 v0, s10, v188
	s_add_i32 s11, 0, 0x1c000
	ds_read_b128 v[52:55], v0
	ds_read_b128 v[56:59], v0 offset:1024
	ds_read_b128 v[76:79], v0 offset:2048
	ds_read_b128 v[80:83], v0 offset:3072
	v_add_u32_e32 v0, s11, v188
	ds_read_b128 v[116:119], v0
	ds_read_b128 v[120:123], v0 offset:1024
	ds_read_b128 v[168:171], v0 offset:2048
	ds_read_b128 v[172:175], v0 offset:3072
	s_add_u32 s8, vcc_lo, 0x80000
	s_addc_u32 s9, vcc_hi, 0
	s_mov_b32 m0, s13
	v_lshl_add_u64 v[6:7], s[8:9], 0, v[156:157]
	ds_read_b128 v[176:179], v189 offset:32768
	ds_read_b128 v[180:183], v189 offset:33792
	ds_read_b128 v[190:193], v189 offset:34816
	ds_read_b128 v[194:197], v189 offset:35840
	ds_read_b128 v[198:201], v189 offset:36864
	ds_read_b128 v[210:213], v189 offset:37888
	ds_read_b128 v[214:217], v189 offset:38912
	ds_read_b128 v[218:221], v189 offset:39936
	global_load_lds_dwordx4 v[6:7], off
	v_lshl_add_u64 v[6:7], s[8:9], 0, v[160:161]
	s_mov_b32 m0, s66
	s_nop 0
	global_load_lds_dwordx4 v[6:7], off
	s_waitcnt vmcnt(8) lgkmcnt(0)
	s_barrier
	v_mfma_f32_16x16x32_bf16 v[152:155], v[52:55], v[176:179], v[152:155]
	v_mfma_f32_16x16x32_bf16 v[144:147], v[76:79], v[176:179], v[144:147]
	v_mfma_f32_16x16x32_bf16 v[140:143], v[76:79], v[190:193], v[140:143]
	v_mfma_f32_16x16x32_bf16 v[148:151], v[52:55], v[190:193], v[148:151]
	v_mfma_f32_16x16x32_bf16 v[136:139], v[52:55], v[198:201], v[136:139]
	v_mfma_f32_16x16x32_bf16 v[132:135], v[76:79], v[198:201], v[132:135]
	v_mfma_f32_16x16x32_bf16 v[124:127], v[76:79], v[214:217], v[124:127]
	v_mfma_f32_16x16x32_bf16 v[128:131], v[52:55], v[214:217], v[128:131]
	v_mfma_f32_16x16x32_bf16 v[152:155], v[56:59], v[180:183], v[152:155]
	v_mfma_f32_16x16x32_bf16 v[144:147], v[80:83], v[180:183], v[144:147]
	v_mfma_f32_16x16x32_bf16 v[140:143], v[80:83], v[194:197], v[140:143]
	v_mfma_f32_16x16x32_bf16 v[148:151], v[56:59], v[194:197], v[148:151]
	v_mfma_f32_16x16x32_bf16 v[136:139], v[56:59], v[210:213], v[136:139]
	v_mfma_f32_16x16x32_bf16 v[132:135], v[80:83], v[210:213], v[132:135]
	v_mfma_f32_16x16x32_bf16 v[124:127], v[80:83], v[218:221], v[124:127]
	v_mfma_f32_16x16x32_bf16 v[128:131], v[56:59], v[218:221], v[128:131]
	v_mfma_f32_16x16x32_bf16 v[112:115], v[116:119], v[176:179], v[112:115]
	v_mfma_f32_16x16x32_bf16 v[104:107], v[168:171], v[176:179], v[104:107]
	v_mfma_f32_16x16x32_bf16 v[100:103], v[168:171], v[190:193], v[100:103]
	v_mfma_f32_16x16x32_bf16 v[108:111], v[116:119], v[190:193], v[108:111]
	v_mfma_f32_16x16x32_bf16 v[96:99], v[116:119], v[198:201], v[96:99]
	v_mfma_f32_16x16x32_bf16 v[92:95], v[168:171], v[198:201], v[92:95]
	v_mfma_f32_16x16x32_bf16 v[84:87], v[168:171], v[214:217], v[84:87]
	v_mfma_f32_16x16x32_bf16 v[88:91], v[116:119], v[214:217], v[88:91]
	v_mfma_f32_16x16x32_bf16 v[112:115], v[120:123], v[180:183], v[112:115]
	v_mfma_f32_16x16x32_bf16 v[104:107], v[172:175], v[180:183], v[104:107]
	v_mfma_f32_16x16x32_bf16 v[100:103], v[172:175], v[194:197], v[100:103]
	v_mfma_f32_16x16x32_bf16 v[108:111], v[120:123], v[194:197], v[108:111]
	v_mfma_f32_16x16x32_bf16 v[96:99], v[120:123], v[210:213], v[96:99]
	v_mfma_f32_16x16x32_bf16 v[92:95], v[172:175], v[210:213], v[92:95]
	v_mfma_f32_16x16x32_bf16 v[84:87], v[172:175], v[218:221], v[84:87]
	v_mfma_f32_16x16x32_bf16 v[88:91], v[120:123], v[218:221], v[88:91]
	s_barrier
; #define PG8_STAGE(bufoff, gbase, voff) do { _Pragma("unroll") for (int _i = 0; _i < 2; ++_i) \
;         __builtin_amdgcn_global_load_lds((const unsigned*)((const char*)(gbase) + (voff)[_i]), (PG8_LAS unsigned*)(lds + (bufoff) + ldsw + _i * 8192), 16, 0, 0); } while (0)
; #define PG8_LDA(dst, b, h) do { _Pragma("unroll") for (int m = 0; m < 4; ++m) _Pragma("unroll") for (int k = 0; k < 2; ++k) dst[m][k] = *(const PG8_LAS bf16x8*)(lds + PG8_SA(b, h) + aoff + m * 2048 + k * 1024); } while (0)
; #define PG8_MMA(ai, bj, At, Bt) do { __builtin_amdgcn_s_setprio(1); _Pragma("unroll") for (int m = 0; m < 4; ++m) _Pragma("unroll") for (int n = 0; n < 2; ++n) _Pragma("unroll") for (int k = 0; k < 2; ++k) \
;         acc[ai][bj][m][n] = mma16<Epi::I8>(Bt[n][k], At[m][k], acc[ai][bj][m][n]); __builtin_amdgcn_s_setprio(0); } while (0)
; #define PG8_WAIT_V(n) asm volatile("s_waitcnt vmcnt(" #n ")" ::: "memory")
; #define PG8_WAIT_L(n) asm volatile("s_waitcnt lgkmcnt(" #n ")" ::: "memory")
; #define PG8_BAR __builtin_amdgcn_s_barrier()
; #define PG8_SCHED __builtin_amdgcn_sched_barrier(0)
; template <class Epi, class Sched, bool ALIGN_EPI = false, bool SP2 = false>
; __device__ __forceinline__ void gemm_phase(PG8_LAS unsigned char* lds, const Gemm g, const Sched& S, const Epi& E) {
;     ...
;             PG8_LDA(At, 1, 1); PG8_STAGE(PG8_SB(1, 0), b3, voffB); PG8_STAGE(PG8_SB(1, 1), b3 + hstep, voffB); PG8_STAGE(PG8_SA(1, 0), a3, voffA);
;             PG8_WAIT_V(8); PG8_WAIT_L(0); PG8_BAR; PG8_MMA(1, 0, At, B0); PG8_MMA(1, 1, At, B1); PG8_BAR; PG8_SCHED;
	s_add_i32 s8, s10, s80
	v_lshl_add_u64 v[6:7], v[184:185], 0, s[92:93]
	s_mov_b32 m0, s8
	ds_read_b128 v[176:179], v189 offset:49152
	ds_read_b128 v[180:183], v189 offset:50176
	ds_read_b128 v[190:193], v189 offset:51200
	ds_read_b128 v[194:197], v189 offset:52224
	ds_read_b128 v[198:201], v189 offset:53248
	ds_read_b128 v[210:213], v189 offset:54272
	ds_read_b128 v[214:217], v189 offset:55296
	ds_read_b128 v[218:221], v189 offset:56320
	global_load_lds_dwordx4 v[6:7], off
	s_add_i32 m0, s8, 0x2000
	s_add_u32 s8, s70, 0x80080
	v_lshl_add_u64 v[6:7], v[206:207], 0, s[92:93]
	s_addc_u32 s9, s71, 0
	s_add_i32 s10, s11, s80
	global_load_lds_dwordx4 v[6:7], off
	v_lshl_add_u64 v[6:7], s[8:9], 0, v[158:159]
	s_mov_b32 m0, s10
	s_nop 0
	global_load_lds_dwordx4 v[6:7], off
	v_lshl_add_u64 v[6:7], s[8:9], 0, v[162:163]
	s_add_i32 m0, s10, 0x2000
	s_nop 0
	global_load_lds_dwordx4 v[6:7], off
	v_lshl_add_u64 v[6:7], v[222:223], 0, s[92:93]
	s_mov_b32 m0, s67
	s_nop 0
	global_load_lds_dwordx4 v[6:7], off
	v_lshl_add_u64 v[6:7], v[224:225], 0, s[92:93]
	s_mov_b32 m0, s81
	s_nop 0
	global_load_lds_dwordx4 v[6:7], off
	s_waitcnt vmcnt(8) lgkmcnt(0)
	s_barrier
	v_mfma_f32_16x16x32_bf16 v[72:75], v[52:55], v[176:179], v[72:75]
	v_mfma_f32_16x16x32_bf16 v[64:67], v[76:79], v[176:179], v[64:67]
	v_mfma_f32_16x16x32_bf16 v[60:63], v[76:79], v[190:193], v[60:63]
	v_mfma_f32_16x16x32_bf16 v[68:71], v[52:55], v[190:193], v[68:71]
	v_mfma_f32_16x16x32_bf16 v[48:51], v[52:55], v[198:201], v[48:51]
	v_mfma_f32_16x16x32_bf16 v[44:47], v[76:79], v[198:201], v[44:47]
	v_mfma_f32_16x16x32_bf16 v[36:39], v[76:79], v[214:217], v[36:39]
	v_mfma_f32_16x16x32_bf16 v[40:43], v[52:55], v[214:217], v[40:43]
	v_mfma_f32_16x16x32_bf16 v[72:75], v[56:59], v[180:183], v[72:75]
	v_mfma_f32_16x16x32_bf16 v[64:67], v[80:83], v[180:183], v[64:67]
	v_mfma_f32_16x16x32_bf16 v[60:63], v[80:83], v[194:197], v[60:63]
	v_mfma_f32_16x16x32_bf16 v[68:71], v[56:59], v[194:197], v[68:71]
	v_mfma_f32_16x16x32_bf16 v[48:51], v[56:59], v[210:213], v[48:51]
	v_mfma_f32_16x16x32_bf16 v[44:47], v[80:83], v[210:213], v[44:47]
	v_mfma_f32_16x16x32_bf16 v[36:39], v[80:83], v[218:221], v[36:39]
	v_mfma_f32_16x16x32_bf16 v[40:43], v[56:59], v[218:221], v[40:43]
	v_mfma_f32_16x16x32_bf16 v[32:35], v[116:119], v[176:179], v[32:35]
	v_mfma_f32_16x16x32_bf16 v[24:27], v[168:171], v[176:179], v[24:27]
	v_mfma_f32_16x16x32_bf16 v[20:23], v[168:171], v[190:193], v[20:23]
	v_mfma_f32_16x16x32_bf16 v[28:31], v[116:119], v[190:193], v[28:31]
	v_mfma_f32_16x16x32_bf16 v[16:19], v[116:119], v[198:201], v[16:19]
	v_mfma_f32_16x16x32_bf16 v[12:15], v[168:171], v[198:201], v[12:15]
	v_mfma_f32_16x16x32_bf16 v[2:5], v[168:171], v[214:217], v[2:5]
	v_mfma_f32_16x16x32_bf16 v[6:9], v[116:119], v[214:217], v[8:11]
	v_mfma_f32_16x16x32_bf16 v[32:35], v[120:123], v[180:183], v[32:35]
	v_mfma_f32_16x16x32_bf16 v[24:27], v[172:175], v[180:183], v[24:27]
	v_mfma_f32_16x16x32_bf16 v[20:23], v[172:175], v[194:197], v[20:23]
	v_mfma_f32_16x16x32_bf16 v[28:31], v[120:123], v[194:197], v[28:31]
	v_mfma_f32_16x16x32_bf16 v[16:19], v[120:123], v[210:213], v[16:19]
	v_mfma_f32_16x16x32_bf16 v[12:15], v[172:175], v[210:213], v[12:15]
	v_mfma_f32_16x16x32_bf16 v[8:11], v[120:123], v[218:221], v[6:9]
	v_mfma_f32_16x16x32_bf16 v[4:7], v[172:175], v[218:221], v[2:5]
	s_barrier
	s_add_i32 s4, s4, 2
	s_add_u32 s97, s97, 0x100
	s_addc_u32 s96, s96, 0
	s_cmp_gt_u32 s4, 29
	s_mov_b64 s[8:9], s[68:69]
	s_cbranch_scc0 .LBB0_327

; #define PG8_STAGE(bufoff, gbase, voff) do { _Pragma("unroll") for (int _i = 0; _i < 2; ++_i) \
;         __builtin_amdgcn_global_load_lds((const unsigned*)((const char*)(gbase) + (voff)[_i]), (PG8_LAS unsigned*)(lds + (bufoff) + ldsw + _i * 8192), 16, 0, 0); } while (0)
; #define PG8_LDA(dst, b, h) do { _Pragma("unroll") for (int m = 0; m < 4; ++m) _Pragma("unroll") for (int k = 0; k < 2; ++k) dst[m][k] = *(const PG8_LAS bf16x8*)(lds + PG8_SA(b, h) + aoff + m * 2048 + k * 1024); } while (0)
; #define PG8_LDB(dst, b, h) do { _Pragma("unroll") for (int n = 0; n < 2; ++n) _Pragma("unroll") for (int k = 0; k < 2; ++k) dst[n][k] = *(const PG8_LAS bf16x8*)(lds + PG8_SB(b, h) + boff + n * 2048 + k * 1024); } while (0)
; #define PG8_MMA(ai, bj, At, Bt) do { __builtin_amdgcn_s_setprio(1); _Pragma("unroll") for (int m = 0; m < 4; ++m) _Pragma("unroll") for (int n = 0; n < 2; ++n) _Pragma("unroll") for (int k = 0; k < 2; ++k) \
;         acc[ai][bj][m][n] = mma16<Epi::I8>(Bt[n][k], At[m][k], acc[ai][bj][m][n]); __builtin_amdgcn_s_setprio(0); } while (0)
; #define PG8_WAIT_V(n) asm volatile("s_waitcnt vmcnt(" #n ")" ::: "memory")
; #define PG8_WAIT_L(n) asm volatile("s_waitcnt lgkmcnt(" #n ")" ::: "memory")
; #define PG8_BAR __builtin_amdgcn_s_barrier()
; template <class Epi, class Sched, bool ALIGN_EPI = false, bool SP2 = false>
; __device__ __forceinline__ void gemm_phase(PG8_LAS unsigned char* lds, const Gemm g, const Sched& S, const Epi& E) {
;     ...
;             const bool last = (t == nt - 2);
;             const char* a1 = cA + (size_t)(t + 1) * kstep;
;             const char* a2 = last ? nA : cA + (size_t)(t + 2) * kstep; const char* b2 = last ? nB : cB + (size_t)(t + 2) * kstep;
;             const char* a3 = a2 + kstep; const char* b3 = b2 + kstep;
;             if (last && has_next) S.a_ready(nxt);
;             if constexpr (SP2) {
;             PG8_LDB(B0, 0, 0); PG8_LDB(B1, 0, 1); PG8_SCHED; PG8_LDA(At, 0, 0); PG8_STAGE(PG8_SA(1, 1), a1 + hstep, voffA);
;             PG8_WAIT_V(8); PG8_WAIT_L(0); PG8_BAR; PG8_MMA(0, 0, At, B0); PG8_MMA(0, 1, At, B1); PG8_BAR; PG8_SCHED;
;             PG8_LDA(At, 0, 1); PG8_STAGE(PG8_SB(0, 0), b2, voffB); PG8_STAGE(PG8_SB(0, 1), b2 + hstep, voffB); PG8_STAGE(PG8_SA(0, 0), a2, voffA);
;             PG8_WAIT_V(8); PG8_WAIT_L(0); PG8_BAR; PG8_MMA(1, 0, At, B0); PG8_MMA(1, 1, At, B1); PG8_BAR; PG8_SCHED;
.Lpeel385:
	s_add_u32 s70, s8, 0x100
	s_addc_u32 s71, s9, 0
	s_add_i32 s84, 0, 0x10000
	s_cmp_eq_u32 s5, 12
	s_cselect_b32 vcc_hi, s1, s71
	s_cselect_b32 vcc_lo, s7, s70
	v_add_u32_e32 v0, s84, v214
	s_cselect_b32 s83, s69, s68
	s_cselect_b32 s82, s81, s85
	s_add_i32 s10, 0, 0x14000
	ds_read_b128 v[44:47], v0
	ds_read_b128 v[52:55], v0 offset:1024
	ds_read_b128 v[60:63], v0 offset:2048
	ds_read_b128 v[64:67], v0 offset:3072
	v_add_u32_e32 v0, s10, v214
	ds_read_b128 v[84:87], v0
	ds_read_b128 v[88:91], v0 offset:1024
	ds_read_b128 v[92:95], v0 offset:2048
	ds_read_b128 v[100:103], v0 offset:3072
	v_lshl_add_u64 v[2:3], s[8:9], 0, v[184:185]
	s_add_i32 m0, s13, 0xc000
	ds_read_b128 v[124:127], v215
	ds_read_b128 v[128:131], v215 offset:1024
	ds_read_b128 v[140:143], v215 offset:2048
	ds_read_b128 v[188:191], v215 offset:3072
	ds_read_b128 v[192:195], v215 offset:4096
	ds_read_b128 v[196:199], v215 offset:5120
	ds_read_b128 v[216:219], v215 offset:6144
	ds_read_b128 v[220:223], v215 offset:7168
	global_load_lds_dwordx4 v[2:3], off
	v_lshl_add_u64 v[2:3], s[8:9], 0, v[186:187]
	s_add_i32 m0, s13, 0xe000
	s_nop 0
	global_load_lds_dwordx4 v[2:3], off
	s_waitcnt vmcnt(8) lgkmcnt(0)
	s_barrier
	v_mfma_i32_16x16x64_i8 v[172:175], v[44:47], v[124:127], 0
	v_mfma_i32_16x16x64_i8 v[164:167], v[60:63], v[124:127], 0
	v_mfma_i32_16x16x64_i8 v[160:163], v[60:63], v[140:143], 0
	v_mfma_i32_16x16x64_i8 v[168:171], v[44:47], v[140:143], 0
	v_mfma_i32_16x16x64_i8 v[156:159], v[44:47], v[192:195], 0
	v_mfma_i32_16x16x64_i8 v[152:155], v[60:63], v[192:195], 0
	v_mfma_i32_16x16x64_i8 v[144:147], v[60:63], v[216:219], 0
	v_mfma_i32_16x16x64_i8 v[148:151], v[44:47], v[216:219], 0
	v_mfma_i32_16x16x64_i8 v[172:175], v[52:55], v[128:131], v[172:175]
	v_mfma_i32_16x16x64_i8 v[164:167], v[64:67], v[128:131], v[164:167]
	v_mfma_i32_16x16x64_i8 v[160:163], v[64:67], v[188:191], v[160:163]
	v_mfma_i32_16x16x64_i8 v[168:171], v[52:55], v[188:191], v[168:171]
	v_mfma_i32_16x16x64_i8 v[156:159], v[52:55], v[196:199], v[156:159]
	v_mfma_i32_16x16x64_i8 v[152:155], v[64:67], v[196:199], v[152:155]
	v_mfma_i32_16x16x64_i8 v[144:147], v[64:67], v[220:223], v[144:147]
	v_mfma_i32_16x16x64_i8 v[148:151], v[52:55], v[220:223], v[148:151]
	v_mfma_i32_16x16x64_i8 v[136:139], v[84:87], v[124:127], 0
	v_mfma_i32_16x16x64_i8 v[120:123], v[92:95], v[124:127], 0
	v_mfma_i32_16x16x64_i8 v[116:119], v[92:95], v[140:143], 0
	v_mfma_i32_16x16x64_i8 v[108:111], v[92:95], v[192:195], 0
	v_mfma_i32_16x16x64_i8 v[112:115], v[84:87], v[192:195], 0
	v_mfma_i32_16x16x64_i8 v[104:107], v[84:87], v[216:219], 0
	v_mfma_i32_16x16x64_i8 v[96:99], v[92:95], v[216:219], 0
	v_mfma_i32_16x16x64_i8 v[136:139], v[88:91], v[128:131], v[136:139]
	v_mfma_i32_16x16x64_i8 v[120:123], v[100:103], v[128:131], v[120:123]
	v_mfma_i32_16x16x64_i8 v[116:119], v[100:103], v[188:191], v[116:119]
	v_mfma_i32_16x16x64_i8 v[108:111], v[100:103], v[196:199], v[108:111]
	v_mfma_i32_16x16x64_i8 v[112:115], v[88:91], v[196:199], v[112:115]
	v_mfma_i32_16x16x64_i8 v[104:107], v[88:91], v[220:223], v[104:107]
	v_mfma_i32_16x16x64_i8 v[96:99], v[100:103], v[220:223], v[96:99]
	v_mfma_i32_16x16x64_i8 v[124:127], v[84:87], v[140:143], 0
	v_mfma_i32_16x16x64_i8 v[124:127], v[88:91], v[188:191], v[124:127]
	s_barrier
	s_add_i32 s8, s84, s12
	v_lshl_add_u64 v[200:201], s[82:83], 0, v[178:179]
	s_mov_b32 m0, s8
	ds_read_b128 v[128:131], v215 offset:16384
	ds_read_b128 v[132:135], v215 offset:17408
	ds_read_b128 v[140:143], v215 offset:18432
	ds_read_b128 v[188:191], v215 offset:19456
	ds_read_b128 v[192:195], v215 offset:20480
	ds_read_b128 v[196:199], v215 offset:21504
	ds_read_b128 v[216:219], v215 offset:22528
	ds_read_b128 v[220:223], v215 offset:23552
	global_load_lds_dwordx4 v[200:201], off
	s_add_i32 m0, s8, 0x2000
	s_add_u32 s8, s82, 0x40000
	v_lshl_add_u64 v[206:207], s[82:83], 0, v[182:183]
	s_addc_u32 s9, s83, 0
	s_add_i32 s10, s10, s12
	global_load_lds_dwordx4 v[206:207], off
	v_lshl_add_u64 v[2:3], s[8:9], 0, v[178:179]
	s_mov_b32 m0, s10
	v_lshl_add_u64 v[210:211], vcc, 0, v[176:177]
	global_load_lds_dwordx4 v[2:3], off
	v_lshl_add_u64 v[2:3], s[8:9], 0, v[182:183]
	s_add_i32 m0, s10, 0x2000
	v_lshl_add_u64 v[224:225], vcc, 0, v[180:181]
	global_load_lds_dwordx4 v[2:3], off
	s_mov_b32 m0, s13
	s_nop 0
	global_load_lds_dwordx4 v[210:211], off
	s_mov_b32 m0, s66
	s_nop 0
	global_load_lds_dwordx4 v[224:225], off
	s_waitcnt vmcnt(8) lgkmcnt(0)
	s_barrier
	v_mfma_i32_16x16x64_i8 v[80:83], v[44:47], v[128:131], 0
	v_mfma_i32_16x16x64_i8 v[72:75], v[60:63], v[128:131], 0
	v_mfma_i32_16x16x64_i8 v[68:71], v[60:63], v[140:143], 0
	v_mfma_i32_16x16x64_i8 v[76:79], v[44:47], v[140:143], 0
	v_mfma_i32_16x16x64_i8 v[56:59], v[44:47], v[192:195], 0
	v_mfma_i32_16x16x64_i8 v[48:51], v[60:63], v[192:195], 0
	v_mfma_i32_16x16x64_i8 v[36:39], v[60:63], v[216:219], 0
	v_mfma_i32_16x16x64_i8 v[40:43], v[44:47], v[216:219], 0
	v_mfma_i32_16x16x64_i8 v[80:83], v[52:55], v[132:135], v[80:83]
	v_mfma_i32_16x16x64_i8 v[72:75], v[64:67], v[132:135], v[72:75]
	v_mfma_i32_16x16x64_i8 v[68:71], v[64:67], v[188:191], v[68:71]
	v_mfma_i32_16x16x64_i8 v[76:79], v[52:55], v[188:191], v[76:79]
	v_mfma_i32_16x16x64_i8 v[56:59], v[52:55], v[196:199], v[56:59]
	v_mfma_i32_16x16x64_i8 v[48:51], v[64:67], v[196:199], v[48:51]
	v_mfma_i32_16x16x64_i8 v[36:39], v[64:67], v[220:223], v[36:39]
	v_mfma_i32_16x16x64_i8 v[40:43], v[52:55], v[220:223], v[40:43]
	v_mfma_i32_16x16x64_i8 v[32:35], v[84:87], v[128:131], 0
	v_mfma_i32_16x16x64_i8 v[24:27], v[92:95], v[128:131], 0
	v_mfma_i32_16x16x64_i8 v[20:23], v[92:95], v[140:143], 0
	v_mfma_i32_16x16x64_i8 v[28:31], v[84:87], v[140:143], 0
	v_mfma_i32_16x16x64_i8 v[16:19], v[84:87], v[192:195], 0
	v_mfma_i32_16x16x64_i8 v[12:15], v[92:95], v[192:195], 0
	v_mfma_i32_16x16x64_i8 v[2:5], v[92:95], v[216:219], 0
	v_mfma_i32_16x16x64_i8 v[8:11], v[84:87], v[216:219], 0
	v_mfma_i32_16x16x64_i8 v[32:35], v[88:91], v[132:135], v[32:35]
	v_mfma_i32_16x16x64_i8 v[24:27], v[100:103], v[132:135], v[24:27]
	v_mfma_i32_16x16x64_i8 v[20:23], v[100:103], v[188:191], v[20:23]
	v_mfma_i32_16x16x64_i8 v[28:31], v[88:91], v[188:191], v[28:31]
	v_mfma_i32_16x16x64_i8 v[16:19], v[88:91], v[196:199], v[16:19]
	v_mfma_i32_16x16x64_i8 v[12:15], v[100:103], v[196:199], v[12:15]
	v_mfma_i32_16x16x64_i8 v[2:5], v[100:103], v[220:223], v[2:5]
	v_mfma_i32_16x16x64_i8 v[8:11], v[88:91], v[220:223], v[8:11]
	s_barrier
; #define PG8_STAGE(bufoff, gbase, voff) do { _Pragma("unroll") for (int _i = 0; _i < 2; ++_i) \
;         __builtin_amdgcn_global_load_lds((const unsigned*)((const char*)(gbase) + (voff)[_i]), (PG8_LAS unsigned*)(lds + (bufoff) + ldsw + _i * 8192), 16, 0, 0); } while (0)
; #define PG8_LDA(dst, b, h) do { _Pragma("unroll") for (int m = 0; m < 4; ++m) _Pragma("unroll") for (int k = 0; k < 2; ++k) dst[m][k] = *(const PG8_LAS bf16x8*)(lds + PG8_SA(b, h) + aoff + m * 2048 + k * 1024); } while (0)
; #define PG8_LDB(dst, b, h) do { _Pragma("unroll") for (int n = 0; n < 2; ++n) _Pragma("unroll") for (int k = 0; k < 2; ++k) dst[n][k] = *(const PG8_LAS bf16x8*)(lds + PG8_SB(b, h) + boff + n * 2048 + k * 1024); } while (0)
; #define PG8_MMA(ai, bj, At, Bt) do { __builtin_amdgcn_s_setprio(1); _Pragma("unroll") for (int m = 0; m < 4; ++m) _Pragma("unroll") for (int n = 0; n < 2; ++n) _Pragma("unroll") for (int k = 0; k < 2; ++k) \
;         acc[ai][bj][m][n] = mma16<Epi::I8>(Bt[n][k], At[m][k], acc[ai][bj][m][n]); __builtin_amdgcn_s_setprio(0); } while (0)
; #define PG8_WAIT_V(n) asm volatile("s_waitcnt vmcnt(" #n ")" ::: "memory")
; #define PG8_WAIT_L(n) asm volatile("s_waitcnt lgkmcnt(" #n ")" ::: "memory")
; #define PG8_BAR __builtin_amdgcn_s_barrier()
; #define PG8_SCHED __builtin_amdgcn_sched_barrier(0)
; template <class Epi, class Sched, bool ALIGN_EPI = false, bool SP2 = false>
; __device__ __forceinline__ void gemm_phase(PG8_LAS unsigned char* lds, const Gemm g, const Sched& S, const Epi& E) {
;     ...
;             PG8_LDB(B0, 1, 0); PG8_LDB(B1, 1, 1); PG8_SCHED; PG8_LDA(At, 1, 0); PG8_STAGE(PG8_SA(0, 1), a2 + hstep, voffA);
;             PG8_WAIT_V(8); PG8_WAIT_L(0); PG8_BAR; PG8_MMA(0, 0, At, B0); PG8_MMA(0, 1, At, B1); PG8_BAR; PG8_SCHED;
;             PG8_LDA(At, 1, 1); PG8_STAGE(PG8_SB(1, 0), b3, voffB); PG8_STAGE(PG8_SB(1, 1), b3 + hstep, voffB); PG8_STAGE(PG8_SA(1, 0), a3, voffA);
;             PG8_WAIT_V(8); PG8_WAIT_L(0); PG8_BAR; PG8_MMA(1, 0, At, B0); PG8_MMA(1, 1, At, B1); PG8_BAR; PG8_SCHED;
	s_add_i32 s10, 0, 0x18000
	v_add_u32_e32 v0, s10, v214
	s_add_i32 s11, 0, 0x1c000
	ds_read_b128 v[44:47], v0
	ds_read_b128 v[52:55], v0 offset:1024
	ds_read_b128 v[60:63], v0 offset:2048
	ds_read_b128 v[64:67], v0 offset:3072
	v_add_u32_e32 v0, s11, v214
	ds_read_b128 v[84:87], v0
	ds_read_b128 v[88:91], v0 offset:1024
	ds_read_b128 v[92:95], v0 offset:2048
	ds_read_b128 v[100:103], v0 offset:3072
	s_add_u32 s8, vcc_lo, 0x40000
	s_addc_u32 s9, vcc_hi, 0
	s_mov_b32 m0, s67
	v_lshl_add_u64 v[6:7], s[8:9], 0, v[176:177]
	ds_read_b128 v[128:131], v215 offset:32768
	ds_read_b128 v[132:135], v215 offset:33792
	ds_read_b128 v[140:143], v215 offset:34816
	ds_read_b128 v[188:191], v215 offset:35840
	ds_read_b128 v[192:195], v215 offset:36864
	ds_read_b128 v[196:199], v215 offset:37888
	ds_read_b128 v[216:219], v215 offset:38912
	ds_read_b128 v[220:223], v215 offset:39936
	global_load_lds_dwordx4 v[6:7], off
	v_lshl_add_u64 v[6:7], s[8:9], 0, v[180:181]
	s_mov_b32 m0, s80
	s_nop 0
	global_load_lds_dwordx4 v[6:7], off
	s_waitcnt vmcnt(8) lgkmcnt(0)
	s_barrier
	v_mfma_i32_16x16x64_i8 v[172:175], v[44:47], v[128:131], v[172:175]
	v_mfma_i32_16x16x64_i8 v[164:167], v[60:63], v[128:131], v[164:167]
	v_mfma_i32_16x16x64_i8 v[160:163], v[60:63], v[140:143], v[160:163]
	v_mfma_i32_16x16x64_i8 v[168:171], v[44:47], v[140:143], v[168:171]
	v_mfma_i32_16x16x64_i8 v[156:159], v[44:47], v[192:195], v[156:159]
	v_mfma_i32_16x16x64_i8 v[152:155], v[60:63], v[192:195], v[152:155]
	v_mfma_i32_16x16x64_i8 v[144:147], v[60:63], v[216:219], v[144:147]
	v_mfma_i32_16x16x64_i8 v[148:151], v[44:47], v[216:219], v[148:151]
	v_mfma_i32_16x16x64_i8 v[172:175], v[52:55], v[132:135], v[172:175]
	v_mfma_i32_16x16x64_i8 v[164:167], v[64:67], v[132:135], v[164:167]
	v_mfma_i32_16x16x64_i8 v[160:163], v[64:67], v[188:191], v[160:163]
	v_mfma_i32_16x16x64_i8 v[168:171], v[52:55], v[188:191], v[168:171]
	v_mfma_i32_16x16x64_i8 v[156:159], v[52:55], v[196:199], v[156:159]
	v_mfma_i32_16x16x64_i8 v[152:155], v[64:67], v[196:199], v[152:155]
	v_mfma_i32_16x16x64_i8 v[144:147], v[64:67], v[220:223], v[144:147]
	v_mfma_i32_16x16x64_i8 v[148:151], v[52:55], v[220:223], v[148:151]
	v_mfma_i32_16x16x64_i8 v[136:139], v[84:87], v[128:131], v[136:139]
	v_mfma_i32_16x16x64_i8 v[120:123], v[92:95], v[128:131], v[120:123]
	v_mfma_i32_16x16x64_i8 v[116:119], v[92:95], v[140:143], v[116:119]
	v_mfma_i32_16x16x64_i8 v[124:127], v[84:87], v[140:143], v[124:127]
	v_mfma_i32_16x16x64_i8 v[112:115], v[84:87], v[192:195], v[112:115]
	v_mfma_i32_16x16x64_i8 v[108:111], v[92:95], v[192:195], v[108:111]
	v_mfma_i32_16x16x64_i8 v[96:99], v[92:95], v[216:219], v[96:99]
	v_mfma_i32_16x16x64_i8 v[104:107], v[84:87], v[216:219], v[104:107]
	v_mfma_i32_16x16x64_i8 v[136:139], v[88:91], v[132:135], v[136:139]
	v_mfma_i32_16x16x64_i8 v[120:123], v[100:103], v[132:135], v[120:123]
	v_mfma_i32_16x16x64_i8 v[116:119], v[100:103], v[188:191], v[116:119]
	v_mfma_i32_16x16x64_i8 v[132:135], v[88:91], v[188:191], v[124:127]
	v_mfma_i32_16x16x64_i8 v[112:115], v[88:91], v[196:199], v[112:115]
	v_mfma_i32_16x16x64_i8 v[108:111], v[100:103], v[196:199], v[108:111]
	v_mfma_i32_16x16x64_i8 v[96:99], v[100:103], v[220:223], v[96:99]
	v_mfma_i32_16x16x64_i8 v[104:107], v[88:91], v[220:223], v[104:107]
	s_barrier
	s_add_i32 s8, s10, s12
	v_lshl_add_u64 v[6:7], v[200:201], 0, s[92:93]
	s_mov_b32 m0, s8
	ds_read_b128 v[124:127], v215 offset:49152
	ds_read_b128 v[128:131], v215 offset:50176
	ds_read_b128 v[140:143], v215 offset:51200
	ds_read_b128 v[188:191], v215 offset:52224
	ds_read_b128 v[192:195], v215 offset:53248
	ds_read_b128 v[196:199], v215 offset:54272
	ds_read_b128 v[216:219], v215 offset:55296
	ds_read_b128 v[220:223], v215 offset:56320
	global_load_lds_dwordx4 v[6:7], off
	s_add_i32 m0, s8, 0x2000
	s_add_u32 s8, s82, 0x40080
	v_lshl_add_u64 v[6:7], v[206:207], 0, s[92:93]
	s_addc_u32 s9, s83, 0
	s_add_i32 s10, s11, s12
	global_load_lds_dwordx4 v[6:7], off
	v_lshl_add_u64 v[6:7], s[8:9], 0, v[178:179]
	s_mov_b32 m0, s10
	s_nop 0
	global_load_lds_dwordx4 v[6:7], off
	v_lshl_add_u64 v[6:7], s[8:9], 0, v[182:183]
	s_add_i32 m0, s10, 0x2000
	s_nop 0
	global_load_lds_dwordx4 v[6:7], off
	v_lshl_add_u64 v[6:7], v[210:211], 0, s[92:93]
	s_mov_b32 m0, s58
	s_nop 0
	global_load_lds_dwordx4 v[6:7], off
	v_lshl_add_u64 v[6:7], v[224:225], 0, s[92:93]
	s_mov_b32 m0, s4
	s_nop 0
	global_load_lds_dwordx4 v[6:7], off
	s_waitcnt vmcnt(8) lgkmcnt(0)
	s_barrier
	v_mfma_i32_16x16x64_i8 v[80:83], v[44:47], v[124:127], v[80:83]
	v_mfma_i32_16x16x64_i8 v[72:75], v[60:63], v[124:127], v[72:75]
	v_mfma_i32_16x16x64_i8 v[68:71], v[60:63], v[140:143], v[68:71]
	v_mfma_i32_16x16x64_i8 v[76:79], v[44:47], v[140:143], v[76:79]
	v_mfma_i32_16x16x64_i8 v[56:59], v[44:47], v[192:195], v[56:59]
	v_mfma_i32_16x16x64_i8 v[48:51], v[60:63], v[192:195], v[48:51]
	v_mfma_i32_16x16x64_i8 v[36:39], v[60:63], v[216:219], v[36:39]
	v_mfma_i32_16x16x64_i8 v[40:43], v[44:47], v[216:219], v[40:43]
	v_mfma_i32_16x16x64_i8 v[80:83], v[52:55], v[128:131], v[80:83]
	v_mfma_i32_16x16x64_i8 v[72:75], v[64:67], v[128:131], v[72:75]
	v_mfma_i32_16x16x64_i8 v[68:71], v[64:67], v[188:191], v[68:71]
	v_mfma_i32_16x16x64_i8 v[76:79], v[52:55], v[188:191], v[76:79]
	v_mfma_i32_16x16x64_i8 v[56:59], v[52:55], v[196:199], v[56:59]
	v_mfma_i32_16x16x64_i8 v[48:51], v[64:67], v[196:199], v[48:51]
	v_mfma_i32_16x16x64_i8 v[36:39], v[64:67], v[220:223], v[36:39]
	v_mfma_i32_16x16x64_i8 v[40:43], v[52:55], v[220:223], v[40:43]
	v_mfma_i32_16x16x64_i8 v[32:35], v[84:87], v[124:127], v[32:35]
	v_mfma_i32_16x16x64_i8 v[24:27], v[92:95], v[124:127], v[24:27]
	v_mfma_i32_16x16x64_i8 v[20:23], v[92:95], v[140:143], v[20:23]
	v_mfma_i32_16x16x64_i8 v[28:31], v[84:87], v[140:143], v[28:31]
	v_mfma_i32_16x16x64_i8 v[16:19], v[84:87], v[192:195], v[16:19]
	v_mfma_i32_16x16x64_i8 v[12:15], v[92:95], v[192:195], v[12:15]
	v_mfma_i32_16x16x64_i8 v[2:5], v[92:95], v[216:219], v[2:5]
	v_mfma_i32_16x16x64_i8 v[6:9], v[84:87], v[216:219], v[8:11]
	v_mfma_i32_16x16x64_i8 v[32:35], v[88:91], v[128:131], v[32:35]
	v_mfma_i32_16x16x64_i8 v[24:27], v[100:103], v[128:131], v[24:27]
	v_mfma_i32_16x16x64_i8 v[20:23], v[100:103], v[188:191], v[20:23]
	v_mfma_i32_16x16x64_i8 v[28:31], v[88:91], v[188:191], v[28:31]
	v_mfma_i32_16x16x64_i8 v[16:19], v[88:91], v[196:199], v[16:19]
	v_mfma_i32_16x16x64_i8 v[12:15], v[100:103], v[196:199], v[12:15]
	v_mfma_i32_16x16x64_i8 v[8:11], v[88:91], v[220:223], v[6:9]
	v_mfma_i32_16x16x64_i8 v[4:7], v[100:103], v[220:223], v[2:5]
	s_barrier
	s_add_i32 s5, s5, 2
	s_add_u32 s85, s85, 0x100
	s_addc_u32 s68, s68, 0
	s_cmp_gt_u32 s5, 13
	s_mov_b64 s[8:9], s[70:71]
	s_cbranch_scc0 .LBB0_385
	s_branch .Lpeelx385
; #define PG8_STAGE(bufoff, gbase, voff) do { _Pragma("unroll") for (int _i = 0; _i < 2; ++_i) \
;         __builtin_amdgcn_global_load_lds((const unsigned*)((const char*)(gbase) + (voff)[_i]), (PG8_LAS unsigned*)(lds + (bufoff) + ldsw + _i * 8192), 16, 0, 0); } while (0)
; #define PG8_LDA(dst, b, h) do { _Pragma("unroll") for (int m = 0; m < 4; ++m) _Pragma("unroll") for (int k = 0; k < 2; ++k) dst[m][k] = *(const PG8_LAS bf16x8*)(lds + PG8_SA(b, h) + aoff + m * 2048 + k * 1024); } while (0)
; #define PG8_LDB(dst, b, h) do { _Pragma("unroll") for (int n = 0; n < 2; ++n) _Pragma("unroll") for (int k = 0; k < 2; ++k) dst[n][k] = *(const PG8_LAS bf16x8*)(lds + PG8_SB(b, h) + boff + n * 2048 + k * 1024); } while (0)
; #define PG8_MMA(ai, bj, At, Bt) do { __builtin_amdgcn_s_setprio(1); _Pragma("unroll") for (int m = 0; m < 4; ++m) _Pragma("unroll") for (int n = 0; n < 2; ++n) _Pragma("unroll") for (int k = 0; k < 2; ++k) \
;         acc[ai][bj][m][n] = mma16<Epi::I8>(Bt[n][k], At[m][k], acc[ai][bj][m][n]); __builtin_amdgcn_s_setprio(0); } while (0)
; #define PG8_WAIT_V(n) asm volatile("s_waitcnt vmcnt(" #n ")" ::: "memory")
; #define PG8_WAIT_L(n) asm volatile("s_waitcnt lgkmcnt(" #n ")" ::: "memory")
; #define PG8_BAR __builtin_amdgcn_s_barrier()
; template <class Epi, class Sched, bool ALIGN_EPI = false, bool SP2 = false>
; __device__ __forceinline__ void gemm_phase(PG8_LAS unsigned char* lds, const Gemm g, const Sched& S, const Epi& E) {
;     ...
;             const bool last = (t == nt - 2);
;             const char* a1 = cA + (size_t)(t + 1) * kstep;
;             const char* a2 = last ? nA : cA + (size_t)(t + 2) * kstep; const char* b2 = last ? nB : cB + (size_t)(t + 2) * kstep;
;             const char* a3 = a2 + kstep; const char* b3 = b2 + kstep;
;             if (last && has_next) S.a_ready(nxt);
;             if constexpr (SP2) {
;             PG8_LDB(B0, 0, 0); PG8_LDB(B1, 0, 1); PG8_SCHED; PG8_LDA(At, 0, 0); PG8_STAGE(PG8_SA(1, 1), a1 + hstep, voffA);
;             PG8_WAIT_V(8); PG8_WAIT_L(0); PG8_BAR; PG8_MMA(0, 0, At, B0); PG8_MMA(0, 1, At, B1); PG8_BAR; PG8_SCHED;
;             PG8_LDA(At, 0, 1); PG8_STAGE(PG8_SB(0, 0), b2, voffB); PG8_STAGE(PG8_SB(0, 1), b2 + hstep, voffB); PG8_STAGE(PG8_SA(0, 0), a2, voffA);
;             PG8_WAIT_V(8); PG8_WAIT_L(0); PG8_BAR; PG8_MMA(1, 0, At, B0); PG8_MMA(1, 1, At, B1); PG8_BAR; PG8_SCHED;
.LBB0_385:
	s_add_u32 s70, s8, 0x100
	s_addc_u32 s71, s9, 0
	s_add_i32 s84, 0, 0x10000
	s_cmp_eq_u32 s5, 12
	s_cselect_b32 vcc_hi, s1, s71
	s_cselect_b32 vcc_lo, s7, s70
	v_add_u32_e32 v0, s84, v214
	s_cselect_b32 s83, s69, s68
	s_cselect_b32 s82, s81, s85
	s_add_i32 s10, 0, 0x14000
	ds_read_b128 v[44:47], v0
	ds_read_b128 v[52:55], v0 offset:1024
	ds_read_b128 v[60:63], v0 offset:2048
	ds_read_b128 v[64:67], v0 offset:3072
	v_add_u32_e32 v0, s10, v214
	ds_read_b128 v[84:87], v0
	ds_read_b128 v[88:91], v0 offset:1024
	ds_read_b128 v[92:95], v0 offset:2048
	ds_read_b128 v[100:103], v0 offset:3072
	v_lshl_add_u64 v[2:3], s[8:9], 0, v[184:185]
	s_add_i32 m0, s13, 0xc000
	ds_read_b128 v[124:127], v215
	ds_read_b128 v[128:131], v215 offset:1024
	ds_read_b128 v[140:143], v215 offset:2048
	ds_read_b128 v[188:191], v215 offset:3072
	ds_read_b128 v[192:195], v215 offset:4096
	ds_read_b128 v[196:199], v215 offset:5120
	ds_read_b128 v[216:219], v215 offset:6144
	ds_read_b128 v[220:223], v215 offset:7168
	global_load_lds_dwordx4 v[2:3], off
	v_lshl_add_u64 v[2:3], s[8:9], 0, v[186:187]
	s_add_i32 m0, s13, 0xe000
	s_nop 0
	global_load_lds_dwordx4 v[2:3], off
	s_waitcnt vmcnt(8) lgkmcnt(0)
	s_barrier
	v_mfma_i32_16x16x64_i8 v[172:175], v[44:47], v[124:127], v[172:175]
	v_mfma_i32_16x16x64_i8 v[164:167], v[60:63], v[124:127], v[164:167]
	v_mfma_i32_16x16x64_i8 v[160:163], v[60:63], v[140:143], v[160:163]
	v_mfma_i32_16x16x64_i8 v[168:171], v[44:47], v[140:143], v[168:171]
	v_mfma_i32_16x16x64_i8 v[156:159], v[44:47], v[192:195], v[156:159]
	v_mfma_i32_16x16x64_i8 v[152:155], v[60:63], v[192:195], v[152:155]
	v_mfma_i32_16x16x64_i8 v[144:147], v[60:63], v[216:219], v[144:147]
	v_mfma_i32_16x16x64_i8 v[148:151], v[44:47], v[216:219], v[148:151]
	v_mfma_i32_16x16x64_i8 v[172:175], v[52:55], v[128:131], v[172:175]
	v_mfma_i32_16x16x64_i8 v[164:167], v[64:67], v[128:131], v[164:167]
	v_mfma_i32_16x16x64_i8 v[160:163], v[64:67], v[188:191], v[160:163]
	v_mfma_i32_16x16x64_i8 v[168:171], v[52:55], v[188:191], v[168:171]
	v_mfma_i32_16x16x64_i8 v[156:159], v[52:55], v[196:199], v[156:159]
	v_mfma_i32_16x16x64_i8 v[152:155], v[64:67], v[196:199], v[152:155]
	v_mfma_i32_16x16x64_i8 v[144:147], v[64:67], v[220:223], v[144:147]
	v_mfma_i32_16x16x64_i8 v[148:151], v[52:55], v[220:223], v[148:151]
	v_mfma_i32_16x16x64_i8 v[136:139], v[84:87], v[124:127], v[136:139]
	v_mfma_i32_16x16x64_i8 v[120:123], v[92:95], v[124:127], v[120:123]
	v_mfma_i32_16x16x64_i8 v[116:119], v[92:95], v[140:143], v[116:119]
	v_mfma_i32_16x16x64_i8 v[108:111], v[92:95], v[192:195], v[108:111]
	v_mfma_i32_16x16x64_i8 v[112:115], v[84:87], v[192:195], v[112:115]
	v_mfma_i32_16x16x64_i8 v[104:107], v[84:87], v[216:219], v[104:107]
	v_mfma_i32_16x16x64_i8 v[96:99], v[92:95], v[216:219], v[96:99]
	v_mfma_i32_16x16x64_i8 v[136:139], v[88:91], v[128:131], v[136:139]
	v_mfma_i32_16x16x64_i8 v[120:123], v[100:103], v[128:131], v[120:123]
	v_mfma_i32_16x16x64_i8 v[116:119], v[100:103], v[188:191], v[116:119]
	v_mfma_i32_16x16x64_i8 v[108:111], v[100:103], v[196:199], v[108:111]
	v_mfma_i32_16x16x64_i8 v[112:115], v[88:91], v[196:199], v[112:115]
	v_mfma_i32_16x16x64_i8 v[104:107], v[88:91], v[220:223], v[104:107]
	v_mfma_i32_16x16x64_i8 v[96:99], v[100:103], v[220:223], v[96:99]
	v_mfma_i32_16x16x64_i8 v[124:127], v[84:87], v[140:143], v[132:135]
	v_mfma_i32_16x16x64_i8 v[124:127], v[88:91], v[188:191], v[124:127]
	s_barrier
	s_add_i32 s8, s84, s12
	v_lshl_add_u64 v[200:201], s[82:83], 0, v[178:179]
	s_mov_b32 m0, s8
	ds_read_b128 v[128:131], v215 offset:16384
	ds_read_b128 v[132:135], v215 offset:17408
	ds_read_b128 v[140:143], v215 offset:18432
	ds_read_b128 v[188:191], v215 offset:19456
	ds_read_b128 v[192:195], v215 offset:20480
	ds_read_b128 v[196:199], v215 offset:21504
	ds_read_b128 v[216:219], v215 offset:22528
	ds_read_b128 v[220:223], v215 offset:23552
	global_load_lds_dwordx4 v[200:201], off
	s_add_i32 m0, s8, 0x2000
	s_add_u32 s8, s82, 0x40000
	v_lshl_add_u64 v[206:207], s[82:83], 0, v[182:183]
	s_addc_u32 s9, s83, 0
	s_add_i32 s10, s10, s12
	global_load_lds_dwordx4 v[206:207], off
	v_lshl_add_u64 v[2:3], s[8:9], 0, v[178:179]
	s_mov_b32 m0, s10
	v_lshl_add_u64 v[210:211], vcc, 0, v[176:177]
	global_load_lds_dwordx4 v[2:3], off
	v_lshl_add_u64 v[2:3], s[8:9], 0, v[182:183]
	s_add_i32 m0, s10, 0x2000
	v_lshl_add_u64 v[224:225], vcc, 0, v[180:181]
	global_load_lds_dwordx4 v[2:3], off
	s_mov_b32 m0, s13
	s_nop 0
	global_load_lds_dwordx4 v[210:211], off
	s_mov_b32 m0, s66
	s_nop 0
	global_load_lds_dwordx4 v[224:225], off
	s_waitcnt vmcnt(8) lgkmcnt(0)
	s_barrier
	v_mfma_i32_16x16x64_i8 v[80:83], v[44:47], v[128:131], v[80:83]
	v_mfma_i32_16x16x64_i8 v[72:75], v[60:63], v[128:131], v[72:75]
	v_mfma_i32_16x16x64_i8 v[68:71], v[60:63], v[140:143], v[68:71]
	v_mfma_i32_16x16x64_i8 v[76:79], v[44:47], v[140:143], v[76:79]
	v_mfma_i32_16x16x64_i8 v[56:59], v[44:47], v[192:195], v[56:59]
	v_mfma_i32_16x16x64_i8 v[48:51], v[60:63], v[192:195], v[48:51]
	v_mfma_i32_16x16x64_i8 v[36:39], v[60:63], v[216:219], v[36:39]
	v_mfma_i32_16x16x64_i8 v[40:43], v[44:47], v[216:219], v[40:43]
	v_mfma_i32_16x16x64_i8 v[80:83], v[52:55], v[132:135], v[80:83]
	v_mfma_i32_16x16x64_i8 v[72:75], v[64:67], v[132:135], v[72:75]
	v_mfma_i32_16x16x64_i8 v[68:71], v[64:67], v[188:191], v[68:71]
	v_mfma_i32_16x16x64_i8 v[76:79], v[52:55], v[188:191], v[76:79]
	v_mfma_i32_16x16x64_i8 v[56:59], v[52:55], v[196:199], v[56:59]
	v_mfma_i32_16x16x64_i8 v[48:51], v[64:67], v[196:199], v[48:51]
	v_mfma_i32_16x16x64_i8 v[36:39], v[64:67], v[220:223], v[36:39]
	v_mfma_i32_16x16x64_i8 v[40:43], v[52:55], v[220:223], v[40:43]
	v_mfma_i32_16x16x64_i8 v[32:35], v[84:87], v[128:131], v[32:35]
	v_mfma_i32_16x16x64_i8 v[24:27], v[92:95], v[128:131], v[24:27]
	v_mfma_i32_16x16x64_i8 v[20:23], v[92:95], v[140:143], v[20:23]
	v_mfma_i32_16x16x64_i8 v[28:31], v[84:87], v[140:143], v[28:31]
	v_mfma_i32_16x16x64_i8 v[16:19], v[84:87], v[192:195], v[16:19]
	v_mfma_i32_16x16x64_i8 v[12:15], v[92:95], v[192:195], v[12:15]
	v_mfma_i32_16x16x64_i8 v[2:5], v[92:95], v[216:219], v[4:7]
	v_mfma_i32_16x16x64_i8 v[8:11], v[84:87], v[216:219], v[8:11]
	v_mfma_i32_16x16x64_i8 v[32:35], v[88:91], v[132:135], v[32:35]
	v_mfma_i32_16x16x64_i8 v[24:27], v[100:103], v[132:135], v[24:27]
	v_mfma_i32_16x16x64_i8 v[20:23], v[100:103], v[188:191], v[20:23]
	v_mfma_i32_16x16x64_i8 v[28:31], v[88:91], v[188:191], v[28:31]
	v_mfma_i32_16x16x64_i8 v[16:19], v[88:91], v[196:199], v[16:19]
	v_mfma_i32_16x16x64_i8 v[12:15], v[100:103], v[196:199], v[12:15]
	v_mfma_i32_16x16x64_i8 v[2:5], v[100:103], v[220:223], v[2:5]
	v_mfma_i32_16x16x64_i8 v[8:11], v[88:91], v[220:223], v[8:11]
	s_barrier
; #define PG8_STAGE(bufoff, gbase, voff) do { _Pragma("unroll") for (int _i = 0; _i < 2; ++_i) \
;         __builtin_amdgcn_global_load_lds((const unsigned*)((const char*)(gbase) + (voff)[_i]), (PG8_LAS unsigned*)(lds + (bufoff) + ldsw + _i * 8192), 16, 0, 0); } while (0)
; #define PG8_LDA(dst, b, h) do { _Pragma("unroll") for (int m = 0; m < 4; ++m) _Pragma("unroll") for (int k = 0; k < 2; ++k) dst[m][k] = *(const PG8_LAS bf16x8*)(lds + PG8_SA(b, h) + aoff + m * 2048 + k * 1024); } while (0)
; #define PG8_LDB(dst, b, h) do { _Pragma("unroll") for (int n = 0; n < 2; ++n) _Pragma("unroll") for (int k = 0; k < 2; ++k) dst[n][k] = *(const PG8_LAS bf16x8*)(lds + PG8_SB(b, h) + boff + n * 2048 + k * 1024); } while (0)
; #define PG8_MMA(ai, bj, At, Bt) do { __builtin_amdgcn_s_setprio(1); _Pragma("unroll") for (int m = 0; m < 4; ++m) _Pragma("unroll") for (int n = 0; n < 2; ++n) _Pragma("unroll") for (int k = 0; k < 2; ++k) \
;         acc[ai][bj][m][n] = mma16<Epi::I8>(Bt[n][k], At[m][k], acc[ai][bj][m][n]); __builtin_amdgcn_s_setprio(0); } while (0)
; #define PG8_WAIT_V(n) asm volatile("s_waitcnt vmcnt(" #n ")" ::: "memory")
; #define PG8_WAIT_L(n) asm volatile("s_waitcnt lgkmcnt(" #n ")" ::: "memory")
; #define PG8_BAR __builtin_amdgcn_s_barrier()
; #define PG8_SCHED __builtin_amdgcn_sched_barrier(0)
; template <class Epi, class Sched, bool ALIGN_EPI = false, bool SP2 = false>
; __device__ __forceinline__ void gemm_phase(PG8_LAS unsigned char* lds, const Gemm g, const Sched& S, const Epi& E) {
;     ...
;             PG8_LDB(B0, 1, 0); PG8_LDB(B1, 1, 1); PG8_SCHED; PG8_LDA(At, 1, 0); PG8_STAGE(PG8_SA(0, 1), a2 + hstep, voffA);
;             PG8_WAIT_V(8); PG8_WAIT_L(0); PG8_BAR; PG8_MMA(0, 0, At, B0); PG8_MMA(0, 1, At, B1); PG8_BAR; PG8_SCHED;
;             PG8_LDA(At, 1, 1); PG8_STAGE(PG8_SB(1, 0), b3, voffB); PG8_STAGE(PG8_SB(1, 1), b3 + hstep, voffB); PG8_STAGE(PG8_SA(1, 0), a3, voffA);
;             PG8_WAIT_V(8); PG8_WAIT_L(0); PG8_BAR; PG8_MMA(1, 0, At, B0); PG8_MMA(1, 1, At, B1); PG8_BAR; PG8_SCHED;
	s_add_i32 s10, 0, 0x18000
	v_add_u32_e32 v0, s10, v214
	s_add_i32 s11, 0, 0x1c000
	ds_read_b128 v[44:47], v0
	ds_read_b128 v[52:55], v0 offset:1024
	ds_read_b128 v[60:63], v0 offset:2048
	ds_read_b128 v[64:67], v0 offset:3072
	v_add_u32_e32 v0, s11, v214
	ds_read_b128 v[84:87], v0
	ds_read_b128 v[88:91], v0 offset:1024
	ds_read_b128 v[92:95], v0 offset:2048
	ds_read_b128 v[100:103], v0 offset:3072
	s_add_u32 s8, vcc_lo, 0x40000
	s_addc_u32 s9, vcc_hi, 0
	s_mov_b32 m0, s67
	v_lshl_add_u64 v[6:7], s[8:9], 0, v[176:177]
	ds_read_b128 v[128:131], v215 offset:32768
	ds_read_b128 v[132:135], v215 offset:33792
	ds_read_b128 v[140:143], v215 offset:34816
	ds_read_b128 v[188:191], v215 offset:35840
	ds_read_b128 v[192:195], v215 offset:36864
	ds_read_b128 v[196:199], v215 offset:37888
	ds_read_b128 v[216:219], v215 offset:38912
	ds_read_b128 v[220:223], v215 offset:39936
	global_load_lds_dwordx4 v[6:7], off
	v_lshl_add_u64 v[6:7], s[8:9], 0, v[180:181]
	s_mov_b32 m0, s80
	s_nop 0
	global_load_lds_dwordx4 v[6:7], off
	s_waitcnt vmcnt(8) lgkmcnt(0)
	s_barrier
	v_mfma_i32_16x16x64_i8 v[172:175], v[44:47], v[128:131], v[172:175]
	v_mfma_i32_16x16x64_i8 v[164:167], v[60:63], v[128:131], v[164:167]
	v_mfma_i32_16x16x64_i8 v[160:163], v[60:63], v[140:143], v[160:163]
	v_mfma_i32_16x16x64_i8 v[168:171], v[44:47], v[140:143], v[168:171]
	v_mfma_i32_16x16x64_i8 v[156:159], v[44:47], v[192:195], v[156:159]
	v_mfma_i32_16x16x64_i8 v[152:155], v[60:63], v[192:195], v[152:155]
	v_mfma_i32_16x16x64_i8 v[144:147], v[60:63], v[216:219], v[144:147]
	v_mfma_i32_16x16x64_i8 v[148:151], v[44:47], v[216:219], v[148:151]
	v_mfma_i32_16x16x64_i8 v[172:175], v[52:55], v[132:135], v[172:175]
	v_mfma_i32_16x16x64_i8 v[164:167], v[64:67], v[132:135], v[164:167]
	v_mfma_i32_16x16x64_i8 v[160:163], v[64:67], v[188:191], v[160:163]
	v_mfma_i32_16x16x64_i8 v[168:171], v[52:55], v[188:191], v[168:171]
	v_mfma_i32_16x16x64_i8 v[156:159], v[52:55], v[196:199], v[156:159]
	v_mfma_i32_16x16x64_i8 v[152:155], v[64:67], v[196:199], v[152:155]
	v_mfma_i32_16x16x64_i8 v[144:147], v[64:67], v[220:223], v[144:147]
	v_mfma_i32_16x16x64_i8 v[148:151], v[52:55], v[220:223], v[148:151]
	v_mfma_i32_16x16x64_i8 v[136:139], v[84:87], v[128:131], v[136:139]
	v_mfma_i32_16x16x64_i8 v[120:123], v[92:95], v[128:131], v[120:123]
	v_mfma_i32_16x16x64_i8 v[116:119], v[92:95], v[140:143], v[116:119]
	v_mfma_i32_16x16x64_i8 v[124:127], v[84:87], v[140:143], v[124:127]
	v_mfma_i32_16x16x64_i8 v[112:115], v[84:87], v[192:195], v[112:115]
	v_mfma_i32_16x16x64_i8 v[108:111], v[92:95], v[192:195], v[108:111]
	v_mfma_i32_16x16x64_i8 v[96:99], v[92:95], v[216:219], v[96:99]
	v_mfma_i32_16x16x64_i8 v[104:107], v[84:87], v[216:219], v[104:107]
	v_mfma_i32_16x16x64_i8 v[136:139], v[88:91], v[132:135], v[136:139]
	v_mfma_i32_16x16x64_i8 v[120:123], v[100:103], v[132:135], v[120:123]
	v_mfma_i32_16x16x64_i8 v[116:119], v[100:103], v[188:191], v[116:119]
	v_mfma_i32_16x16x64_i8 v[132:135], v[88:91], v[188:191], v[124:127]
	v_mfma_i32_16x16x64_i8 v[112:115], v[88:91], v[196:199], v[112:115]
	v_mfma_i32_16x16x64_i8 v[108:111], v[100:103], v[196:199], v[108:111]
	v_mfma_i32_16x16x64_i8 v[96:99], v[100:103], v[220:223], v[96:99]
	v_mfma_i32_16x16x64_i8 v[104:107], v[88:91], v[220:223], v[104:107]
	s_barrier
	s_add_i32 s8, s10, s12
	v_lshl_add_u64 v[6:7], v[200:201], 0, s[92:93]
	s_mov_b32 m0, s8
	ds_read_b128 v[124:127], v215 offset:49152
	ds_read_b128 v[128:131], v215 offset:50176
	ds_read_b128 v[140:143], v215 offset:51200
	ds_read_b128 v[188:191], v215 offset:52224
	ds_read_b128 v[192:195], v215 offset:53248
	ds_read_b128 v[196:199], v215 offset:54272
	ds_read_b128 v[216:219], v215 offset:55296
	ds_read_b128 v[220:223], v215 offset:56320
	global_load_lds_dwordx4 v[6:7], off
	s_add_i32 m0, s8, 0x2000
	s_add_u32 s8, s82, 0x40080
	v_lshl_add_u64 v[6:7], v[206:207], 0, s[92:93]
	s_addc_u32 s9, s83, 0
	s_add_i32 s10, s11, s12
	global_load_lds_dwordx4 v[6:7], off
	v_lshl_add_u64 v[6:7], s[8:9], 0, v[178:179]
	s_mov_b32 m0, s10
	s_nop 0
	global_load_lds_dwordx4 v[6:7], off
	v_lshl_add_u64 v[6:7], s[8:9], 0, v[182:183]
	s_add_i32 m0, s10, 0x2000
	s_nop 0
	global_load_lds_dwordx4 v[6:7], off
	v_lshl_add_u64 v[6:7], v[210:211], 0, s[92:93]
	s_mov_b32 m0, s58
	s_nop 0
	global_load_lds_dwordx4 v[6:7], off
	v_lshl_add_u64 v[6:7], v[224:225], 0, s[92:93]
	s_mov_b32 m0, s4
	s_nop 0
	global_load_lds_dwordx4 v[6:7], off
	s_waitcnt vmcnt(8) lgkmcnt(0)
	s_barrier
	v_mfma_i32_16x16x64_i8 v[80:83], v[44:47], v[124:127], v[80:83]
	v_mfma_i32_16x16x64_i8 v[72:75], v[60:63], v[124:127], v[72:75]
	v_mfma_i32_16x16x64_i8 v[68:71], v[60:63], v[140:143], v[68:71]
	v_mfma_i32_16x16x64_i8 v[76:79], v[44:47], v[140:143], v[76:79]
	v_mfma_i32_16x16x64_i8 v[56:59], v[44:47], v[192:195], v[56:59]
	v_mfma_i32_16x16x64_i8 v[48:51], v[60:63], v[192:195], v[48:51]
	v_mfma_i32_16x16x64_i8 v[36:39], v[60:63], v[216:219], v[36:39]
	v_mfma_i32_16x16x64_i8 v[40:43], v[44:47], v[216:219], v[40:43]
	v_mfma_i32_16x16x64_i8 v[80:83], v[52:55], v[128:131], v[80:83]
	v_mfma_i32_16x16x64_i8 v[72:75], v[64:67], v[128:131], v[72:75]
	v_mfma_i32_16x16x64_i8 v[68:71], v[64:67], v[188:191], v[68:71]
	v_mfma_i32_16x16x64_i8 v[76:79], v[52:55], v[188:191], v[76:79]
	v_mfma_i32_16x16x64_i8 v[56:59], v[52:55], v[196:199], v[56:59]
	v_mfma_i32_16x16x64_i8 v[48:51], v[64:67], v[196:199], v[48:51]
	v_mfma_i32_16x16x64_i8 v[36:39], v[64:67], v[220:223], v[36:39]
	v_mfma_i32_16x16x64_i8 v[40:43], v[52:55], v[220:223], v[40:43]
	v_mfma_i32_16x16x64_i8 v[32:35], v[84:87], v[124:127], v[32:35]
	v_mfma_i32_16x16x64_i8 v[24:27], v[92:95], v[124:127], v[24:27]
	v_mfma_i32_16x16x64_i8 v[20:23], v[92:95], v[140:143], v[20:23]
	v_mfma_i32_16x16x64_i8 v[28:31], v[84:87], v[140:143], v[28:31]
	v_mfma_i32_16x16x64_i8 v[16:19], v[84:87], v[192:195], v[16:19]
	v_mfma_i32_16x16x64_i8 v[12:15], v[92:95], v[192:195], v[12:15]
	v_mfma_i32_16x16x64_i8 v[2:5], v[92:95], v[216:219], v[2:5]
	v_mfma_i32_16x16x64_i8 v[6:9], v[84:87], v[216:219], v[8:11]
	v_mfma_i32_16x16x64_i8 v[32:35], v[88:91], v[128:131], v[32:35]
	v_mfma_i32_16x16x64_i8 v[24:27], v[100:103], v[128:131], v[24:27]
	v_mfma_i32_16x16x64_i8 v[20:23], v[100:103], v[188:191], v[20:23]
	v_mfma_i32_16x16x64_i8 v[28:31], v[88:91], v[188:191], v[28:31]
	v_mfma_i32_16x16x64_i8 v[16:19], v[88:91], v[196:199], v[16:19]
	v_mfma_i32_16x16x64_i8 v[12:15], v[100:103], v[196:199], v[12:15]
	v_mfma_i32_16x16x64_i8 v[8:11], v[88:91], v[220:223], v[6:9]
	v_mfma_i32_16x16x64_i8 v[4:7], v[100:103], v[220:223], v[2:5]
	s_barrier
	s_add_i32 s5, s5, 2
	s_add_u32 s85, s85, 0x100
	s_addc_u32 s68, s68, 0
	s_cmp_gt_u32 s5, 13
	s_mov_b64 s[8:9], s[70:71]
	s_cbranch_scc0 .LBB0_385
